# v48 without the mid-MMA priority drop/raise pair between the two 16-MFMA blocks of each K-loop phase
# baseline (speedup 1.0000x reference)
.LBB0_261:
	s_ashr_i32 s35, s34, 31
	s_lshl_b64 vcc, s[34:35], 21
	s_add_u32 s13, s30, vcc_lo
	s_addc_u32 s15, s31, vcc_hi
	s_add_u32 s54, s13, s54
	s_addc_u32 s55, s15, s55
	s_and_b64 s[86:87], s[86:87], exec
	s_cselect_b32 s13, s55, s11
	s_cselect_b32 s15, s54, s10
	s_add_i32 s35, s19, -2
	s_add_u32 s40, s10, 0x100
	s_addc_u32 s49, s11, 0
	s_add_u32 s10, s38, 0x100080
	s_addc_u32 s11, s39, 0
	s_mov_b32 s38, 0
	s_add_i32 vcc_lo, s38, 2
	s_add_u32 s39, s10, 0xfff00080
	s_addc_u32 s66, s11, -1
	s_add_i32 s67, 0, 0x10000
	s_cmp_eq_u32 s35, s38
	s_cselect_b32 s87, s53, s66
	s_cselect_b32 s86, s52, s39
	s_cselect_b32 s39, s13, s49
	s_cselect_b32 s38, s15, s40
	s_add_i32 vcc_hi, 0, 0x14000
	v_add_u32_e32 v142, s67, v1
	v_add_u32_e32 v180, vcc_hi, v1
	ds_read_b128 v[130:133], v142
	ds_read_b128 v[134:137], v142 offset:1024
	ds_read_b128 v[138:141], v142 offset:2048
	ds_read_b128 v[142:145], v142 offset:3072
	ds_read_b128 v[168:171], v180
	ds_read_b128 v[172:175], v180 offset:1024
	ds_read_b128 v[176:179], v180 offset:2048
	ds_read_b128 v[180:183], v180 offset:3072
	s_add_i32 m0, s85, 0xc000
	ds_read_b128 v[198:201], v197
	ds_read_b128 v[202:205], v197 offset:1024
	ds_read_b128 v[206:209], v197 offset:2048
	ds_read_b128 v[210:213], v197 offset:3072
	ds_read_b128 v[214:217], v197 offset:4096
	ds_read_b128 v[218:221], v197 offset:5120
	ds_read_b128 v[222:225], v197 offset:6144
	ds_read_b128 v[226:229], v197 offset:7168
	global_load_lds_dwordx4 v164, s[10:11]
	s_add_i32 m0, s85, 0xe000
	s_nop 0
	global_load_lds_dwordx4 v166, s[10:11]
	s_waitcnt vmcnt(8)
	s_waitcnt lgkmcnt(0)
	s_setprio 1
	s_barrier
	v_mfma_f32_16x16x32_bf16 v[114:117], v[130:133], v[198:201], 0
	v_mfma_f32_16x16x32_bf16 v[118:121], v[138:141], v[198:201], 0
	v_mfma_f32_16x16x32_bf16 v[102:105], v[130:133], v[206:209], 0
	v_mfma_f32_16x16x32_bf16 v[98:101], v[138:141], v[206:209], 0
	v_mfma_f32_16x16x32_bf16 v[86:89], v[130:133], v[214:217], 0
	v_mfma_f32_16x16x32_bf16 v[82:85], v[138:141], v[214:217], 0
	v_mfma_f32_16x16x32_bf16 v[54:57], v[130:133], v[222:225], 0
	v_mfma_f32_16x16x32_bf16 v[50:53], v[138:141], v[222:225], 0
	v_mfma_f32_16x16x32_bf16 v[114:117], v[134:137], v[202:205], v[114:117]
	v_mfma_f32_16x16x32_bf16 v[118:121], v[142:145], v[202:205], v[118:121]
	v_mfma_f32_16x16x32_bf16 v[102:105], v[134:137], v[210:213], v[102:105]
	v_mfma_f32_16x16x32_bf16 v[98:101], v[142:145], v[210:213], v[98:101]
	v_mfma_f32_16x16x32_bf16 v[86:89], v[134:137], v[218:221], v[86:89]
	v_mfma_f32_16x16x32_bf16 v[82:85], v[142:145], v[218:221], v[82:85]
	v_mfma_f32_16x16x32_bf16 v[54:57], v[134:137], v[226:229], v[54:57]
	v_mfma_f32_16x16x32_bf16 v[50:53], v[142:145], v[226:229], v[50:53]
	v_mfma_f32_16x16x32_bf16 v[126:129], v[168:171], v[198:201], 0
	v_mfma_f32_16x16x32_bf16 v[122:125], v[176:179], v[198:201], 0
	v_mfma_f32_16x16x32_bf16 v[110:113], v[168:171], v[206:209], 0
	v_mfma_f32_16x16x32_bf16 v[106:109], v[176:179], v[206:209], 0
	v_mfma_f32_16x16x32_bf16 v[94:97], v[168:171], v[214:217], 0
	v_mfma_f32_16x16x32_bf16 v[90:93], v[176:179], v[214:217], 0
	v_mfma_f32_16x16x32_bf16 v[70:73], v[168:171], v[222:225], 0
	v_mfma_f32_16x16x32_bf16 v[66:69], v[176:179], v[222:225], 0
	v_mfma_f32_16x16x32_bf16 v[126:129], v[172:175], v[202:205], v[126:129]
	v_mfma_f32_16x16x32_bf16 v[122:125], v[180:183], v[202:205], v[122:125]
	v_mfma_f32_16x16x32_bf16 v[110:113], v[172:175], v[210:213], v[110:113]
	v_mfma_f32_16x16x32_bf16 v[106:109], v[180:183], v[210:213], v[106:109]
	v_mfma_f32_16x16x32_bf16 v[94:97], v[172:175], v[218:221], v[94:97]
	v_mfma_f32_16x16x32_bf16 v[90:93], v[180:183], v[218:221], v[90:93]
	v_mfma_f32_16x16x32_bf16 v[70:73], v[172:175], v[226:229], v[70:73]
	v_mfma_f32_16x16x32_bf16 v[66:69], v[180:183], v[226:229], v[66:69]
	s_barrier
	s_setprio 0
	s_add_i32 s66, s67, s97
	s_add_u32 s98, s38, 0x80
	s_addc_u32 s99, s39, 0
	s_mov_b32 m0, s66
	ds_read_b128 v[198:201], v197 offset:16384
	ds_read_b128 v[202:205], v197 offset:17408
	ds_read_b128 v[206:209], v197 offset:18432
	ds_read_b128 v[210:213], v197 offset:19456
	ds_read_b128 v[214:217], v197 offset:20480
	ds_read_b128 v[218:221], v197 offset:21504
	ds_read_b128 v[222:225], v197 offset:22528
	ds_read_b128 v[226:229], v197 offset:23552
	global_load_lds_dwordx4 v156, s[38:39]
	s_add_i32 m0, s66, 0x2000
	s_add_u32 s66, s38, 0x100000
	s_addc_u32 s67, s39, 0
	s_add_i32 vcc_hi, vcc_hi, s97
	global_load_lds_dwordx4 v160, s[38:39]
	s_mov_b32 m0, vcc_hi
	s_add_u32 s100, s86, 0x80
	s_addc_u32 s101, s87, 0
	global_load_lds_dwordx4 v156, s[66:67]
	s_add_i32 m0, vcc_hi, 0x2000
	s_nop 0
	global_load_lds_dwordx4 v160, s[66:67]
	s_mov_b32 m0, s85
	s_nop 0
	global_load_lds_dwordx4 v154, s[86:87]
	s_mov_b32 m0, s92
	s_nop 0
	global_load_lds_dwordx4 v158, s[86:87]
	s_waitcnt vmcnt(8)
	s_waitcnt lgkmcnt(0)
	s_setprio 1
	s_barrier
	v_mfma_f32_16x16x32_bf16 v[62:65], v[130:133], v[198:201], 0
	v_mfma_f32_16x16x32_bf16 v[58:61], v[138:141], v[198:201], 0
	v_mfma_f32_16x16x32_bf16 v[38:41], v[130:133], v[206:209], 0
	v_mfma_f32_16x16x32_bf16 v[34:37], v[138:141], v[206:209], 0
	v_mfma_f32_16x16x32_bf16 v[22:25], v[130:133], v[214:217], 0
	v_mfma_f32_16x16x32_bf16 v[18:21], v[138:141], v[214:217], 0
	v_mfma_f32_16x16x32_bf16 v[6:9], v[130:133], v[222:225], 0
	v_mfma_f32_16x16x32_bf16 v[2:5], v[138:141], v[222:225], 0
	v_mfma_f32_16x16x32_bf16 v[62:65], v[134:137], v[202:205], v[62:65]
	v_mfma_f32_16x16x32_bf16 v[58:61], v[142:145], v[202:205], v[58:61]
	v_mfma_f32_16x16x32_bf16 v[38:41], v[134:137], v[210:213], v[38:41]
	v_mfma_f32_16x16x32_bf16 v[34:37], v[142:145], v[210:213], v[34:37]
	v_mfma_f32_16x16x32_bf16 v[22:25], v[134:137], v[218:221], v[22:25]
	v_mfma_f32_16x16x32_bf16 v[18:21], v[142:145], v[218:221], v[18:21]
	v_mfma_f32_16x16x32_bf16 v[6:9], v[134:137], v[226:229], v[6:9]
	v_mfma_f32_16x16x32_bf16 v[2:5], v[142:145], v[226:229], v[2:5]
	v_mfma_f32_16x16x32_bf16 v[78:81], v[168:171], v[198:201], 0
	v_mfma_f32_16x16x32_bf16 v[74:77], v[176:179], v[198:201], 0
	v_mfma_f32_16x16x32_bf16 v[46:49], v[168:171], v[206:209], 0
	v_mfma_f32_16x16x32_bf16 v[42:45], v[176:179], v[206:209], 0
	v_mfma_f32_16x16x32_bf16 v[30:33], v[168:171], v[214:217], 0
	v_mfma_f32_16x16x32_bf16 v[26:29], v[176:179], v[214:217], 0
	v_mfma_f32_16x16x32_bf16 v[14:17], v[168:171], v[222:225], 0
	v_mfma_f32_16x16x32_bf16 v[10:13], v[176:179], v[222:225], 0
	v_mfma_f32_16x16x32_bf16 v[78:81], v[172:175], v[202:205], v[78:81]
	v_mfma_f32_16x16x32_bf16 v[74:77], v[180:183], v[202:205], v[74:77]
	v_mfma_f32_16x16x32_bf16 v[46:49], v[172:175], v[210:213], v[46:49]
	v_mfma_f32_16x16x32_bf16 v[42:45], v[180:183], v[210:213], v[42:45]
	v_mfma_f32_16x16x32_bf16 v[30:33], v[172:175], v[218:221], v[30:33]
	v_mfma_f32_16x16x32_bf16 v[26:29], v[180:183], v[218:221], v[26:29]
	v_mfma_f32_16x16x32_bf16 v[14:17], v[172:175], v[226:229], v[14:17]
	v_mfma_f32_16x16x32_bf16 v[10:13], v[180:183], v[226:229], v[10:13]
	s_barrier
	s_setprio 0
	s_add_i32 vcc_hi, 0, 0x18000
	s_add_i32 s56, 0, 0x1c000
	v_add_u32_e32 v142, vcc_hi, v1
	v_add_u32_e32 v180, s56, v1
	ds_read_b128 v[130:133], v142
	ds_read_b128 v[134:137], v142 offset:1024
	ds_read_b128 v[138:141], v142 offset:2048
	ds_read_b128 v[142:145], v142 offset:3072
	ds_read_b128 v[168:171], v180
	ds_read_b128 v[172:175], v180 offset:1024
	ds_read_b128 v[176:179], v180 offset:2048
	ds_read_b128 v[180:183], v180 offset:3072
	s_add_u32 s66, s86, 0x100000
	s_addc_u32 s67, s87, 0
	s_mov_b32 m0, s93
	ds_read_b128 v[198:201], v197 offset:32768
	ds_read_b128 v[202:205], v197 offset:33792
	ds_read_b128 v[206:209], v197 offset:34816
	ds_read_b128 v[210:213], v197 offset:35840
	ds_read_b128 v[214:217], v197 offset:36864
	ds_read_b128 v[218:221], v197 offset:37888
	ds_read_b128 v[222:225], v197 offset:38912
	ds_read_b128 v[226:229], v197 offset:39936
	global_load_lds_dwordx4 v154, s[66:67]
	s_mov_b32 m0, s42
	s_nop 0
	global_load_lds_dwordx4 v158, s[66:67]
	s_waitcnt vmcnt(8)
	s_waitcnt lgkmcnt(0)
	s_setprio 1
	s_barrier
	v_mfma_f32_16x16x32_bf16 v[114:117], v[130:133], v[198:201], v[114:117]
	v_mfma_f32_16x16x32_bf16 v[118:121], v[138:141], v[198:201], v[118:121]
	v_mfma_f32_16x16x32_bf16 v[102:105], v[130:133], v[206:209], v[102:105]
	v_mfma_f32_16x16x32_bf16 v[98:101], v[138:141], v[206:209], v[98:101]
	v_mfma_f32_16x16x32_bf16 v[86:89], v[130:133], v[214:217], v[86:89]
	v_mfma_f32_16x16x32_bf16 v[82:85], v[138:141], v[214:217], v[82:85]
	v_mfma_f32_16x16x32_bf16 v[54:57], v[130:133], v[222:225], v[54:57]
	v_mfma_f32_16x16x32_bf16 v[50:53], v[138:141], v[222:225], v[50:53]
	v_mfma_f32_16x16x32_bf16 v[114:117], v[134:137], v[202:205], v[114:117]
	v_mfma_f32_16x16x32_bf16 v[118:121], v[142:145], v[202:205], v[118:121]
	v_mfma_f32_16x16x32_bf16 v[102:105], v[134:137], v[210:213], v[102:105]
	v_mfma_f32_16x16x32_bf16 v[98:101], v[142:145], v[210:213], v[98:101]
	v_mfma_f32_16x16x32_bf16 v[86:89], v[134:137], v[218:221], v[86:89]
	v_mfma_f32_16x16x32_bf16 v[82:85], v[142:145], v[218:221], v[82:85]
	v_mfma_f32_16x16x32_bf16 v[54:57], v[134:137], v[226:229], v[54:57]
	v_mfma_f32_16x16x32_bf16 v[50:53], v[142:145], v[226:229], v[50:53]
	v_mfma_f32_16x16x32_bf16 v[126:129], v[168:171], v[198:201], v[126:129]
	v_mfma_f32_16x16x32_bf16 v[122:125], v[176:179], v[198:201], v[122:125]
	v_mfma_f32_16x16x32_bf16 v[110:113], v[168:171], v[206:209], v[110:113]
	v_mfma_f32_16x16x32_bf16 v[106:109], v[176:179], v[206:209], v[106:109]
	v_mfma_f32_16x16x32_bf16 v[94:97], v[168:171], v[214:217], v[94:97]
	v_mfma_f32_16x16x32_bf16 v[90:93], v[176:179], v[214:217], v[90:93]
	v_mfma_f32_16x16x32_bf16 v[70:73], v[168:171], v[222:225], v[70:73]
	v_mfma_f32_16x16x32_bf16 v[66:69], v[176:179], v[222:225], v[66:69]
	v_mfma_f32_16x16x32_bf16 v[126:129], v[172:175], v[202:205], v[126:129]
	v_mfma_f32_16x16x32_bf16 v[122:125], v[180:183], v[202:205], v[122:125]
	v_mfma_f32_16x16x32_bf16 v[110:113], v[172:175], v[210:213], v[110:113]
	v_mfma_f32_16x16x32_bf16 v[106:109], v[180:183], v[210:213], v[106:109]
	v_mfma_f32_16x16x32_bf16 v[94:97], v[172:175], v[218:221], v[94:97]
	v_mfma_f32_16x16x32_bf16 v[90:93], v[180:183], v[218:221], v[90:93]
	v_mfma_f32_16x16x32_bf16 v[70:73], v[172:175], v[226:229], v[70:73]
	v_mfma_f32_16x16x32_bf16 v[66:69], v[180:183], v[226:229], v[66:69]
	s_barrier
	s_setprio 0
	s_add_i32 s57, vcc_hi, s97
	s_mov_b32 m0, s57
	ds_read_b128 v[198:201], v197 offset:49152
	ds_read_b128 v[202:205], v197 offset:50176
	ds_read_b128 v[206:209], v197 offset:51200
	ds_read_b128 v[210:213], v197 offset:52224
	ds_read_b128 v[214:217], v197 offset:53248
	ds_read_b128 v[218:221], v197 offset:54272
	ds_read_b128 v[222:225], v197 offset:55296
	ds_read_b128 v[226:229], v197 offset:56320
	global_load_lds_dwordx4 v156, s[98:99]
	s_add_i32 m0, s57, 0x2000
	s_add_u32 s38, s38, 0x100080
	s_addc_u32 s39, s39, 0
	s_add_i32 s56, s56, s97
	global_load_lds_dwordx4 v160, s[98:99]
	s_mov_b32 m0, s56
	s_nop 0
	global_load_lds_dwordx4 v156, s[38:39]
	s_add_i32 m0, s56, 0x2000
	s_nop 0
	global_load_lds_dwordx4 v160, s[38:39]
	s_mov_b32 m0, s43
	s_nop 0
	global_load_lds_dwordx4 v154, s[100:101]
	s_mov_b32 m0, s90
	s_nop 0
	global_load_lds_dwordx4 v158, s[100:101]
	s_waitcnt vmcnt(8)
	s_waitcnt lgkmcnt(0)
	s_setprio 1
	s_barrier
	v_mfma_f32_16x16x32_bf16 v[62:65], v[130:133], v[198:201], v[62:65]
	v_mfma_f32_16x16x32_bf16 v[58:61], v[138:141], v[198:201], v[58:61]
	v_mfma_f32_16x16x32_bf16 v[38:41], v[130:133], v[206:209], v[38:41]
	v_mfma_f32_16x16x32_bf16 v[34:37], v[138:141], v[206:209], v[34:37]
	v_mfma_f32_16x16x32_bf16 v[22:25], v[130:133], v[214:217], v[22:25]
	v_mfma_f32_16x16x32_bf16 v[18:21], v[138:141], v[214:217], v[18:21]
	v_mfma_f32_16x16x32_bf16 v[6:9], v[130:133], v[222:225], v[6:9]
	v_mfma_f32_16x16x32_bf16 v[2:5], v[138:141], v[222:225], v[2:5]
	v_mfma_f32_16x16x32_bf16 v[62:65], v[134:137], v[202:205], v[62:65]
	v_mfma_f32_16x16x32_bf16 v[58:61], v[142:145], v[202:205], v[58:61]
	v_mfma_f32_16x16x32_bf16 v[38:41], v[134:137], v[210:213], v[38:41]
	v_mfma_f32_16x16x32_bf16 v[34:37], v[142:145], v[210:213], v[34:37]
	v_mfma_f32_16x16x32_bf16 v[22:25], v[134:137], v[218:221], v[22:25]
	v_mfma_f32_16x16x32_bf16 v[18:21], v[142:145], v[218:221], v[18:21]
	v_mfma_f32_16x16x32_bf16 v[6:9], v[134:137], v[226:229], v[6:9]
	v_mfma_f32_16x16x32_bf16 v[2:5], v[142:145], v[226:229], v[2:5]
	v_mfma_f32_16x16x32_bf16 v[78:81], v[168:171], v[198:201], v[78:81]
	v_mfma_f32_16x16x32_bf16 v[74:77], v[176:179], v[198:201], v[74:77]
	v_mfma_f32_16x16x32_bf16 v[46:49], v[168:171], v[206:209], v[46:49]
	v_mfma_f32_16x16x32_bf16 v[42:45], v[176:179], v[206:209], v[42:45]
	v_mfma_f32_16x16x32_bf16 v[30:33], v[168:171], v[214:217], v[30:33]
	v_mfma_f32_16x16x32_bf16 v[26:29], v[176:179], v[214:217], v[26:29]
	v_mfma_f32_16x16x32_bf16 v[14:17], v[168:171], v[222:225], v[14:17]
	v_mfma_f32_16x16x32_bf16 v[10:13], v[176:179], v[222:225], v[10:13]
	v_mfma_f32_16x16x32_bf16 v[78:81], v[172:175], v[202:205], v[78:81]
	v_mfma_f32_16x16x32_bf16 v[74:77], v[180:183], v[202:205], v[74:77]
	v_mfma_f32_16x16x32_bf16 v[46:49], v[172:175], v[210:213], v[46:49]
	v_mfma_f32_16x16x32_bf16 v[42:45], v[180:183], v[210:213], v[42:45]
	v_mfma_f32_16x16x32_bf16 v[30:33], v[172:175], v[218:221], v[30:33]
	v_mfma_f32_16x16x32_bf16 v[26:29], v[180:183], v[218:221], v[26:29]
	v_mfma_f32_16x16x32_bf16 v[14:17], v[172:175], v[226:229], v[14:17]
	v_mfma_f32_16x16x32_bf16 v[10:13], v[180:183], v[226:229], v[10:13]
	s_barrier
	s_setprio 0
	s_add_u32 s40, s40, 0x100
	s_addc_u32 s49, s49, 0
	s_add_u32 s10, s10, 0x100
	s_addc_u32 s11, s11, 0
	s_cmp_ge_u32 vcc_lo, s19
	s_mov_b32 s38, vcc_lo
	s_cbranch_scc1 .Lpeel_done_0
.LBB0_262:
	s_add_i32 vcc_lo, s38, 2
	s_add_u32 s39, s10, 0xfff00080
	s_addc_u32 s66, s11, -1
	s_add_i32 s67, 0, 0x10000
	s_cmp_eq_u32 s35, s38
	s_cselect_b32 s87, s53, s66
	s_cselect_b32 s86, s52, s39
	s_cselect_b32 s39, s13, s49
	s_cselect_b32 s38, s15, s40
	s_add_i32 vcc_hi, 0, 0x14000
	v_add_u32_e32 v142, s67, v1
	v_add_u32_e32 v180, vcc_hi, v1
	ds_read_b128 v[130:133], v142
	ds_read_b128 v[134:137], v142 offset:1024
	ds_read_b128 v[138:141], v142 offset:2048
	ds_read_b128 v[142:145], v142 offset:3072
	ds_read_b128 v[168:171], v180
	ds_read_b128 v[172:175], v180 offset:1024
	ds_read_b128 v[176:179], v180 offset:2048
	ds_read_b128 v[180:183], v180 offset:3072
	s_add_i32 m0, s85, 0xc000
	ds_read_b128 v[198:201], v197
	ds_read_b128 v[202:205], v197 offset:1024
	ds_read_b128 v[206:209], v197 offset:2048
	ds_read_b128 v[210:213], v197 offset:3072
	ds_read_b128 v[214:217], v197 offset:4096
	ds_read_b128 v[218:221], v197 offset:5120
	ds_read_b128 v[222:225], v197 offset:6144
	ds_read_b128 v[226:229], v197 offset:7168
	global_load_lds_dwordx4 v164, s[10:11]
	s_add_i32 m0, s85, 0xe000
	s_nop 0
	global_load_lds_dwordx4 v166, s[10:11]
	s_waitcnt vmcnt(8)
	s_waitcnt lgkmcnt(0)
	s_setprio 1
	s_barrier
	v_mfma_f32_16x16x32_bf16 v[114:117], v[130:133], v[198:201], v[114:117]
	v_mfma_f32_16x16x32_bf16 v[118:121], v[138:141], v[198:201], v[118:121]
	v_mfma_f32_16x16x32_bf16 v[102:105], v[130:133], v[206:209], v[102:105]
	v_mfma_f32_16x16x32_bf16 v[98:101], v[138:141], v[206:209], v[98:101]
	v_mfma_f32_16x16x32_bf16 v[86:89], v[130:133], v[214:217], v[86:89]
	v_mfma_f32_16x16x32_bf16 v[82:85], v[138:141], v[214:217], v[82:85]
	v_mfma_f32_16x16x32_bf16 v[54:57], v[130:133], v[222:225], v[54:57]
	v_mfma_f32_16x16x32_bf16 v[50:53], v[138:141], v[222:225], v[50:53]
	v_mfma_f32_16x16x32_bf16 v[114:117], v[134:137], v[202:205], v[114:117]
	v_mfma_f32_16x16x32_bf16 v[118:121], v[142:145], v[202:205], v[118:121]
	v_mfma_f32_16x16x32_bf16 v[102:105], v[134:137], v[210:213], v[102:105]
	v_mfma_f32_16x16x32_bf16 v[98:101], v[142:145], v[210:213], v[98:101]
	v_mfma_f32_16x16x32_bf16 v[86:89], v[134:137], v[218:221], v[86:89]
	v_mfma_f32_16x16x32_bf16 v[82:85], v[142:145], v[218:221], v[82:85]
	v_mfma_f32_16x16x32_bf16 v[54:57], v[134:137], v[226:229], v[54:57]
	v_mfma_f32_16x16x32_bf16 v[50:53], v[142:145], v[226:229], v[50:53]
	v_mfma_f32_16x16x32_bf16 v[126:129], v[168:171], v[198:201], v[126:129]
	v_mfma_f32_16x16x32_bf16 v[122:125], v[176:179], v[198:201], v[122:125]
	v_mfma_f32_16x16x32_bf16 v[110:113], v[168:171], v[206:209], v[110:113]
	v_mfma_f32_16x16x32_bf16 v[106:109], v[176:179], v[206:209], v[106:109]
	v_mfma_f32_16x16x32_bf16 v[94:97], v[168:171], v[214:217], v[94:97]
	v_mfma_f32_16x16x32_bf16 v[90:93], v[176:179], v[214:217], v[90:93]
	v_mfma_f32_16x16x32_bf16 v[70:73], v[168:171], v[222:225], v[70:73]
	v_mfma_f32_16x16x32_bf16 v[66:69], v[176:179], v[222:225], v[66:69]
	v_mfma_f32_16x16x32_bf16 v[126:129], v[172:175], v[202:205], v[126:129]
	v_mfma_f32_16x16x32_bf16 v[122:125], v[180:183], v[202:205], v[122:125]
	v_mfma_f32_16x16x32_bf16 v[110:113], v[172:175], v[210:213], v[110:113]
	v_mfma_f32_16x16x32_bf16 v[106:109], v[180:183], v[210:213], v[106:109]
	v_mfma_f32_16x16x32_bf16 v[94:97], v[172:175], v[218:221], v[94:97]
	v_mfma_f32_16x16x32_bf16 v[90:93], v[180:183], v[218:221], v[90:93]
	v_mfma_f32_16x16x32_bf16 v[70:73], v[172:175], v[226:229], v[70:73]
	v_mfma_f32_16x16x32_bf16 v[66:69], v[180:183], v[226:229], v[66:69]
	s_barrier
	s_setprio 0
	s_add_i32 s66, s67, s97
	s_add_u32 s98, s38, 0x80
	s_addc_u32 s99, s39, 0
	s_mov_b32 m0, s66
	ds_read_b128 v[198:201], v197 offset:16384
	ds_read_b128 v[202:205], v197 offset:17408
	ds_read_b128 v[206:209], v197 offset:18432
	ds_read_b128 v[210:213], v197 offset:19456
	ds_read_b128 v[214:217], v197 offset:20480
	ds_read_b128 v[218:221], v197 offset:21504
	ds_read_b128 v[222:225], v197 offset:22528
	ds_read_b128 v[226:229], v197 offset:23552
	global_load_lds_dwordx4 v156, s[38:39]
	s_add_i32 m0, s66, 0x2000
	s_add_u32 s66, s38, 0x100000
	s_addc_u32 s67, s39, 0
	s_add_i32 vcc_hi, vcc_hi, s97
	global_load_lds_dwordx4 v160, s[38:39]
	s_mov_b32 m0, vcc_hi
	s_add_u32 s100, s86, 0x80
	s_addc_u32 s101, s87, 0
	global_load_lds_dwordx4 v156, s[66:67]
	s_add_i32 m0, vcc_hi, 0x2000
	s_nop 0
	global_load_lds_dwordx4 v160, s[66:67]
	s_mov_b32 m0, s85
	s_nop 0
	global_load_lds_dwordx4 v154, s[86:87]
	s_mov_b32 m0, s92
	s_nop 0
	global_load_lds_dwordx4 v158, s[86:87]
	s_waitcnt vmcnt(8)
	s_waitcnt lgkmcnt(0)
	s_setprio 1
	s_barrier
	v_mfma_f32_16x16x32_bf16 v[62:65], v[130:133], v[198:201], v[62:65]
	v_mfma_f32_16x16x32_bf16 v[58:61], v[138:141], v[198:201], v[58:61]
	v_mfma_f32_16x16x32_bf16 v[38:41], v[130:133], v[206:209], v[38:41]
	v_mfma_f32_16x16x32_bf16 v[34:37], v[138:141], v[206:209], v[34:37]
	v_mfma_f32_16x16x32_bf16 v[22:25], v[130:133], v[214:217], v[22:25]
	v_mfma_f32_16x16x32_bf16 v[18:21], v[138:141], v[214:217], v[18:21]
	v_mfma_f32_16x16x32_bf16 v[6:9], v[130:133], v[222:225], v[6:9]
	v_mfma_f32_16x16x32_bf16 v[2:5], v[138:141], v[222:225], v[2:5]
	v_mfma_f32_16x16x32_bf16 v[62:65], v[134:137], v[202:205], v[62:65]
	v_mfma_f32_16x16x32_bf16 v[58:61], v[142:145], v[202:205], v[58:61]
	v_mfma_f32_16x16x32_bf16 v[38:41], v[134:137], v[210:213], v[38:41]
	v_mfma_f32_16x16x32_bf16 v[34:37], v[142:145], v[210:213], v[34:37]
	v_mfma_f32_16x16x32_bf16 v[22:25], v[134:137], v[218:221], v[22:25]
	v_mfma_f32_16x16x32_bf16 v[18:21], v[142:145], v[218:221], v[18:21]
	v_mfma_f32_16x16x32_bf16 v[6:9], v[134:137], v[226:229], v[6:9]
	v_mfma_f32_16x16x32_bf16 v[2:5], v[142:145], v[226:229], v[2:5]
	v_mfma_f32_16x16x32_bf16 v[78:81], v[168:171], v[198:201], v[78:81]
	v_mfma_f32_16x16x32_bf16 v[74:77], v[176:179], v[198:201], v[74:77]
	v_mfma_f32_16x16x32_bf16 v[46:49], v[168:171], v[206:209], v[46:49]
	v_mfma_f32_16x16x32_bf16 v[42:45], v[176:179], v[206:209], v[42:45]
	v_mfma_f32_16x16x32_bf16 v[30:33], v[168:171], v[214:217], v[30:33]
	v_mfma_f32_16x16x32_bf16 v[26:29], v[176:179], v[214:217], v[26:29]
	v_mfma_f32_16x16x32_bf16 v[14:17], v[168:171], v[222:225], v[14:17]
	v_mfma_f32_16x16x32_bf16 v[10:13], v[176:179], v[222:225], v[10:13]
	v_mfma_f32_16x16x32_bf16 v[78:81], v[172:175], v[202:205], v[78:81]
	v_mfma_f32_16x16x32_bf16 v[74:77], v[180:183], v[202:205], v[74:77]
	v_mfma_f32_16x16x32_bf16 v[46:49], v[172:175], v[210:213], v[46:49]
	v_mfma_f32_16x16x32_bf16 v[42:45], v[180:183], v[210:213], v[42:45]
	v_mfma_f32_16x16x32_bf16 v[30:33], v[172:175], v[218:221], v[30:33]
	v_mfma_f32_16x16x32_bf16 v[26:29], v[180:183], v[218:221], v[26:29]
	v_mfma_f32_16x16x32_bf16 v[14:17], v[172:175], v[226:229], v[14:17]
	v_mfma_f32_16x16x32_bf16 v[10:13], v[180:183], v[226:229], v[10:13]
	s_barrier
	s_setprio 0
	s_add_i32 vcc_hi, 0, 0x18000
	s_add_i32 s56, 0, 0x1c000
	v_add_u32_e32 v142, vcc_hi, v1
	v_add_u32_e32 v180, s56, v1
	ds_read_b128 v[130:133], v142
	ds_read_b128 v[134:137], v142 offset:1024
	ds_read_b128 v[138:141], v142 offset:2048
	ds_read_b128 v[142:145], v142 offset:3072
	ds_read_b128 v[168:171], v180
	ds_read_b128 v[172:175], v180 offset:1024
	ds_read_b128 v[176:179], v180 offset:2048
	ds_read_b128 v[180:183], v180 offset:3072
	s_add_u32 s66, s86, 0x100000
	s_addc_u32 s67, s87, 0
	s_mov_b32 m0, s93
	ds_read_b128 v[198:201], v197 offset:32768
	ds_read_b128 v[202:205], v197 offset:33792
	ds_read_b128 v[206:209], v197 offset:34816
	ds_read_b128 v[210:213], v197 offset:35840
	ds_read_b128 v[214:217], v197 offset:36864
	ds_read_b128 v[218:221], v197 offset:37888
	ds_read_b128 v[222:225], v197 offset:38912
	ds_read_b128 v[226:229], v197 offset:39936
	global_load_lds_dwordx4 v154, s[66:67]
	s_mov_b32 m0, s42
	s_nop 0
	global_load_lds_dwordx4 v158, s[66:67]
	s_waitcnt vmcnt(8)
	s_waitcnt lgkmcnt(0)
	s_setprio 1
	s_barrier
	v_mfma_f32_16x16x32_bf16 v[114:117], v[130:133], v[198:201], v[114:117]
	v_mfma_f32_16x16x32_bf16 v[118:121], v[138:141], v[198:201], v[118:121]
	v_mfma_f32_16x16x32_bf16 v[102:105], v[130:133], v[206:209], v[102:105]
	v_mfma_f32_16x16x32_bf16 v[98:101], v[138:141], v[206:209], v[98:101]
	v_mfma_f32_16x16x32_bf16 v[86:89], v[130:133], v[214:217], v[86:89]
	v_mfma_f32_16x16x32_bf16 v[82:85], v[138:141], v[214:217], v[82:85]
	v_mfma_f32_16x16x32_bf16 v[54:57], v[130:133], v[222:225], v[54:57]
	v_mfma_f32_16x16x32_bf16 v[50:53], v[138:141], v[222:225], v[50:53]
	v_mfma_f32_16x16x32_bf16 v[114:117], v[134:137], v[202:205], v[114:117]
	v_mfma_f32_16x16x32_bf16 v[118:121], v[142:145], v[202:205], v[118:121]
	v_mfma_f32_16x16x32_bf16 v[102:105], v[134:137], v[210:213], v[102:105]
	v_mfma_f32_16x16x32_bf16 v[98:101], v[142:145], v[210:213], v[98:101]
	v_mfma_f32_16x16x32_bf16 v[86:89], v[134:137], v[218:221], v[86:89]
	v_mfma_f32_16x16x32_bf16 v[82:85], v[142:145], v[218:221], v[82:85]
	v_mfma_f32_16x16x32_bf16 v[54:57], v[134:137], v[226:229], v[54:57]
	v_mfma_f32_16x16x32_bf16 v[50:53], v[142:145], v[226:229], v[50:53]
	v_mfma_f32_16x16x32_bf16 v[126:129], v[168:171], v[198:201], v[126:129]
	v_mfma_f32_16x16x32_bf16 v[122:125], v[176:179], v[198:201], v[122:125]
	v_mfma_f32_16x16x32_bf16 v[110:113], v[168:171], v[206:209], v[110:113]
	v_mfma_f32_16x16x32_bf16 v[106:109], v[176:179], v[206:209], v[106:109]
	v_mfma_f32_16x16x32_bf16 v[94:97], v[168:171], v[214:217], v[94:97]
	v_mfma_f32_16x16x32_bf16 v[90:93], v[176:179], v[214:217], v[90:93]
	v_mfma_f32_16x16x32_bf16 v[70:73], v[168:171], v[222:225], v[70:73]
	v_mfma_f32_16x16x32_bf16 v[66:69], v[176:179], v[222:225], v[66:69]
	v_mfma_f32_16x16x32_bf16 v[126:129], v[172:175], v[202:205], v[126:129]
	v_mfma_f32_16x16x32_bf16 v[122:125], v[180:183], v[202:205], v[122:125]
	v_mfma_f32_16x16x32_bf16 v[110:113], v[172:175], v[210:213], v[110:113]
	v_mfma_f32_16x16x32_bf16 v[106:109], v[180:183], v[210:213], v[106:109]
	v_mfma_f32_16x16x32_bf16 v[94:97], v[172:175], v[218:221], v[94:97]
	v_mfma_f32_16x16x32_bf16 v[90:93], v[180:183], v[218:221], v[90:93]
	v_mfma_f32_16x16x32_bf16 v[70:73], v[172:175], v[226:229], v[70:73]
	v_mfma_f32_16x16x32_bf16 v[66:69], v[180:183], v[226:229], v[66:69]
	s_barrier
	s_setprio 0
	s_add_i32 s57, vcc_hi, s97
	s_mov_b32 m0, s57
	ds_read_b128 v[198:201], v197 offset:49152
	ds_read_b128 v[202:205], v197 offset:50176
	ds_read_b128 v[206:209], v197 offset:51200
	ds_read_b128 v[210:213], v197 offset:52224
	ds_read_b128 v[214:217], v197 offset:53248
	ds_read_b128 v[218:221], v197 offset:54272
	ds_read_b128 v[222:225], v197 offset:55296
	ds_read_b128 v[226:229], v197 offset:56320
	global_load_lds_dwordx4 v156, s[98:99]
	s_add_i32 m0, s57, 0x2000
	s_add_u32 s38, s38, 0x100080
	s_addc_u32 s39, s39, 0
	s_add_i32 s56, s56, s97
	global_load_lds_dwordx4 v160, s[98:99]
	s_mov_b32 m0, s56
	s_nop 0
	global_load_lds_dwordx4 v156, s[38:39]
	s_add_i32 m0, s56, 0x2000
	s_nop 0
	global_load_lds_dwordx4 v160, s[38:39]
	s_mov_b32 m0, s43
	s_nop 0
	global_load_lds_dwordx4 v154, s[100:101]
	s_mov_b32 m0, s90
	s_nop 0
	global_load_lds_dwordx4 v158, s[100:101]
	s_waitcnt vmcnt(8)
	s_waitcnt lgkmcnt(0)
	s_setprio 1
	s_barrier
	v_mfma_f32_16x16x32_bf16 v[62:65], v[130:133], v[198:201], v[62:65]
	v_mfma_f32_16x16x32_bf16 v[58:61], v[138:141], v[198:201], v[58:61]
	v_mfma_f32_16x16x32_bf16 v[38:41], v[130:133], v[206:209], v[38:41]
	v_mfma_f32_16x16x32_bf16 v[34:37], v[138:141], v[206:209], v[34:37]
	v_mfma_f32_16x16x32_bf16 v[22:25], v[130:133], v[214:217], v[22:25]
	v_mfma_f32_16x16x32_bf16 v[18:21], v[138:141], v[214:217], v[18:21]
	v_mfma_f32_16x16x32_bf16 v[6:9], v[130:133], v[222:225], v[6:9]
	v_mfma_f32_16x16x32_bf16 v[2:5], v[138:141], v[222:225], v[2:5]
	v_mfma_f32_16x16x32_bf16 v[62:65], v[134:137], v[202:205], v[62:65]
	v_mfma_f32_16x16x32_bf16 v[58:61], v[142:145], v[202:205], v[58:61]
	v_mfma_f32_16x16x32_bf16 v[38:41], v[134:137], v[210:213], v[38:41]
	v_mfma_f32_16x16x32_bf16 v[34:37], v[142:145], v[210:213], v[34:37]
	v_mfma_f32_16x16x32_bf16 v[22:25], v[134:137], v[218:221], v[22:25]
	v_mfma_f32_16x16x32_bf16 v[18:21], v[142:145], v[218:221], v[18:21]
	v_mfma_f32_16x16x32_bf16 v[6:9], v[134:137], v[226:229], v[6:9]
	v_mfma_f32_16x16x32_bf16 v[2:5], v[142:145], v[226:229], v[2:5]
	v_mfma_f32_16x16x32_bf16 v[78:81], v[168:171], v[198:201], v[78:81]
	v_mfma_f32_16x16x32_bf16 v[74:77], v[176:179], v[198:201], v[74:77]
	v_mfma_f32_16x16x32_bf16 v[46:49], v[168:171], v[206:209], v[46:49]
	v_mfma_f32_16x16x32_bf16 v[42:45], v[176:179], v[206:209], v[42:45]
	v_mfma_f32_16x16x32_bf16 v[30:33], v[168:171], v[214:217], v[30:33]
	v_mfma_f32_16x16x32_bf16 v[26:29], v[176:179], v[214:217], v[26:29]
	v_mfma_f32_16x16x32_bf16 v[14:17], v[168:171], v[222:225], v[14:17]
	v_mfma_f32_16x16x32_bf16 v[10:13], v[176:179], v[222:225], v[10:13]
	v_mfma_f32_16x16x32_bf16 v[78:81], v[172:175], v[202:205], v[78:81]
	v_mfma_f32_16x16x32_bf16 v[74:77], v[180:183], v[202:205], v[74:77]
	v_mfma_f32_16x16x32_bf16 v[46:49], v[172:175], v[210:213], v[46:49]
	v_mfma_f32_16x16x32_bf16 v[42:45], v[180:183], v[210:213], v[42:45]
	v_mfma_f32_16x16x32_bf16 v[30:33], v[172:175], v[218:221], v[30:33]
	v_mfma_f32_16x16x32_bf16 v[26:29], v[180:183], v[218:221], v[26:29]
	v_mfma_f32_16x16x32_bf16 v[14:17], v[172:175], v[226:229], v[14:17]
	v_mfma_f32_16x16x32_bf16 v[10:13], v[180:183], v[226:229], v[10:13]
	s_barrier
	s_setprio 0
	s_add_u32 s40, s40, 0x100
	s_addc_u32 s49, s49, 0
	s_add_u32 s10, s10, 0x100
	s_addc_u32 s11, s11, 0
	s_cmp_ge_u32 vcc_lo, s19
	s_mov_b32 s38, vcc_lo
	s_cbranch_scc0 .LBB0_262

.LBB0_1692:
	s_ashr_i32 s13, s12, 31
	s_lshl_b64 s[16:17], s[12:13], 18
	s_add_u32 s16, s45, s16
	s_addc_u32 s17, s44, s17
	s_and_b64 s[26:27], s[26:27], exec
	s_cselect_b32 s13, s17, s25
	s_cselect_b32 s15, s16, s24
	s_add_u32 s34, s24, 0x100
	s_addc_u32 s35, s25, 0
	s_add_u32 s22, s22, 0x80080
	s_addc_u32 s23, s23, 0
	s_mov_b32 s36, -2
	ds_read_b128 v[128:131], v169
	ds_read_b128 v[132:135], v169 offset:1024
	ds_read_b128 v[136:139], v169 offset:2048
	ds_read_b128 v[140:143], v169 offset:3072
	ds_read_b128 v[158:161], v170
	ds_read_b128 v[162:165], v170 offset:1024
	ds_read_b128 v[172:175], v170 offset:2048
	ds_read_b128 v[176:179], v170 offset:3072
	s_add_u32 s24, s22, 0xfff80080
	s_addc_u32 s25, s23, -1
	s_cmp_eq_u32 s36, 4
	s_cselect_b32 s27, s5, s25
	s_cselect_b32 s26, s4, s24
	s_cselect_b32 s25, s13, s35
	s_cselect_b32 s24, s15, s34
	s_add_i32 m0, s94, 0xc000
	ds_read_b128 v[180:183], v171
	ds_read_b128 v[184:187], v171 offset:1024
	ds_read_b128 v[188:191], v171 offset:2048
	ds_read_b128 v[192:195], v171 offset:3072
	ds_read_b128 v[196:199], v171 offset:4096
	ds_read_b128 v[200:203], v171 offset:5120
	ds_read_b128 v[204:207], v171 offset:6144
	ds_read_b128 v[208:211], v171 offset:7168
	global_load_lds_dwordx4 v152, s[22:23]
	s_add_i32 m0, s94, 0xe000
	s_nop 0
	global_load_lds_dwordx4 v154, s[22:23]
	s_waitcnt vmcnt(8)
	s_waitcnt lgkmcnt(0)
	s_setprio 1
	s_barrier
	v_mfma_f32_16x16x32_bf16 v[80:83], v[128:131], v[180:183], 0
	v_mfma_f32_16x16x32_bf16 v[92:95], v[136:139], v[180:183], 0
	v_mfma_f32_16x16x32_bf16 v[84:87], v[128:131], v[188:191], 0
	v_mfma_f32_16x16x32_bf16 v[96:99], v[136:139], v[188:191], 0
	v_mfma_f32_16x16x32_bf16 v[88:91], v[128:131], v[196:199], 0
	v_mfma_f32_16x16x32_bf16 v[100:103], v[136:139], v[196:199], 0
	v_mfma_f32_16x16x32_bf16 v[72:75], v[128:131], v[204:207], 0
	v_mfma_f32_16x16x32_bf16 v[76:79], v[136:139], v[204:207], 0
	v_mfma_f32_16x16x32_bf16 v[80:83], v[132:135], v[184:187], v[80:83]
	v_mfma_f32_16x16x32_bf16 v[92:95], v[140:143], v[184:187], v[92:95]
	v_mfma_f32_16x16x32_bf16 v[84:87], v[132:135], v[192:195], v[84:87]
	v_mfma_f32_16x16x32_bf16 v[96:99], v[140:143], v[192:195], v[96:99]
	v_mfma_f32_16x16x32_bf16 v[88:91], v[132:135], v[200:203], v[88:91]
	v_mfma_f32_16x16x32_bf16 v[100:103], v[140:143], v[200:203], v[100:103]
	v_mfma_f32_16x16x32_bf16 v[72:75], v[132:135], v[208:211], v[72:75]
	v_mfma_f32_16x16x32_bf16 v[76:79], v[140:143], v[208:211], v[76:79]
	v_mfma_f32_16x16x32_bf16 v[104:107], v[158:161], v[180:183], 0
	v_mfma_f32_16x16x32_bf16 v[116:119], v[172:175], v[180:183], 0
	v_mfma_f32_16x16x32_bf16 v[108:111], v[158:161], v[188:191], 0
	v_mfma_f32_16x16x32_bf16 v[120:123], v[172:175], v[188:191], 0
	v_mfma_f32_16x16x32_bf16 v[112:115], v[158:161], v[196:199], 0
	v_mfma_f32_16x16x32_bf16 v[124:127], v[172:175], v[196:199], 0
	v_mfma_f32_16x16x32_bf16 v[68:71], v[158:161], v[204:207], 0
	v_mfma_f32_16x16x32_bf16 v[64:67], v[172:175], v[204:207], 0
	v_mfma_f32_16x16x32_bf16 v[104:107], v[162:165], v[184:187], v[104:107]
	v_mfma_f32_16x16x32_bf16 v[116:119], v[176:179], v[184:187], v[116:119]
	v_mfma_f32_16x16x32_bf16 v[108:111], v[162:165], v[192:195], v[108:111]
	v_mfma_f32_16x16x32_bf16 v[120:123], v[176:179], v[192:195], v[120:123]
	v_mfma_f32_16x16x32_bf16 v[112:115], v[162:165], v[200:203], v[112:115]
	v_mfma_f32_16x16x32_bf16 v[124:127], v[176:179], v[200:203], v[124:127]
	v_mfma_f32_16x16x32_bf16 v[68:71], v[162:165], v[208:211], v[68:71]
	v_mfma_f32_16x16x32_bf16 v[64:67], v[176:179], v[208:211], v[64:67]
	s_barrier
	s_setprio 0
	s_add_i32 s37, s31, s97
	s_add_u32 s98, s24, 0x80
	s_addc_u32 s99, s25, 0
	s_mov_b32 m0, s37
	ds_read_b128 v[180:183], v171 offset:16384
	ds_read_b128 v[184:187], v171 offset:17408
	ds_read_b128 v[188:191], v171 offset:18432
	ds_read_b128 v[192:195], v171 offset:19456
	ds_read_b128 v[196:199], v171 offset:20480
	ds_read_b128 v[200:203], v171 offset:21504
	ds_read_b128 v[204:207], v171 offset:22528
	ds_read_b128 v[208:211], v171 offset:23552
	global_load_lds_dwordx4 v148, s[24:25]
	s_add_i32 m0, s37, 0x2000
	s_add_u32 s38, s24, 0x20000
	s_addc_u32 s39, s25, 0
	s_add_i32 s37, s33, s97
	global_load_lds_dwordx4 v144, s[24:25]
	s_mov_b32 m0, s37
	s_add_u32 s100, s26, 0x80
	s_addc_u32 s101, s27, 0
	global_load_lds_dwordx4 v148, s[38:39]
	s_add_i32 m0, s37, 0x2000
	s_nop 0
	global_load_lds_dwordx4 v144, s[38:39]
	s_mov_b32 m0, s94
	s_nop 0
	global_load_lds_dwordx4 v150, s[26:27]
	s_mov_b32 m0, s3
	s_nop 0
	global_load_lds_dwordx4 v146, s[26:27]
	s_waitcnt vmcnt(8)
	s_waitcnt lgkmcnt(0)
	s_setprio 1
	s_barrier
	v_mfma_f32_16x16x32_bf16 v[48:51], v[128:131], v[180:183], 0
	v_mfma_f32_16x16x32_bf16 v[52:55], v[136:139], v[180:183], 0
	v_mfma_f32_16x16x32_bf16 v[32:35], v[128:131], v[188:191], 0
	v_mfma_f32_16x16x32_bf16 v[36:39], v[136:139], v[188:191], 0
	v_mfma_f32_16x16x32_bf16 v[16:19], v[128:131], v[196:199], 0
	v_mfma_f32_16x16x32_bf16 v[20:23], v[136:139], v[196:199], 0
	v_mfma_f32_16x16x32_bf16 v[0:3], v[128:131], v[204:207], 0
	v_mfma_f32_16x16x32_bf16 v[4:7], v[136:139], v[204:207], 0
	v_mfma_f32_16x16x32_bf16 v[48:51], v[132:135], v[184:187], v[48:51]
	v_mfma_f32_16x16x32_bf16 v[52:55], v[140:143], v[184:187], v[52:55]
	v_mfma_f32_16x16x32_bf16 v[32:35], v[132:135], v[192:195], v[32:35]
	v_mfma_f32_16x16x32_bf16 v[36:39], v[140:143], v[192:195], v[36:39]
	v_mfma_f32_16x16x32_bf16 v[16:19], v[132:135], v[200:203], v[16:19]
	v_mfma_f32_16x16x32_bf16 v[20:23], v[140:143], v[200:203], v[20:23]
	v_mfma_f32_16x16x32_bf16 v[0:3], v[132:135], v[208:211], v[0:3]
	v_mfma_f32_16x16x32_bf16 v[4:7], v[140:143], v[208:211], v[4:7]
	v_mfma_f32_16x16x32_bf16 v[56:59], v[158:161], v[180:183], 0
	v_mfma_f32_16x16x32_bf16 v[60:63], v[172:175], v[180:183], 0
	v_mfma_f32_16x16x32_bf16 v[40:43], v[158:161], v[188:191], 0
	v_mfma_f32_16x16x32_bf16 v[44:47], v[172:175], v[188:191], 0
	v_mfma_f32_16x16x32_bf16 v[24:27], v[158:161], v[196:199], 0
	v_mfma_f32_16x16x32_bf16 v[28:31], v[172:175], v[196:199], 0
	v_mfma_f32_16x16x32_bf16 v[8:11], v[158:161], v[204:207], 0
	v_mfma_f32_16x16x32_bf16 v[12:15], v[172:175], v[204:207], 0
	v_mfma_f32_16x16x32_bf16 v[56:59], v[162:165], v[184:187], v[56:59]
	v_mfma_f32_16x16x32_bf16 v[60:63], v[176:179], v[184:187], v[60:63]
	v_mfma_f32_16x16x32_bf16 v[40:43], v[162:165], v[192:195], v[40:43]
	v_mfma_f32_16x16x32_bf16 v[44:47], v[176:179], v[192:195], v[44:47]
	v_mfma_f32_16x16x32_bf16 v[24:27], v[162:165], v[200:203], v[24:27]
	v_mfma_f32_16x16x32_bf16 v[28:31], v[176:179], v[200:203], v[28:31]
	v_mfma_f32_16x16x32_bf16 v[8:11], v[162:165], v[208:211], v[8:11]
	v_mfma_f32_16x16x32_bf16 v[12:15], v[176:179], v[208:211], v[12:15]
	s_barrier
	s_setprio 0
	s_add_i32 s37, 0, 0x18000
	s_add_i32 s38, 0, 0x1c000
	v_add_u32_e32 v140, s37, v167
	v_add_u32_e32 v176, s38, v167
	ds_read_b128 v[128:131], v140
	ds_read_b128 v[132:135], v140 offset:1024
	ds_read_b128 v[136:139], v140 offset:2048
	ds_read_b128 v[140:143], v140 offset:3072
	ds_read_b128 v[158:161], v176
	ds_read_b128 v[162:165], v176 offset:1024
	ds_read_b128 v[172:175], v176 offset:2048
	ds_read_b128 v[176:179], v176 offset:3072
	s_add_u32 s26, s26, 0x80000
	s_addc_u32 s27, s27, 0
	s_mov_b32 m0, s7
	ds_read_b128 v[180:183], v171 offset:32768
	ds_read_b128 v[184:187], v171 offset:33792
	ds_read_b128 v[188:191], v171 offset:34816
	ds_read_b128 v[192:195], v171 offset:35840
	ds_read_b128 v[196:199], v171 offset:36864
	ds_read_b128 v[200:203], v171 offset:37888
	ds_read_b128 v[204:207], v171 offset:38912
	ds_read_b128 v[208:211], v171 offset:39936
	global_load_lds_dwordx4 v150, s[26:27]
	s_mov_b32 m0, s19
	s_nop 0
	global_load_lds_dwordx4 v146, s[26:27]
	s_waitcnt vmcnt(8)
	s_waitcnt lgkmcnt(0)
	s_setprio 1
	s_barrier
	v_mfma_f32_16x16x32_bf16 v[80:83], v[128:131], v[180:183], v[80:83]
	v_mfma_f32_16x16x32_bf16 v[92:95], v[136:139], v[180:183], v[92:95]
	v_mfma_f32_16x16x32_bf16 v[84:87], v[128:131], v[188:191], v[84:87]
	v_mfma_f32_16x16x32_bf16 v[96:99], v[136:139], v[188:191], v[96:99]
	v_mfma_f32_16x16x32_bf16 v[88:91], v[128:131], v[196:199], v[88:91]
	v_mfma_f32_16x16x32_bf16 v[100:103], v[136:139], v[196:199], v[100:103]
	v_mfma_f32_16x16x32_bf16 v[72:75], v[128:131], v[204:207], v[72:75]
	v_mfma_f32_16x16x32_bf16 v[76:79], v[136:139], v[204:207], v[76:79]
	v_mfma_f32_16x16x32_bf16 v[80:83], v[132:135], v[184:187], v[80:83]
	v_mfma_f32_16x16x32_bf16 v[92:95], v[140:143], v[184:187], v[92:95]
	v_mfma_f32_16x16x32_bf16 v[84:87], v[132:135], v[192:195], v[84:87]
	v_mfma_f32_16x16x32_bf16 v[96:99], v[140:143], v[192:195], v[96:99]
	v_mfma_f32_16x16x32_bf16 v[88:91], v[132:135], v[200:203], v[88:91]
	v_mfma_f32_16x16x32_bf16 v[100:103], v[140:143], v[200:203], v[100:103]
	v_mfma_f32_16x16x32_bf16 v[72:75], v[132:135], v[208:211], v[72:75]
	v_mfma_f32_16x16x32_bf16 v[76:79], v[140:143], v[208:211], v[76:79]
	v_mfma_f32_16x16x32_bf16 v[104:107], v[158:161], v[180:183], v[104:107]
	v_mfma_f32_16x16x32_bf16 v[116:119], v[172:175], v[180:183], v[116:119]
	v_mfma_f32_16x16x32_bf16 v[108:111], v[158:161], v[188:191], v[108:111]
	v_mfma_f32_16x16x32_bf16 v[120:123], v[172:175], v[188:191], v[120:123]
	v_mfma_f32_16x16x32_bf16 v[112:115], v[158:161], v[196:199], v[112:115]
	v_mfma_f32_16x16x32_bf16 v[124:127], v[172:175], v[196:199], v[124:127]
	v_mfma_f32_16x16x32_bf16 v[68:71], v[158:161], v[204:207], v[68:71]
	v_mfma_f32_16x16x32_bf16 v[64:67], v[172:175], v[204:207], v[64:67]
	v_mfma_f32_16x16x32_bf16 v[104:107], v[162:165], v[184:187], v[104:107]
	v_mfma_f32_16x16x32_bf16 v[116:119], v[176:179], v[184:187], v[116:119]
	v_mfma_f32_16x16x32_bf16 v[108:111], v[162:165], v[192:195], v[108:111]
	v_mfma_f32_16x16x32_bf16 v[120:123], v[176:179], v[192:195], v[120:123]
	v_mfma_f32_16x16x32_bf16 v[112:115], v[162:165], v[200:203], v[112:115]
	v_mfma_f32_16x16x32_bf16 v[124:127], v[176:179], v[200:203], v[124:127]
	v_mfma_f32_16x16x32_bf16 v[68:71], v[162:165], v[208:211], v[68:71]
	v_mfma_f32_16x16x32_bf16 v[64:67], v[176:179], v[208:211], v[64:67]
	s_barrier
	s_setprio 0
	s_add_i32 s26, s37, s97
	s_mov_b32 m0, s26
	ds_read_b128 v[180:183], v171 offset:49152
	ds_read_b128 v[184:187], v171 offset:50176
	ds_read_b128 v[188:191], v171 offset:51200
	ds_read_b128 v[192:195], v171 offset:52224
	ds_read_b128 v[196:199], v171 offset:53248
	ds_read_b128 v[200:203], v171 offset:54272
	ds_read_b128 v[204:207], v171 offset:55296
	ds_read_b128 v[208:211], v171 offset:56320
	global_load_lds_dwordx4 v148, s[98:99]
	s_add_i32 m0, s26, 0x2000
	s_add_u32 s24, s24, 0x20080
	s_addc_u32 s25, s25, 0
	s_add_i32 s26, s38, s97
	global_load_lds_dwordx4 v144, s[98:99]
	s_mov_b32 m0, s26
	s_nop 0
	global_load_lds_dwordx4 v148, s[24:25]
	s_add_i32 m0, s26, 0x2000
	s_nop 0
	global_load_lds_dwordx4 v144, s[24:25]
	s_mov_b32 m0, s28
	s_nop 0
	global_load_lds_dwordx4 v150, s[100:101]
	s_mov_b32 m0, s29
	s_nop 0
	global_load_lds_dwordx4 v146, s[100:101]
	s_waitcnt vmcnt(8)
	s_waitcnt lgkmcnt(0)
	s_setprio 1
	s_barrier
	v_mfma_f32_16x16x32_bf16 v[48:51], v[128:131], v[180:183], v[48:51]
	v_mfma_f32_16x16x32_bf16 v[52:55], v[136:139], v[180:183], v[52:55]
	v_mfma_f32_16x16x32_bf16 v[32:35], v[128:131], v[188:191], v[32:35]
	v_mfma_f32_16x16x32_bf16 v[36:39], v[136:139], v[188:191], v[36:39]
	v_mfma_f32_16x16x32_bf16 v[16:19], v[128:131], v[196:199], v[16:19]
	v_mfma_f32_16x16x32_bf16 v[20:23], v[136:139], v[196:199], v[20:23]
	v_mfma_f32_16x16x32_bf16 v[0:3], v[128:131], v[204:207], v[0:3]
	v_mfma_f32_16x16x32_bf16 v[4:7], v[136:139], v[204:207], v[4:7]
	v_mfma_f32_16x16x32_bf16 v[48:51], v[132:135], v[184:187], v[48:51]
	v_mfma_f32_16x16x32_bf16 v[52:55], v[140:143], v[184:187], v[52:55]
	v_mfma_f32_16x16x32_bf16 v[32:35], v[132:135], v[192:195], v[32:35]
	v_mfma_f32_16x16x32_bf16 v[36:39], v[140:143], v[192:195], v[36:39]
	v_mfma_f32_16x16x32_bf16 v[16:19], v[132:135], v[200:203], v[16:19]
	v_mfma_f32_16x16x32_bf16 v[20:23], v[140:143], v[200:203], v[20:23]
	v_mfma_f32_16x16x32_bf16 v[0:3], v[132:135], v[208:211], v[0:3]
	v_mfma_f32_16x16x32_bf16 v[4:7], v[140:143], v[208:211], v[4:7]
	v_mfma_f32_16x16x32_bf16 v[56:59], v[158:161], v[180:183], v[56:59]
	v_mfma_f32_16x16x32_bf16 v[60:63], v[172:175], v[180:183], v[60:63]
	v_mfma_f32_16x16x32_bf16 v[40:43], v[158:161], v[188:191], v[40:43]
	v_mfma_f32_16x16x32_bf16 v[44:47], v[172:175], v[188:191], v[44:47]
	v_mfma_f32_16x16x32_bf16 v[24:27], v[158:161], v[196:199], v[24:27]
	v_mfma_f32_16x16x32_bf16 v[28:31], v[172:175], v[196:199], v[28:31]
	v_mfma_f32_16x16x32_bf16 v[8:11], v[158:161], v[204:207], v[8:11]
	v_mfma_f32_16x16x32_bf16 v[12:15], v[172:175], v[204:207], v[12:15]
	v_mfma_f32_16x16x32_bf16 v[56:59], v[162:165], v[184:187], v[56:59]
	v_mfma_f32_16x16x32_bf16 v[60:63], v[176:179], v[184:187], v[60:63]
	v_mfma_f32_16x16x32_bf16 v[40:43], v[162:165], v[192:195], v[40:43]
	v_mfma_f32_16x16x32_bf16 v[44:47], v[176:179], v[192:195], v[44:47]
	v_mfma_f32_16x16x32_bf16 v[24:27], v[162:165], v[200:203], v[24:27]
	v_mfma_f32_16x16x32_bf16 v[28:31], v[176:179], v[200:203], v[28:31]
	v_mfma_f32_16x16x32_bf16 v[8:11], v[162:165], v[208:211], v[8:11]
	v_mfma_f32_16x16x32_bf16 v[12:15], v[176:179], v[208:211], v[12:15]
	s_barrier
	s_setprio 0
	s_add_i32 s36, s36, 2
	s_add_u32 s34, s34, 0x100
	s_addc_u32 s35, s35, 0
	s_add_u32 s22, s22, 0x100
	s_addc_u32 s23, s23, 0
	s_cmp_gt_u32 s36, 5
	s_cbranch_scc1 .Lpeel_done_1
.LBB0_1693:
	ds_read_b128 v[128:131], v169
	ds_read_b128 v[132:135], v169 offset:1024
	ds_read_b128 v[136:139], v169 offset:2048
	ds_read_b128 v[140:143], v169 offset:3072
	ds_read_b128 v[158:161], v170
	ds_read_b128 v[162:165], v170 offset:1024
	ds_read_b128 v[172:175], v170 offset:2048
	ds_read_b128 v[176:179], v170 offset:3072
	s_add_u32 s24, s22, 0xfff80080
	s_addc_u32 s25, s23, -1
	s_cmp_eq_u32 s36, 4
	s_cselect_b32 s27, s5, s25
	s_cselect_b32 s26, s4, s24
	s_cselect_b32 s25, s13, s35
	s_cselect_b32 s24, s15, s34
	s_add_i32 m0, s94, 0xc000
	ds_read_b128 v[180:183], v171
	ds_read_b128 v[184:187], v171 offset:1024
	ds_read_b128 v[188:191], v171 offset:2048
	ds_read_b128 v[192:195], v171 offset:3072
	ds_read_b128 v[196:199], v171 offset:4096
	ds_read_b128 v[200:203], v171 offset:5120
	ds_read_b128 v[204:207], v171 offset:6144
	ds_read_b128 v[208:211], v171 offset:7168
	global_load_lds_dwordx4 v152, s[22:23]
	s_add_i32 m0, s94, 0xe000
	s_nop 0
	global_load_lds_dwordx4 v154, s[22:23]
	s_waitcnt vmcnt(8)
	s_waitcnt lgkmcnt(0)
	s_setprio 1
	s_barrier
	v_mfma_f32_16x16x32_bf16 v[80:83], v[128:131], v[180:183], v[80:83]
	v_mfma_f32_16x16x32_bf16 v[92:95], v[136:139], v[180:183], v[92:95]
	v_mfma_f32_16x16x32_bf16 v[84:87], v[128:131], v[188:191], v[84:87]
	v_mfma_f32_16x16x32_bf16 v[96:99], v[136:139], v[188:191], v[96:99]
	v_mfma_f32_16x16x32_bf16 v[88:91], v[128:131], v[196:199], v[88:91]
	v_mfma_f32_16x16x32_bf16 v[100:103], v[136:139], v[196:199], v[100:103]
	v_mfma_f32_16x16x32_bf16 v[72:75], v[128:131], v[204:207], v[72:75]
	v_mfma_f32_16x16x32_bf16 v[76:79], v[136:139], v[204:207], v[76:79]
	v_mfma_f32_16x16x32_bf16 v[80:83], v[132:135], v[184:187], v[80:83]
	v_mfma_f32_16x16x32_bf16 v[92:95], v[140:143], v[184:187], v[92:95]
	v_mfma_f32_16x16x32_bf16 v[84:87], v[132:135], v[192:195], v[84:87]
	v_mfma_f32_16x16x32_bf16 v[96:99], v[140:143], v[192:195], v[96:99]
	v_mfma_f32_16x16x32_bf16 v[88:91], v[132:135], v[200:203], v[88:91]
	v_mfma_f32_16x16x32_bf16 v[100:103], v[140:143], v[200:203], v[100:103]
	v_mfma_f32_16x16x32_bf16 v[72:75], v[132:135], v[208:211], v[72:75]
	v_mfma_f32_16x16x32_bf16 v[76:79], v[140:143], v[208:211], v[76:79]
	v_mfma_f32_16x16x32_bf16 v[104:107], v[158:161], v[180:183], v[104:107]
	v_mfma_f32_16x16x32_bf16 v[116:119], v[172:175], v[180:183], v[116:119]
	v_mfma_f32_16x16x32_bf16 v[108:111], v[158:161], v[188:191], v[108:111]
	v_mfma_f32_16x16x32_bf16 v[120:123], v[172:175], v[188:191], v[120:123]
	v_mfma_f32_16x16x32_bf16 v[112:115], v[158:161], v[196:199], v[112:115]
	v_mfma_f32_16x16x32_bf16 v[124:127], v[172:175], v[196:199], v[124:127]
	v_mfma_f32_16x16x32_bf16 v[68:71], v[158:161], v[204:207], v[68:71]
	v_mfma_f32_16x16x32_bf16 v[64:67], v[172:175], v[204:207], v[64:67]
	v_mfma_f32_16x16x32_bf16 v[104:107], v[162:165], v[184:187], v[104:107]
	v_mfma_f32_16x16x32_bf16 v[116:119], v[176:179], v[184:187], v[116:119]
	v_mfma_f32_16x16x32_bf16 v[108:111], v[162:165], v[192:195], v[108:111]
	v_mfma_f32_16x16x32_bf16 v[120:123], v[176:179], v[192:195], v[120:123]
	v_mfma_f32_16x16x32_bf16 v[112:115], v[162:165], v[200:203], v[112:115]
	v_mfma_f32_16x16x32_bf16 v[124:127], v[176:179], v[200:203], v[124:127]
	v_mfma_f32_16x16x32_bf16 v[68:71], v[162:165], v[208:211], v[68:71]
	v_mfma_f32_16x16x32_bf16 v[64:67], v[176:179], v[208:211], v[64:67]
	s_barrier
	s_setprio 0
	s_add_i32 s37, s31, s97
	s_add_u32 s98, s24, 0x80
	s_addc_u32 s99, s25, 0
	s_mov_b32 m0, s37
	ds_read_b128 v[180:183], v171 offset:16384
	ds_read_b128 v[184:187], v171 offset:17408
	ds_read_b128 v[188:191], v171 offset:18432
	ds_read_b128 v[192:195], v171 offset:19456
	ds_read_b128 v[196:199], v171 offset:20480
	ds_read_b128 v[200:203], v171 offset:21504
	ds_read_b128 v[204:207], v171 offset:22528
	ds_read_b128 v[208:211], v171 offset:23552
	global_load_lds_dwordx4 v148, s[24:25]
	s_add_i32 m0, s37, 0x2000
	s_add_u32 s38, s24, 0x20000
	s_addc_u32 s39, s25, 0
	s_add_i32 s37, s33, s97
	global_load_lds_dwordx4 v144, s[24:25]
	s_mov_b32 m0, s37
	s_add_u32 s100, s26, 0x80
	s_addc_u32 s101, s27, 0
	global_load_lds_dwordx4 v148, s[38:39]
	s_add_i32 m0, s37, 0x2000
	s_nop 0
	global_load_lds_dwordx4 v144, s[38:39]
	s_mov_b32 m0, s94
	s_nop 0
	global_load_lds_dwordx4 v150, s[26:27]
	s_mov_b32 m0, s3
	s_nop 0
	global_load_lds_dwordx4 v146, s[26:27]
	s_waitcnt vmcnt(8)
	s_waitcnt lgkmcnt(0)
	s_setprio 1
	s_barrier
	v_mfma_f32_16x16x32_bf16 v[48:51], v[128:131], v[180:183], v[48:51]
	v_mfma_f32_16x16x32_bf16 v[52:55], v[136:139], v[180:183], v[52:55]
	v_mfma_f32_16x16x32_bf16 v[32:35], v[128:131], v[188:191], v[32:35]
	v_mfma_f32_16x16x32_bf16 v[36:39], v[136:139], v[188:191], v[36:39]
	v_mfma_f32_16x16x32_bf16 v[16:19], v[128:131], v[196:199], v[16:19]
	v_mfma_f32_16x16x32_bf16 v[20:23], v[136:139], v[196:199], v[20:23]
	v_mfma_f32_16x16x32_bf16 v[0:3], v[128:131], v[204:207], v[0:3]
	v_mfma_f32_16x16x32_bf16 v[4:7], v[136:139], v[204:207], v[4:7]
	v_mfma_f32_16x16x32_bf16 v[48:51], v[132:135], v[184:187], v[48:51]
	v_mfma_f32_16x16x32_bf16 v[52:55], v[140:143], v[184:187], v[52:55]
	v_mfma_f32_16x16x32_bf16 v[32:35], v[132:135], v[192:195], v[32:35]
	v_mfma_f32_16x16x32_bf16 v[36:39], v[140:143], v[192:195], v[36:39]
	v_mfma_f32_16x16x32_bf16 v[16:19], v[132:135], v[200:203], v[16:19]
	v_mfma_f32_16x16x32_bf16 v[20:23], v[140:143], v[200:203], v[20:23]
	v_mfma_f32_16x16x32_bf16 v[0:3], v[132:135], v[208:211], v[0:3]
	v_mfma_f32_16x16x32_bf16 v[4:7], v[140:143], v[208:211], v[4:7]
	v_mfma_f32_16x16x32_bf16 v[56:59], v[158:161], v[180:183], v[56:59]
	v_mfma_f32_16x16x32_bf16 v[60:63], v[172:175], v[180:183], v[60:63]
	v_mfma_f32_16x16x32_bf16 v[40:43], v[158:161], v[188:191], v[40:43]
	v_mfma_f32_16x16x32_bf16 v[44:47], v[172:175], v[188:191], v[44:47]
	v_mfma_f32_16x16x32_bf16 v[24:27], v[158:161], v[196:199], v[24:27]
	v_mfma_f32_16x16x32_bf16 v[28:31], v[172:175], v[196:199], v[28:31]
	v_mfma_f32_16x16x32_bf16 v[8:11], v[158:161], v[204:207], v[8:11]
	v_mfma_f32_16x16x32_bf16 v[12:15], v[172:175], v[204:207], v[12:15]
	v_mfma_f32_16x16x32_bf16 v[56:59], v[162:165], v[184:187], v[56:59]
	v_mfma_f32_16x16x32_bf16 v[60:63], v[176:179], v[184:187], v[60:63]
	v_mfma_f32_16x16x32_bf16 v[40:43], v[162:165], v[192:195], v[40:43]
	v_mfma_f32_16x16x32_bf16 v[44:47], v[176:179], v[192:195], v[44:47]
	v_mfma_f32_16x16x32_bf16 v[24:27], v[162:165], v[200:203], v[24:27]
	v_mfma_f32_16x16x32_bf16 v[28:31], v[176:179], v[200:203], v[28:31]
	v_mfma_f32_16x16x32_bf16 v[8:11], v[162:165], v[208:211], v[8:11]
	v_mfma_f32_16x16x32_bf16 v[12:15], v[176:179], v[208:211], v[12:15]
	s_barrier
	s_setprio 0
	s_add_i32 s37, 0, 0x18000
	s_add_i32 s38, 0, 0x1c000
	v_add_u32_e32 v140, s37, v167
	v_add_u32_e32 v176, s38, v167
	ds_read_b128 v[128:131], v140
	ds_read_b128 v[132:135], v140 offset:1024
	ds_read_b128 v[136:139], v140 offset:2048
	ds_read_b128 v[140:143], v140 offset:3072
	ds_read_b128 v[158:161], v176
	ds_read_b128 v[162:165], v176 offset:1024
	ds_read_b128 v[172:175], v176 offset:2048
	ds_read_b128 v[176:179], v176 offset:3072
	s_add_u32 s26, s26, 0x80000
	s_addc_u32 s27, s27, 0
	s_mov_b32 m0, s7
	ds_read_b128 v[180:183], v171 offset:32768
	ds_read_b128 v[184:187], v171 offset:33792
	ds_read_b128 v[188:191], v171 offset:34816
	ds_read_b128 v[192:195], v171 offset:35840
	ds_read_b128 v[196:199], v171 offset:36864
	ds_read_b128 v[200:203], v171 offset:37888
	ds_read_b128 v[204:207], v171 offset:38912
	ds_read_b128 v[208:211], v171 offset:39936
	global_load_lds_dwordx4 v150, s[26:27]
	s_mov_b32 m0, s19
	s_nop 0
	global_load_lds_dwordx4 v146, s[26:27]
	s_waitcnt vmcnt(8)
	s_waitcnt lgkmcnt(0)
	s_setprio 1
	s_barrier
	v_mfma_f32_16x16x32_bf16 v[80:83], v[128:131], v[180:183], v[80:83]
	v_mfma_f32_16x16x32_bf16 v[92:95], v[136:139], v[180:183], v[92:95]
	v_mfma_f32_16x16x32_bf16 v[84:87], v[128:131], v[188:191], v[84:87]
	v_mfma_f32_16x16x32_bf16 v[96:99], v[136:139], v[188:191], v[96:99]
	v_mfma_f32_16x16x32_bf16 v[88:91], v[128:131], v[196:199], v[88:91]
	v_mfma_f32_16x16x32_bf16 v[100:103], v[136:139], v[196:199], v[100:103]
	v_mfma_f32_16x16x32_bf16 v[72:75], v[128:131], v[204:207], v[72:75]
	v_mfma_f32_16x16x32_bf16 v[76:79], v[136:139], v[204:207], v[76:79]
	v_mfma_f32_16x16x32_bf16 v[80:83], v[132:135], v[184:187], v[80:83]
	v_mfma_f32_16x16x32_bf16 v[92:95], v[140:143], v[184:187], v[92:95]
	v_mfma_f32_16x16x32_bf16 v[84:87], v[132:135], v[192:195], v[84:87]
	v_mfma_f32_16x16x32_bf16 v[96:99], v[140:143], v[192:195], v[96:99]
	v_mfma_f32_16x16x32_bf16 v[88:91], v[132:135], v[200:203], v[88:91]
	v_mfma_f32_16x16x32_bf16 v[100:103], v[140:143], v[200:203], v[100:103]
	v_mfma_f32_16x16x32_bf16 v[72:75], v[132:135], v[208:211], v[72:75]
	v_mfma_f32_16x16x32_bf16 v[76:79], v[140:143], v[208:211], v[76:79]
	v_mfma_f32_16x16x32_bf16 v[104:107], v[158:161], v[180:183], v[104:107]
	v_mfma_f32_16x16x32_bf16 v[116:119], v[172:175], v[180:183], v[116:119]
	v_mfma_f32_16x16x32_bf16 v[108:111], v[158:161], v[188:191], v[108:111]
	v_mfma_f32_16x16x32_bf16 v[120:123], v[172:175], v[188:191], v[120:123]
	v_mfma_f32_16x16x32_bf16 v[112:115], v[158:161], v[196:199], v[112:115]
	v_mfma_f32_16x16x32_bf16 v[124:127], v[172:175], v[196:199], v[124:127]
	v_mfma_f32_16x16x32_bf16 v[68:71], v[158:161], v[204:207], v[68:71]
	v_mfma_f32_16x16x32_bf16 v[64:67], v[172:175], v[204:207], v[64:67]
	v_mfma_f32_16x16x32_bf16 v[104:107], v[162:165], v[184:187], v[104:107]
	v_mfma_f32_16x16x32_bf16 v[116:119], v[176:179], v[184:187], v[116:119]
	v_mfma_f32_16x16x32_bf16 v[108:111], v[162:165], v[192:195], v[108:111]
	v_mfma_f32_16x16x32_bf16 v[120:123], v[176:179], v[192:195], v[120:123]
	v_mfma_f32_16x16x32_bf16 v[112:115], v[162:165], v[200:203], v[112:115]
	v_mfma_f32_16x16x32_bf16 v[124:127], v[176:179], v[200:203], v[124:127]
	v_mfma_f32_16x16x32_bf16 v[68:71], v[162:165], v[208:211], v[68:71]
	v_mfma_f32_16x16x32_bf16 v[64:67], v[176:179], v[208:211], v[64:67]
	s_barrier
	s_setprio 0
	s_add_i32 s26, s37, s97
	s_mov_b32 m0, s26
	ds_read_b128 v[180:183], v171 offset:49152
	ds_read_b128 v[184:187], v171 offset:50176
	ds_read_b128 v[188:191], v171 offset:51200
	ds_read_b128 v[192:195], v171 offset:52224
	ds_read_b128 v[196:199], v171 offset:53248
	ds_read_b128 v[200:203], v171 offset:54272
	ds_read_b128 v[204:207], v171 offset:55296
	ds_read_b128 v[208:211], v171 offset:56320
	global_load_lds_dwordx4 v148, s[98:99]
	s_add_i32 m0, s26, 0x2000
	s_add_u32 s24, s24, 0x20080
	s_addc_u32 s25, s25, 0
	s_add_i32 s26, s38, s97
	global_load_lds_dwordx4 v144, s[98:99]
	s_mov_b32 m0, s26
	s_nop 0
	global_load_lds_dwordx4 v148, s[24:25]
	s_add_i32 m0, s26, 0x2000
	s_nop 0
	global_load_lds_dwordx4 v144, s[24:25]
	s_mov_b32 m0, s28
	s_nop 0
	global_load_lds_dwordx4 v150, s[100:101]
	s_mov_b32 m0, s29
	s_nop 0
	global_load_lds_dwordx4 v146, s[100:101]
	s_waitcnt vmcnt(8)
	s_waitcnt lgkmcnt(0)
	s_setprio 1
	s_barrier
	v_mfma_f32_16x16x32_bf16 v[48:51], v[128:131], v[180:183], v[48:51]
	v_mfma_f32_16x16x32_bf16 v[52:55], v[136:139], v[180:183], v[52:55]
	v_mfma_f32_16x16x32_bf16 v[32:35], v[128:131], v[188:191], v[32:35]
	v_mfma_f32_16x16x32_bf16 v[36:39], v[136:139], v[188:191], v[36:39]
	v_mfma_f32_16x16x32_bf16 v[16:19], v[128:131], v[196:199], v[16:19]
	v_mfma_f32_16x16x32_bf16 v[20:23], v[136:139], v[196:199], v[20:23]
	v_mfma_f32_16x16x32_bf16 v[0:3], v[128:131], v[204:207], v[0:3]
	v_mfma_f32_16x16x32_bf16 v[4:7], v[136:139], v[204:207], v[4:7]
	v_mfma_f32_16x16x32_bf16 v[48:51], v[132:135], v[184:187], v[48:51]
	v_mfma_f32_16x16x32_bf16 v[52:55], v[140:143], v[184:187], v[52:55]
	v_mfma_f32_16x16x32_bf16 v[32:35], v[132:135], v[192:195], v[32:35]
	v_mfma_f32_16x16x32_bf16 v[36:39], v[140:143], v[192:195], v[36:39]
	v_mfma_f32_16x16x32_bf16 v[16:19], v[132:135], v[200:203], v[16:19]
	v_mfma_f32_16x16x32_bf16 v[20:23], v[140:143], v[200:203], v[20:23]
	v_mfma_f32_16x16x32_bf16 v[0:3], v[132:135], v[208:211], v[0:3]
	v_mfma_f32_16x16x32_bf16 v[4:7], v[140:143], v[208:211], v[4:7]
	v_mfma_f32_16x16x32_bf16 v[56:59], v[158:161], v[180:183], v[56:59]
	v_mfma_f32_16x16x32_bf16 v[60:63], v[172:175], v[180:183], v[60:63]
	v_mfma_f32_16x16x32_bf16 v[40:43], v[158:161], v[188:191], v[40:43]
	v_mfma_f32_16x16x32_bf16 v[44:47], v[172:175], v[188:191], v[44:47]
	v_mfma_f32_16x16x32_bf16 v[24:27], v[158:161], v[196:199], v[24:27]
	v_mfma_f32_16x16x32_bf16 v[28:31], v[172:175], v[196:199], v[28:31]
	v_mfma_f32_16x16x32_bf16 v[8:11], v[158:161], v[204:207], v[8:11]
	v_mfma_f32_16x16x32_bf16 v[12:15], v[172:175], v[204:207], v[12:15]
	v_mfma_f32_16x16x32_bf16 v[56:59], v[162:165], v[184:187], v[56:59]
	v_mfma_f32_16x16x32_bf16 v[60:63], v[176:179], v[184:187], v[60:63]
	v_mfma_f32_16x16x32_bf16 v[40:43], v[162:165], v[192:195], v[40:43]
	v_mfma_f32_16x16x32_bf16 v[44:47], v[176:179], v[192:195], v[44:47]
	v_mfma_f32_16x16x32_bf16 v[24:27], v[162:165], v[200:203], v[24:27]
	v_mfma_f32_16x16x32_bf16 v[28:31], v[176:179], v[200:203], v[28:31]
	v_mfma_f32_16x16x32_bf16 v[8:11], v[162:165], v[208:211], v[8:11]
	v_mfma_f32_16x16x32_bf16 v[12:15], v[176:179], v[208:211], v[12:15]
	s_barrier
	s_setprio 0
	s_add_i32 s36, s36, 2
	s_add_u32 s34, s34, 0x100
	s_addc_u32 s35, s35, 0
	s_add_u32 s22, s22, 0x100
	s_addc_u32 s23, s23, 0
	s_cmp_gt_u32 s36, 5
	s_cbranch_scc0 .LBB0_1693

.LBB0_2019:
	s_cmp_lt_u32 s5, 0x3fffffff
	s_cselect_b64 s[40:41], -1, 0
	s_ashr_i32 s23, s22, 31
	s_and_b64 s[40:41], s[36:37], s[40:41]
	s_lshl_b64 s[36:37], s[22:23], 21
	s_add_u32 s5, s86, s36
	s_addc_u32 s21, s87, s37
	s_add_u32 s36, s5, s38
	s_addc_u32 s37, s21, s39
	s_and_b64 s[48:49], s[40:41], exec
	s_cselect_b32 s5, s37, s47
	s_cselect_b32 s23, s36, s46
	s_ashr_i32 s21, s20, 31
	s_lshl_b64 s[48:49], s[20:21], 21
	v_readlane_b32 s68, v254, 13
	v_readlane_b32 s69, v254, 14
	s_add_u32 s21, s68, s48
	s_addc_u32 s43, s69, s49
	s_add_u32 s38, s21, s38
	s_addc_u32 s39, s43, s39
	s_and_b64 s[48:49], s[40:41], exec
	s_cselect_b32 s21, s39, s45
	s_cselect_b32 s43, s38, s44
	s_add_i32 s68, s67, -2
	s_add_u32 s69, s44, 0x100
	s_addc_u32 s70, s45, 0
	s_add_u32 s44, s46, 0x100080
	s_addc_u32 s45, s47, 0
	s_mov_b32 s46, 0
	s_waitcnt vmcnt(0)
	ds_read_b128 v[128:131], v244
	ds_read_b128 v[132:135], v244 offset:1024
	ds_read_b128 v[136:139], v244 offset:2048
	ds_read_b128 v[140:143], v244 offset:3072
	ds_read_b128 v[144:147], v245
	ds_read_b128 v[148:151], v245 offset:1024
	ds_read_b128 v[152:155], v245 offset:2048
	ds_read_b128 v[156:159], v245 offset:3072
	s_add_i32 s71, s46, 2
	s_add_u32 s47, s44, 0xfff00080
	s_addc_u32 s48, s45, -1
	s_cmp_eq_u32 s68, s46
	s_cselect_b32 s46, s43, s69
	s_cselect_b32 s49, s5, s48
	s_cselect_b32 s48, s23, s47
	s_cselect_b32 s47, s21, s70
	s_add_i32 m0, s94, 0xc000
	ds_read_b128 v[160:163], v246
	ds_read_b128 v[164:167], v246 offset:1024
	ds_read_b128 v[168:171], v246 offset:2048
	ds_read_b128 v[172:175], v246 offset:3072
	ds_read_b128 v[176:179], v246 offset:4096
	ds_read_b128 v[180:183], v246 offset:5120
	ds_read_b128 v[184:187], v246 offset:6144
	ds_read_b128 v[188:191], v246 offset:7168
	global_load_lds_dwordx4 v218, s[44:45]
	s_add_i32 m0, s94, 0xe000
	s_nop 0
	global_load_lds_dwordx4 v220, s[44:45]
	s_waitcnt vmcnt(8)
	s_waitcnt lgkmcnt(0)
	s_setprio 1
	s_barrier
	v_mfma_f32_16x16x32_bf16 v[112:115], v[128:131], v[160:163], 0
	v_mfma_f32_16x16x32_bf16 v[116:119], v[136:139], v[160:163], 0
	v_mfma_f32_16x16x32_bf16 v[100:103], v[128:131], v[168:171], 0
	v_mfma_f32_16x16x32_bf16 v[96:99], v[136:139], v[168:171], 0
	v_mfma_f32_16x16x32_bf16 v[84:87], v[128:131], v[176:179], 0
	v_mfma_f32_16x16x32_bf16 v[80:83], v[136:139], v[176:179], 0
	v_mfma_f32_16x16x32_bf16 v[52:55], v[128:131], v[184:187], 0
	v_mfma_f32_16x16x32_bf16 v[48:51], v[136:139], v[184:187], 0
	v_mfma_f32_16x16x32_bf16 v[112:115], v[132:135], v[164:167], v[112:115]
	v_mfma_f32_16x16x32_bf16 v[116:119], v[140:143], v[164:167], v[116:119]
	v_mfma_f32_16x16x32_bf16 v[100:103], v[132:135], v[172:175], v[100:103]
	v_mfma_f32_16x16x32_bf16 v[96:99], v[140:143], v[172:175], v[96:99]
	v_mfma_f32_16x16x32_bf16 v[84:87], v[132:135], v[180:183], v[84:87]
	v_mfma_f32_16x16x32_bf16 v[80:83], v[140:143], v[180:183], v[80:83]
	v_mfma_f32_16x16x32_bf16 v[52:55], v[132:135], v[188:191], v[52:55]
	v_mfma_f32_16x16x32_bf16 v[48:51], v[140:143], v[188:191], v[48:51]
	v_mfma_f32_16x16x32_bf16 v[124:127], v[144:147], v[160:163], 0
	v_mfma_f32_16x16x32_bf16 v[120:123], v[152:155], v[160:163], 0
	v_mfma_f32_16x16x32_bf16 v[108:111], v[144:147], v[168:171], 0
	v_mfma_f32_16x16x32_bf16 v[104:107], v[152:155], v[168:171], 0
	v_mfma_f32_16x16x32_bf16 v[92:95], v[144:147], v[176:179], 0
	v_mfma_f32_16x16x32_bf16 v[88:91], v[152:155], v[176:179], 0
	v_mfma_f32_16x16x32_bf16 v[68:71], v[144:147], v[184:187], 0
	v_mfma_f32_16x16x32_bf16 v[64:67], v[152:155], v[184:187], 0
	v_mfma_f32_16x16x32_bf16 v[124:127], v[148:151], v[164:167], v[124:127]
	v_mfma_f32_16x16x32_bf16 v[120:123], v[156:159], v[164:167], v[120:123]
	v_mfma_f32_16x16x32_bf16 v[108:111], v[148:151], v[172:175], v[108:111]
	v_mfma_f32_16x16x32_bf16 v[104:107], v[156:159], v[172:175], v[104:107]
	v_mfma_f32_16x16x32_bf16 v[92:95], v[148:151], v[180:183], v[92:95]
	v_mfma_f32_16x16x32_bf16 v[88:91], v[156:159], v[180:183], v[88:91]
	v_mfma_f32_16x16x32_bf16 v[68:71], v[148:151], v[188:191], v[68:71]
	v_mfma_f32_16x16x32_bf16 v[64:67], v[156:159], v[188:191], v[64:67]
	s_barrier
	s_setprio 0
	s_add_i32 s76, s60, s97
	s_add_u32 s98, s46, 0x80
	s_addc_u32 s99, s47, 0
	s_mov_b32 m0, s76
	ds_read_b128 v[160:163], v246 offset:16384
	ds_read_b128 v[164:167], v246 offset:17408
	ds_read_b128 v[168:171], v246 offset:18432
	ds_read_b128 v[172:175], v246 offset:19456
	ds_read_b128 v[176:179], v246 offset:20480
	ds_read_b128 v[180:183], v246 offset:21504
	ds_read_b128 v[184:187], v246 offset:22528
	ds_read_b128 v[188:191], v246 offset:23552
	global_load_lds_dwordx4 v210, s[46:47]
	s_add_i32 m0, s76, 0x2000
	s_add_u32 s76, s46, 0x100000
	s_addc_u32 s77, s47, 0
	s_add_i32 s78, s61, s97
	global_load_lds_dwordx4 v214, s[46:47]
	s_mov_b32 m0, s78
	s_add_u32 s100, s48, 0x80
	s_addc_u32 s101, s49, 0
	global_load_lds_dwordx4 v210, s[76:77]
	s_add_i32 m0, s78, 0x2000
	s_nop 0
	global_load_lds_dwordx4 v214, s[76:77]
	s_mov_b32 m0, s94
	s_nop 0
	global_load_lds_dwordx4 v208, s[48:49]
	s_mov_b32 m0, s2
	s_nop 0
	global_load_lds_dwordx4 v212, s[48:49]
	s_waitcnt vmcnt(8)
	s_waitcnt lgkmcnt(0)
	s_setprio 1
	s_barrier
	v_mfma_f32_16x16x32_bf16 v[60:63], v[128:131], v[160:163], 0
	v_mfma_f32_16x16x32_bf16 v[56:59], v[136:139], v[160:163], 0
	v_mfma_f32_16x16x32_bf16 v[36:39], v[128:131], v[168:171], 0
	v_mfma_f32_16x16x32_bf16 v[32:35], v[136:139], v[168:171], 0
	v_mfma_f32_16x16x32_bf16 v[20:23], v[128:131], v[176:179], 0
	v_mfma_f32_16x16x32_bf16 v[16:19], v[136:139], v[176:179], 0
	v_mfma_f32_16x16x32_bf16 v[4:7], v[128:131], v[184:187], 0
	v_mfma_f32_16x16x32_bf16 v[0:3], v[136:139], v[184:187], 0
	v_mfma_f32_16x16x32_bf16 v[60:63], v[132:135], v[164:167], v[60:63]
	v_mfma_f32_16x16x32_bf16 v[56:59], v[140:143], v[164:167], v[56:59]
	v_mfma_f32_16x16x32_bf16 v[36:39], v[132:135], v[172:175], v[36:39]
	v_mfma_f32_16x16x32_bf16 v[32:35], v[140:143], v[172:175], v[32:35]
	v_mfma_f32_16x16x32_bf16 v[20:23], v[132:135], v[180:183], v[20:23]
	v_mfma_f32_16x16x32_bf16 v[16:19], v[140:143], v[180:183], v[16:19]
	v_mfma_f32_16x16x32_bf16 v[4:7], v[132:135], v[188:191], v[4:7]
	v_mfma_f32_16x16x32_bf16 v[0:3], v[140:143], v[188:191], v[0:3]
	v_mfma_f32_16x16x32_bf16 v[76:79], v[144:147], v[160:163], 0
	v_mfma_f32_16x16x32_bf16 v[72:75], v[152:155], v[160:163], 0
	v_mfma_f32_16x16x32_bf16 v[44:47], v[144:147], v[168:171], 0
	v_mfma_f32_16x16x32_bf16 v[40:43], v[152:155], v[168:171], 0
	v_mfma_f32_16x16x32_bf16 v[28:31], v[144:147], v[176:179], 0
	v_mfma_f32_16x16x32_bf16 v[24:27], v[152:155], v[176:179], 0
	v_mfma_f32_16x16x32_bf16 v[12:15], v[144:147], v[184:187], 0
	v_mfma_f32_16x16x32_bf16 v[8:11], v[152:155], v[184:187], 0
	v_mfma_f32_16x16x32_bf16 v[76:79], v[148:151], v[164:167], v[76:79]
	v_mfma_f32_16x16x32_bf16 v[72:75], v[156:159], v[164:167], v[72:75]
	v_mfma_f32_16x16x32_bf16 v[44:47], v[148:151], v[172:175], v[44:47]
	v_mfma_f32_16x16x32_bf16 v[40:43], v[156:159], v[172:175], v[40:43]
	v_mfma_f32_16x16x32_bf16 v[28:31], v[148:151], v[180:183], v[28:31]
	v_mfma_f32_16x16x32_bf16 v[24:27], v[156:159], v[180:183], v[24:27]
	v_mfma_f32_16x16x32_bf16 v[12:15], v[148:151], v[188:191], v[12:15]
	v_mfma_f32_16x16x32_bf16 v[8:11], v[156:159], v[188:191], v[8:11]
	s_barrier
	s_setprio 0
	s_add_i32 s76, 0, 0x18000
	s_add_i32 s77, 0, 0x1c000
	v_add_u32_e32 v140, s76, v243
	v_add_u32_e32 v156, s77, v243
	ds_read_b128 v[128:131], v140
	ds_read_b128 v[132:135], v140 offset:1024
	ds_read_b128 v[136:139], v140 offset:2048
	ds_read_b128 v[140:143], v140 offset:3072
	ds_read_b128 v[144:147], v156
	ds_read_b128 v[148:151], v156 offset:1024
	ds_read_b128 v[152:155], v156 offset:2048
	ds_read_b128 v[156:159], v156 offset:3072
	s_add_u32 s48, s48, 0x100000
	s_addc_u32 s49, s49, 0
	s_mov_b32 m0, s3
	ds_read_b128 v[160:163], v246 offset:32768
	ds_read_b128 v[164:167], v246 offset:33792
	ds_read_b128 v[168:171], v246 offset:34816
	ds_read_b128 v[172:175], v246 offset:35840
	ds_read_b128 v[176:179], v246 offset:36864
	ds_read_b128 v[180:183], v246 offset:37888
	ds_read_b128 v[184:187], v246 offset:38912
	ds_read_b128 v[188:191], v246 offset:39936
	global_load_lds_dwordx4 v208, s[48:49]
	s_mov_b32 m0, s33
	s_nop 0
	global_load_lds_dwordx4 v212, s[48:49]
	s_waitcnt vmcnt(8)
	s_waitcnt lgkmcnt(0)
	s_setprio 1
	s_barrier
	v_mfma_f32_16x16x32_bf16 v[112:115], v[128:131], v[160:163], v[112:115]
	v_mfma_f32_16x16x32_bf16 v[116:119], v[136:139], v[160:163], v[116:119]
	v_mfma_f32_16x16x32_bf16 v[100:103], v[128:131], v[168:171], v[100:103]
	v_mfma_f32_16x16x32_bf16 v[96:99], v[136:139], v[168:171], v[96:99]
	v_mfma_f32_16x16x32_bf16 v[84:87], v[128:131], v[176:179], v[84:87]
	v_mfma_f32_16x16x32_bf16 v[80:83], v[136:139], v[176:179], v[80:83]
	v_mfma_f32_16x16x32_bf16 v[52:55], v[128:131], v[184:187], v[52:55]
	v_mfma_f32_16x16x32_bf16 v[48:51], v[136:139], v[184:187], v[48:51]
	v_mfma_f32_16x16x32_bf16 v[112:115], v[132:135], v[164:167], v[112:115]
	v_mfma_f32_16x16x32_bf16 v[116:119], v[140:143], v[164:167], v[116:119]
	v_mfma_f32_16x16x32_bf16 v[100:103], v[132:135], v[172:175], v[100:103]
	v_mfma_f32_16x16x32_bf16 v[96:99], v[140:143], v[172:175], v[96:99]
	v_mfma_f32_16x16x32_bf16 v[84:87], v[132:135], v[180:183], v[84:87]
	v_mfma_f32_16x16x32_bf16 v[80:83], v[140:143], v[180:183], v[80:83]
	v_mfma_f32_16x16x32_bf16 v[52:55], v[132:135], v[188:191], v[52:55]
	v_mfma_f32_16x16x32_bf16 v[48:51], v[140:143], v[188:191], v[48:51]
	v_mfma_f32_16x16x32_bf16 v[124:127], v[144:147], v[160:163], v[124:127]
	v_mfma_f32_16x16x32_bf16 v[120:123], v[152:155], v[160:163], v[120:123]
	v_mfma_f32_16x16x32_bf16 v[108:111], v[144:147], v[168:171], v[108:111]
	v_mfma_f32_16x16x32_bf16 v[104:107], v[152:155], v[168:171], v[104:107]
	v_mfma_f32_16x16x32_bf16 v[92:95], v[144:147], v[176:179], v[92:95]
	v_mfma_f32_16x16x32_bf16 v[88:91], v[152:155], v[176:179], v[88:91]
	v_mfma_f32_16x16x32_bf16 v[68:71], v[144:147], v[184:187], v[68:71]
	v_mfma_f32_16x16x32_bf16 v[64:67], v[152:155], v[184:187], v[64:67]
	v_mfma_f32_16x16x32_bf16 v[124:127], v[148:151], v[164:167], v[124:127]
	v_mfma_f32_16x16x32_bf16 v[120:123], v[156:159], v[164:167], v[120:123]
	v_mfma_f32_16x16x32_bf16 v[108:111], v[148:151], v[172:175], v[108:111]
	v_mfma_f32_16x16x32_bf16 v[104:107], v[156:159], v[172:175], v[104:107]
	v_mfma_f32_16x16x32_bf16 v[92:95], v[148:151], v[180:183], v[92:95]
	v_mfma_f32_16x16x32_bf16 v[88:91], v[156:159], v[180:183], v[88:91]
	v_mfma_f32_16x16x32_bf16 v[68:71], v[148:151], v[188:191], v[68:71]
	v_mfma_f32_16x16x32_bf16 v[64:67], v[156:159], v[188:191], v[64:67]
	s_barrier
	s_setprio 0
	s_add_i32 s48, s76, s97
	s_mov_b32 m0, s48
	ds_read_b128 v[160:163], v246 offset:49152
	ds_read_b128 v[164:167], v246 offset:50176
	ds_read_b128 v[168:171], v246 offset:51200
	ds_read_b128 v[172:175], v246 offset:52224
	ds_read_b128 v[176:179], v246 offset:53248
	ds_read_b128 v[180:183], v246 offset:54272
	ds_read_b128 v[184:187], v246 offset:55296
	ds_read_b128 v[188:191], v246 offset:56320
	global_load_lds_dwordx4 v210, s[98:99]
	s_add_i32 m0, s48, 0x2000
	s_add_u32 s46, s46, 0x100080
	s_addc_u32 s47, s47, 0
	s_add_i32 s48, s77, s97
	global_load_lds_dwordx4 v214, s[98:99]
	s_mov_b32 m0, s48
	s_nop 0
	global_load_lds_dwordx4 v210, s[46:47]
	s_add_i32 m0, s48, 0x2000
	s_nop 0
	global_load_lds_dwordx4 v214, s[46:47]
	s_mov_b32 m0, s54
	s_nop 0
	global_load_lds_dwordx4 v208, s[100:101]
	s_mov_b32 m0, s55
	s_nop 0
	global_load_lds_dwordx4 v212, s[100:101]
	s_waitcnt vmcnt(8)
	s_waitcnt lgkmcnt(0)
	s_setprio 1
	s_barrier
	v_mfma_f32_16x16x32_bf16 v[60:63], v[128:131], v[160:163], v[60:63]
	v_mfma_f32_16x16x32_bf16 v[56:59], v[136:139], v[160:163], v[56:59]
	v_mfma_f32_16x16x32_bf16 v[36:39], v[128:131], v[168:171], v[36:39]
	v_mfma_f32_16x16x32_bf16 v[32:35], v[136:139], v[168:171], v[32:35]
	v_mfma_f32_16x16x32_bf16 v[20:23], v[128:131], v[176:179], v[20:23]
	v_mfma_f32_16x16x32_bf16 v[16:19], v[136:139], v[176:179], v[16:19]
	v_mfma_f32_16x16x32_bf16 v[4:7], v[128:131], v[184:187], v[4:7]
	v_mfma_f32_16x16x32_bf16 v[0:3], v[136:139], v[184:187], v[0:3]
	v_mfma_f32_16x16x32_bf16 v[60:63], v[132:135], v[164:167], v[60:63]
	v_mfma_f32_16x16x32_bf16 v[56:59], v[140:143], v[164:167], v[56:59]
	v_mfma_f32_16x16x32_bf16 v[36:39], v[132:135], v[172:175], v[36:39]
	v_mfma_f32_16x16x32_bf16 v[32:35], v[140:143], v[172:175], v[32:35]
	v_mfma_f32_16x16x32_bf16 v[20:23], v[132:135], v[180:183], v[20:23]
	v_mfma_f32_16x16x32_bf16 v[16:19], v[140:143], v[180:183], v[16:19]
	v_mfma_f32_16x16x32_bf16 v[4:7], v[132:135], v[188:191], v[4:7]
	v_mfma_f32_16x16x32_bf16 v[0:3], v[140:143], v[188:191], v[0:3]
	v_mfma_f32_16x16x32_bf16 v[76:79], v[144:147], v[160:163], v[76:79]
	v_mfma_f32_16x16x32_bf16 v[72:75], v[152:155], v[160:163], v[72:75]
	v_mfma_f32_16x16x32_bf16 v[44:47], v[144:147], v[168:171], v[44:47]
	v_mfma_f32_16x16x32_bf16 v[40:43], v[152:155], v[168:171], v[40:43]
	v_mfma_f32_16x16x32_bf16 v[28:31], v[144:147], v[176:179], v[28:31]
	v_mfma_f32_16x16x32_bf16 v[24:27], v[152:155], v[176:179], v[24:27]
	v_mfma_f32_16x16x32_bf16 v[12:15], v[144:147], v[184:187], v[12:15]
	v_mfma_f32_16x16x32_bf16 v[8:11], v[152:155], v[184:187], v[8:11]
	v_mfma_f32_16x16x32_bf16 v[76:79], v[148:151], v[164:167], v[76:79]
	v_mfma_f32_16x16x32_bf16 v[72:75], v[156:159], v[164:167], v[72:75]
	v_mfma_f32_16x16x32_bf16 v[44:47], v[148:151], v[172:175], v[44:47]
	v_mfma_f32_16x16x32_bf16 v[40:43], v[156:159], v[172:175], v[40:43]
	v_mfma_f32_16x16x32_bf16 v[28:31], v[148:151], v[180:183], v[28:31]
	v_mfma_f32_16x16x32_bf16 v[24:27], v[156:159], v[180:183], v[24:27]
	v_mfma_f32_16x16x32_bf16 v[12:15], v[148:151], v[188:191], v[12:15]
	v_mfma_f32_16x16x32_bf16 v[8:11], v[156:159], v[188:191], v[8:11]
	s_barrier
	s_setprio 0
	s_add_u32 s69, s69, 0x100
	s_addc_u32 s70, s70, 0
	s_add_u32 s44, s44, 0x100
	s_addc_u32 s45, s45, 0
	s_cmp_ge_u32 s71, s67
	s_mov_b32 s46, s71
	s_cbranch_scc1 .Lpeel_done_2
.LBB0_2020:
	ds_read_b128 v[128:131], v244
	ds_read_b128 v[132:135], v244 offset:1024
	ds_read_b128 v[136:139], v244 offset:2048
	ds_read_b128 v[140:143], v244 offset:3072
	ds_read_b128 v[144:147], v245
	ds_read_b128 v[148:151], v245 offset:1024
	ds_read_b128 v[152:155], v245 offset:2048
	ds_read_b128 v[156:159], v245 offset:3072
	s_add_i32 s71, s46, 2
	s_add_u32 s47, s44, 0xfff00080
	s_addc_u32 s48, s45, -1
	s_cmp_eq_u32 s68, s46
	s_cselect_b32 s46, s43, s69
	s_cselect_b32 s49, s5, s48
	s_cselect_b32 s48, s23, s47
	s_cselect_b32 s47, s21, s70
	s_add_i32 m0, s94, 0xc000
	ds_read_b128 v[160:163], v246
	ds_read_b128 v[164:167], v246 offset:1024
	ds_read_b128 v[168:171], v246 offset:2048
	ds_read_b128 v[172:175], v246 offset:3072
	ds_read_b128 v[176:179], v246 offset:4096
	ds_read_b128 v[180:183], v246 offset:5120
	ds_read_b128 v[184:187], v246 offset:6144
	ds_read_b128 v[188:191], v246 offset:7168
	global_load_lds_dwordx4 v218, s[44:45]
	s_add_i32 m0, s94, 0xe000
	s_nop 0
	global_load_lds_dwordx4 v220, s[44:45]
	s_waitcnt vmcnt(8)
	s_waitcnt lgkmcnt(0)
	s_setprio 1
	s_barrier
	v_mfma_f32_16x16x32_bf16 v[112:115], v[128:131], v[160:163], v[112:115]
	v_mfma_f32_16x16x32_bf16 v[116:119], v[136:139], v[160:163], v[116:119]
	v_mfma_f32_16x16x32_bf16 v[100:103], v[128:131], v[168:171], v[100:103]
	v_mfma_f32_16x16x32_bf16 v[96:99], v[136:139], v[168:171], v[96:99]
	v_mfma_f32_16x16x32_bf16 v[84:87], v[128:131], v[176:179], v[84:87]
	v_mfma_f32_16x16x32_bf16 v[80:83], v[136:139], v[176:179], v[80:83]
	v_mfma_f32_16x16x32_bf16 v[52:55], v[128:131], v[184:187], v[52:55]
	v_mfma_f32_16x16x32_bf16 v[48:51], v[136:139], v[184:187], v[48:51]
	v_mfma_f32_16x16x32_bf16 v[112:115], v[132:135], v[164:167], v[112:115]
	v_mfma_f32_16x16x32_bf16 v[116:119], v[140:143], v[164:167], v[116:119]
	v_mfma_f32_16x16x32_bf16 v[100:103], v[132:135], v[172:175], v[100:103]
	v_mfma_f32_16x16x32_bf16 v[96:99], v[140:143], v[172:175], v[96:99]
	v_mfma_f32_16x16x32_bf16 v[84:87], v[132:135], v[180:183], v[84:87]
	v_mfma_f32_16x16x32_bf16 v[80:83], v[140:143], v[180:183], v[80:83]
	v_mfma_f32_16x16x32_bf16 v[52:55], v[132:135], v[188:191], v[52:55]
	v_mfma_f32_16x16x32_bf16 v[48:51], v[140:143], v[188:191], v[48:51]
	v_mfma_f32_16x16x32_bf16 v[124:127], v[144:147], v[160:163], v[124:127]
	v_mfma_f32_16x16x32_bf16 v[120:123], v[152:155], v[160:163], v[120:123]
	v_mfma_f32_16x16x32_bf16 v[108:111], v[144:147], v[168:171], v[108:111]
	v_mfma_f32_16x16x32_bf16 v[104:107], v[152:155], v[168:171], v[104:107]
	v_mfma_f32_16x16x32_bf16 v[92:95], v[144:147], v[176:179], v[92:95]
	v_mfma_f32_16x16x32_bf16 v[88:91], v[152:155], v[176:179], v[88:91]
	v_mfma_f32_16x16x32_bf16 v[68:71], v[144:147], v[184:187], v[68:71]
	v_mfma_f32_16x16x32_bf16 v[64:67], v[152:155], v[184:187], v[64:67]
	v_mfma_f32_16x16x32_bf16 v[124:127], v[148:151], v[164:167], v[124:127]
	v_mfma_f32_16x16x32_bf16 v[120:123], v[156:159], v[164:167], v[120:123]
	v_mfma_f32_16x16x32_bf16 v[108:111], v[148:151], v[172:175], v[108:111]
	v_mfma_f32_16x16x32_bf16 v[104:107], v[156:159], v[172:175], v[104:107]
	v_mfma_f32_16x16x32_bf16 v[92:95], v[148:151], v[180:183], v[92:95]
	v_mfma_f32_16x16x32_bf16 v[88:91], v[156:159], v[180:183], v[88:91]
	v_mfma_f32_16x16x32_bf16 v[68:71], v[148:151], v[188:191], v[68:71]
	v_mfma_f32_16x16x32_bf16 v[64:67], v[156:159], v[188:191], v[64:67]
	s_barrier
	s_setprio 0
	s_add_i32 s76, s60, s97
	s_add_u32 s98, s46, 0x80
	s_addc_u32 s99, s47, 0
	s_mov_b32 m0, s76
	ds_read_b128 v[160:163], v246 offset:16384
	ds_read_b128 v[164:167], v246 offset:17408
	ds_read_b128 v[168:171], v246 offset:18432
	ds_read_b128 v[172:175], v246 offset:19456
	ds_read_b128 v[176:179], v246 offset:20480
	ds_read_b128 v[180:183], v246 offset:21504
	ds_read_b128 v[184:187], v246 offset:22528
	ds_read_b128 v[188:191], v246 offset:23552
	global_load_lds_dwordx4 v210, s[46:47]
	s_add_i32 m0, s76, 0x2000
	s_add_u32 s76, s46, 0x100000
	s_addc_u32 s77, s47, 0
	s_add_i32 s78, s61, s97
	global_load_lds_dwordx4 v214, s[46:47]
	s_mov_b32 m0, s78
	s_add_u32 s100, s48, 0x80
	s_addc_u32 s101, s49, 0
	global_load_lds_dwordx4 v210, s[76:77]
	s_add_i32 m0, s78, 0x2000
	s_nop 0
	global_load_lds_dwordx4 v214, s[76:77]
	s_mov_b32 m0, s94
	s_nop 0
	global_load_lds_dwordx4 v208, s[48:49]
	s_mov_b32 m0, s2
	s_nop 0
	global_load_lds_dwordx4 v212, s[48:49]
	s_waitcnt vmcnt(8)
	s_waitcnt lgkmcnt(0)
	s_setprio 1
	s_barrier
	v_mfma_f32_16x16x32_bf16 v[60:63], v[128:131], v[160:163], v[60:63]
	v_mfma_f32_16x16x32_bf16 v[56:59], v[136:139], v[160:163], v[56:59]
	v_mfma_f32_16x16x32_bf16 v[36:39], v[128:131], v[168:171], v[36:39]
	v_mfma_f32_16x16x32_bf16 v[32:35], v[136:139], v[168:171], v[32:35]
	v_mfma_f32_16x16x32_bf16 v[20:23], v[128:131], v[176:179], v[20:23]
	v_mfma_f32_16x16x32_bf16 v[16:19], v[136:139], v[176:179], v[16:19]
	v_mfma_f32_16x16x32_bf16 v[4:7], v[128:131], v[184:187], v[4:7]
	v_mfma_f32_16x16x32_bf16 v[0:3], v[136:139], v[184:187], v[0:3]
	v_mfma_f32_16x16x32_bf16 v[60:63], v[132:135], v[164:167], v[60:63]
	v_mfma_f32_16x16x32_bf16 v[56:59], v[140:143], v[164:167], v[56:59]
	v_mfma_f32_16x16x32_bf16 v[36:39], v[132:135], v[172:175], v[36:39]
	v_mfma_f32_16x16x32_bf16 v[32:35], v[140:143], v[172:175], v[32:35]
	v_mfma_f32_16x16x32_bf16 v[20:23], v[132:135], v[180:183], v[20:23]
	v_mfma_f32_16x16x32_bf16 v[16:19], v[140:143], v[180:183], v[16:19]
	v_mfma_f32_16x16x32_bf16 v[4:7], v[132:135], v[188:191], v[4:7]
	v_mfma_f32_16x16x32_bf16 v[0:3], v[140:143], v[188:191], v[0:3]
	v_mfma_f32_16x16x32_bf16 v[76:79], v[144:147], v[160:163], v[76:79]
	v_mfma_f32_16x16x32_bf16 v[72:75], v[152:155], v[160:163], v[72:75]
	v_mfma_f32_16x16x32_bf16 v[44:47], v[144:147], v[168:171], v[44:47]
	v_mfma_f32_16x16x32_bf16 v[40:43], v[152:155], v[168:171], v[40:43]
	v_mfma_f32_16x16x32_bf16 v[28:31], v[144:147], v[176:179], v[28:31]
	v_mfma_f32_16x16x32_bf16 v[24:27], v[152:155], v[176:179], v[24:27]
	v_mfma_f32_16x16x32_bf16 v[12:15], v[144:147], v[184:187], v[12:15]
	v_mfma_f32_16x16x32_bf16 v[8:11], v[152:155], v[184:187], v[8:11]
	v_mfma_f32_16x16x32_bf16 v[76:79], v[148:151], v[164:167], v[76:79]
	v_mfma_f32_16x16x32_bf16 v[72:75], v[156:159], v[164:167], v[72:75]
	v_mfma_f32_16x16x32_bf16 v[44:47], v[148:151], v[172:175], v[44:47]
	v_mfma_f32_16x16x32_bf16 v[40:43], v[156:159], v[172:175], v[40:43]
	v_mfma_f32_16x16x32_bf16 v[28:31], v[148:151], v[180:183], v[28:31]
	v_mfma_f32_16x16x32_bf16 v[24:27], v[156:159], v[180:183], v[24:27]
	v_mfma_f32_16x16x32_bf16 v[12:15], v[148:151], v[188:191], v[12:15]
	v_mfma_f32_16x16x32_bf16 v[8:11], v[156:159], v[188:191], v[8:11]
	s_barrier
	s_setprio 0
	s_add_i32 s76, 0, 0x18000
	s_add_i32 s77, 0, 0x1c000
	v_add_u32_e32 v140, s76, v243
	v_add_u32_e32 v156, s77, v243
	ds_read_b128 v[128:131], v140
	ds_read_b128 v[132:135], v140 offset:1024
	ds_read_b128 v[136:139], v140 offset:2048
	ds_read_b128 v[140:143], v140 offset:3072
	ds_read_b128 v[144:147], v156
	ds_read_b128 v[148:151], v156 offset:1024
	ds_read_b128 v[152:155], v156 offset:2048
	ds_read_b128 v[156:159], v156 offset:3072
	s_add_u32 s48, s48, 0x100000
	s_addc_u32 s49, s49, 0
	s_mov_b32 m0, s3
	ds_read_b128 v[160:163], v246 offset:32768
	ds_read_b128 v[164:167], v246 offset:33792
	ds_read_b128 v[168:171], v246 offset:34816
	ds_read_b128 v[172:175], v246 offset:35840
	ds_read_b128 v[176:179], v246 offset:36864
	ds_read_b128 v[180:183], v246 offset:37888
	ds_read_b128 v[184:187], v246 offset:38912
	ds_read_b128 v[188:191], v246 offset:39936
	global_load_lds_dwordx4 v208, s[48:49]
	s_mov_b32 m0, s33
	s_nop 0
	global_load_lds_dwordx4 v212, s[48:49]
	s_waitcnt vmcnt(8)
	s_waitcnt lgkmcnt(0)
	s_setprio 1
	s_barrier
	v_mfma_f32_16x16x32_bf16 v[112:115], v[128:131], v[160:163], v[112:115]
	v_mfma_f32_16x16x32_bf16 v[116:119], v[136:139], v[160:163], v[116:119]
	v_mfma_f32_16x16x32_bf16 v[100:103], v[128:131], v[168:171], v[100:103]
	v_mfma_f32_16x16x32_bf16 v[96:99], v[136:139], v[168:171], v[96:99]
	v_mfma_f32_16x16x32_bf16 v[84:87], v[128:131], v[176:179], v[84:87]
	v_mfma_f32_16x16x32_bf16 v[80:83], v[136:139], v[176:179], v[80:83]
	v_mfma_f32_16x16x32_bf16 v[52:55], v[128:131], v[184:187], v[52:55]
	v_mfma_f32_16x16x32_bf16 v[48:51], v[136:139], v[184:187], v[48:51]
	v_mfma_f32_16x16x32_bf16 v[112:115], v[132:135], v[164:167], v[112:115]
	v_mfma_f32_16x16x32_bf16 v[116:119], v[140:143], v[164:167], v[116:119]
	v_mfma_f32_16x16x32_bf16 v[100:103], v[132:135], v[172:175], v[100:103]
	v_mfma_f32_16x16x32_bf16 v[96:99], v[140:143], v[172:175], v[96:99]
	v_mfma_f32_16x16x32_bf16 v[84:87], v[132:135], v[180:183], v[84:87]
	v_mfma_f32_16x16x32_bf16 v[80:83], v[140:143], v[180:183], v[80:83]
	v_mfma_f32_16x16x32_bf16 v[52:55], v[132:135], v[188:191], v[52:55]
	v_mfma_f32_16x16x32_bf16 v[48:51], v[140:143], v[188:191], v[48:51]
	v_mfma_f32_16x16x32_bf16 v[124:127], v[144:147], v[160:163], v[124:127]
	v_mfma_f32_16x16x32_bf16 v[120:123], v[152:155], v[160:163], v[120:123]
	v_mfma_f32_16x16x32_bf16 v[108:111], v[144:147], v[168:171], v[108:111]
	v_mfma_f32_16x16x32_bf16 v[104:107], v[152:155], v[168:171], v[104:107]
	v_mfma_f32_16x16x32_bf16 v[92:95], v[144:147], v[176:179], v[92:95]
	v_mfma_f32_16x16x32_bf16 v[88:91], v[152:155], v[176:179], v[88:91]
	v_mfma_f32_16x16x32_bf16 v[68:71], v[144:147], v[184:187], v[68:71]
	v_mfma_f32_16x16x32_bf16 v[64:67], v[152:155], v[184:187], v[64:67]
	v_mfma_f32_16x16x32_bf16 v[124:127], v[148:151], v[164:167], v[124:127]
	v_mfma_f32_16x16x32_bf16 v[120:123], v[156:159], v[164:167], v[120:123]
	v_mfma_f32_16x16x32_bf16 v[108:111], v[148:151], v[172:175], v[108:111]
	v_mfma_f32_16x16x32_bf16 v[104:107], v[156:159], v[172:175], v[104:107]
	v_mfma_f32_16x16x32_bf16 v[92:95], v[148:151], v[180:183], v[92:95]
	v_mfma_f32_16x16x32_bf16 v[88:91], v[156:159], v[180:183], v[88:91]
	v_mfma_f32_16x16x32_bf16 v[68:71], v[148:151], v[188:191], v[68:71]
	v_mfma_f32_16x16x32_bf16 v[64:67], v[156:159], v[188:191], v[64:67]
	s_barrier
	s_setprio 0
	s_add_i32 s48, s76, s97
	s_mov_b32 m0, s48
	ds_read_b128 v[160:163], v246 offset:49152
	ds_read_b128 v[164:167], v246 offset:50176
	ds_read_b128 v[168:171], v246 offset:51200
	ds_read_b128 v[172:175], v246 offset:52224
	ds_read_b128 v[176:179], v246 offset:53248
	ds_read_b128 v[180:183], v246 offset:54272
	ds_read_b128 v[184:187], v246 offset:55296
	ds_read_b128 v[188:191], v246 offset:56320
	global_load_lds_dwordx4 v210, s[98:99]
	s_add_i32 m0, s48, 0x2000
	s_add_u32 s46, s46, 0x100080
	s_addc_u32 s47, s47, 0
	s_add_i32 s48, s77, s97
	global_load_lds_dwordx4 v214, s[98:99]
	s_mov_b32 m0, s48
	s_nop 0
	global_load_lds_dwordx4 v210, s[46:47]
	s_add_i32 m0, s48, 0x2000
	s_nop 0
	global_load_lds_dwordx4 v214, s[46:47]
	s_mov_b32 m0, s54
	s_nop 0
	global_load_lds_dwordx4 v208, s[100:101]
	s_mov_b32 m0, s55
	s_nop 0
	global_load_lds_dwordx4 v212, s[100:101]
	s_waitcnt vmcnt(8)
	s_waitcnt lgkmcnt(0)
	s_setprio 1
	s_barrier
	v_mfma_f32_16x16x32_bf16 v[60:63], v[128:131], v[160:163], v[60:63]
	v_mfma_f32_16x16x32_bf16 v[56:59], v[136:139], v[160:163], v[56:59]
	v_mfma_f32_16x16x32_bf16 v[36:39], v[128:131], v[168:171], v[36:39]
	v_mfma_f32_16x16x32_bf16 v[32:35], v[136:139], v[168:171], v[32:35]
	v_mfma_f32_16x16x32_bf16 v[20:23], v[128:131], v[176:179], v[20:23]
	v_mfma_f32_16x16x32_bf16 v[16:19], v[136:139], v[176:179], v[16:19]
	v_mfma_f32_16x16x32_bf16 v[4:7], v[128:131], v[184:187], v[4:7]
	v_mfma_f32_16x16x32_bf16 v[0:3], v[136:139], v[184:187], v[0:3]
	v_mfma_f32_16x16x32_bf16 v[60:63], v[132:135], v[164:167], v[60:63]
	v_mfma_f32_16x16x32_bf16 v[56:59], v[140:143], v[164:167], v[56:59]
	v_mfma_f32_16x16x32_bf16 v[36:39], v[132:135], v[172:175], v[36:39]
	v_mfma_f32_16x16x32_bf16 v[32:35], v[140:143], v[172:175], v[32:35]
	v_mfma_f32_16x16x32_bf16 v[20:23], v[132:135], v[180:183], v[20:23]
	v_mfma_f32_16x16x32_bf16 v[16:19], v[140:143], v[180:183], v[16:19]
	v_mfma_f32_16x16x32_bf16 v[4:7], v[132:135], v[188:191], v[4:7]
	v_mfma_f32_16x16x32_bf16 v[0:3], v[140:143], v[188:191], v[0:3]
	v_mfma_f32_16x16x32_bf16 v[76:79], v[144:147], v[160:163], v[76:79]
	v_mfma_f32_16x16x32_bf16 v[72:75], v[152:155], v[160:163], v[72:75]
	v_mfma_f32_16x16x32_bf16 v[44:47], v[144:147], v[168:171], v[44:47]
	v_mfma_f32_16x16x32_bf16 v[40:43], v[152:155], v[168:171], v[40:43]
	v_mfma_f32_16x16x32_bf16 v[28:31], v[144:147], v[176:179], v[28:31]
	v_mfma_f32_16x16x32_bf16 v[24:27], v[152:155], v[176:179], v[24:27]
	v_mfma_f32_16x16x32_bf16 v[12:15], v[144:147], v[184:187], v[12:15]
	v_mfma_f32_16x16x32_bf16 v[8:11], v[152:155], v[184:187], v[8:11]
	v_mfma_f32_16x16x32_bf16 v[76:79], v[148:151], v[164:167], v[76:79]
	v_mfma_f32_16x16x32_bf16 v[72:75], v[156:159], v[164:167], v[72:75]
	v_mfma_f32_16x16x32_bf16 v[44:47], v[148:151], v[172:175], v[44:47]
	v_mfma_f32_16x16x32_bf16 v[40:43], v[156:159], v[172:175], v[40:43]
	v_mfma_f32_16x16x32_bf16 v[28:31], v[148:151], v[180:183], v[28:31]
	v_mfma_f32_16x16x32_bf16 v[24:27], v[156:159], v[180:183], v[24:27]
	v_mfma_f32_16x16x32_bf16 v[12:15], v[148:151], v[188:191], v[12:15]
	v_mfma_f32_16x16x32_bf16 v[8:11], v[156:159], v[188:191], v[8:11]
	s_barrier
	s_setprio 0
	s_add_u32 s69, s69, 0x100
	s_addc_u32 s70, s70, 0
	s_add_u32 s44, s44, 0x100
	s_addc_u32 s45, s45, 0
	s_cmp_ge_u32 s71, s67
	s_mov_b32 s46, s71
	s_cbranch_scc0 .LBB0_2020

.LBB0_2288:
	s_ashr_i32 s25, s24, 31
	s_lshl_b64 s[86:87], s[24:25], 21
	v_readlane_b32 s88, v254, 52
	v_readlane_b32 s89, v254, 53
	s_add_u32 s5, s88, s86
	s_addc_u32 s25, s89, s87
	s_add_u32 s38, s5, s38
	s_addc_u32 s39, s25, s39
	s_and_b64 s[48:49], s[48:49], exec
	s_cselect_b32 s5, s39, s45
	s_cselect_b32 s25, s38, s44
	s_add_i32 s43, s84, -2
	s_add_u32 s85, s44, 0x100
	s_addc_u32 s86, s45, 0
	s_add_u32 s44, s46, 0x100080
	s_addc_u32 s45, s47, 0
	s_mov_b32 s46, 0
	ds_read_b128 v[148:151], v159
	ds_read_b128 v[164:167], v159 offset:1024
	ds_read_b128 v[168:171], v159 offset:2048
	ds_read_b128 v[172:175], v159 offset:3072
	ds_read_b128 v[176:179], v160
	ds_read_b128 v[180:183], v160 offset:1024
	ds_read_b128 v[184:187], v160 offset:2048
	ds_read_b128 v[188:191], v160 offset:3072
	s_add_i32 s87, s46, 2
	s_add_u32 s47, s44, 0xfff00080
	s_addc_u32 s48, s45, -1
	s_cmp_eq_u32 s43, s46
	s_cselect_b32 s46, s25, s85
	s_cselect_b32 s49, s37, s48
	s_cselect_b32 s48, s36, s47
	s_cselect_b32 s47, s5, s86
	s_add_i32 m0, s94, 0xc000
	ds_read_b128 v[192:195], v161
	ds_read_b128 v[196:199], v161 offset:1024
	ds_read_b128 v[200:203], v161 offset:2048
	ds_read_b128 v[204:207], v161 offset:3072
	ds_read_b128 v[208:211], v161 offset:4096
	ds_read_b128 v[212:215], v161 offset:5120
	ds_read_b128 v[216:219], v161 offset:6144
	ds_read_b128 v[220:223], v161 offset:7168
	global_load_lds_dwordx4 v142, s[44:45]
	s_add_i32 m0, s94, 0xe000
	s_nop 0
	global_load_lds_dwordx4 v144, s[44:45]
	s_waitcnt vmcnt(8)
	s_waitcnt lgkmcnt(0)
	s_setprio 1
	s_barrier
	v_mfma_f32_16x16x32_bf16 v[112:115], v[148:151], v[192:195], 0
	v_mfma_f32_16x16x32_bf16 v[116:119], v[168:171], v[192:195], 0
	v_mfma_f32_16x16x32_bf16 v[100:103], v[148:151], v[200:203], 0
	v_mfma_f32_16x16x32_bf16 v[96:99], v[168:171], v[200:203], 0
	v_mfma_f32_16x16x32_bf16 v[84:87], v[148:151], v[208:211], 0
	v_mfma_f32_16x16x32_bf16 v[80:83], v[168:171], v[208:211], 0
	v_mfma_f32_16x16x32_bf16 v[52:55], v[148:151], v[216:219], 0
	v_mfma_f32_16x16x32_bf16 v[48:51], v[168:171], v[216:219], 0
	v_mfma_f32_16x16x32_bf16 v[112:115], v[164:167], v[196:199], v[112:115]
	v_mfma_f32_16x16x32_bf16 v[116:119], v[172:175], v[196:199], v[116:119]
	v_mfma_f32_16x16x32_bf16 v[100:103], v[164:167], v[204:207], v[100:103]
	v_mfma_f32_16x16x32_bf16 v[96:99], v[172:175], v[204:207], v[96:99]
	v_mfma_f32_16x16x32_bf16 v[84:87], v[164:167], v[212:215], v[84:87]
	v_mfma_f32_16x16x32_bf16 v[80:83], v[172:175], v[212:215], v[80:83]
	v_mfma_f32_16x16x32_bf16 v[52:55], v[164:167], v[220:223], v[52:55]
	v_mfma_f32_16x16x32_bf16 v[48:51], v[172:175], v[220:223], v[48:51]
	v_mfma_f32_16x16x32_bf16 v[124:127], v[176:179], v[192:195], 0
	v_mfma_f32_16x16x32_bf16 v[120:123], v[184:187], v[192:195], 0
	v_mfma_f32_16x16x32_bf16 v[108:111], v[176:179], v[200:203], 0
	v_mfma_f32_16x16x32_bf16 v[104:107], v[184:187], v[200:203], 0
	v_mfma_f32_16x16x32_bf16 v[92:95], v[176:179], v[208:211], 0
	v_mfma_f32_16x16x32_bf16 v[88:91], v[184:187], v[208:211], 0
	v_mfma_f32_16x16x32_bf16 v[68:71], v[176:179], v[216:219], 0
	v_mfma_f32_16x16x32_bf16 v[64:67], v[184:187], v[216:219], 0
	v_mfma_f32_16x16x32_bf16 v[124:127], v[180:183], v[196:199], v[124:127]
	v_mfma_f32_16x16x32_bf16 v[120:123], v[188:191], v[196:199], v[120:123]
	v_mfma_f32_16x16x32_bf16 v[108:111], v[180:183], v[204:207], v[108:111]
	v_mfma_f32_16x16x32_bf16 v[104:107], v[188:191], v[204:207], v[104:107]
	v_mfma_f32_16x16x32_bf16 v[92:95], v[180:183], v[212:215], v[92:95]
	v_mfma_f32_16x16x32_bf16 v[88:91], v[188:191], v[212:215], v[88:91]
	v_mfma_f32_16x16x32_bf16 v[68:71], v[180:183], v[220:223], v[68:71]
	v_mfma_f32_16x16x32_bf16 v[64:67], v[188:191], v[220:223], v[64:67]
	s_barrier
	s_setprio 0
	s_add_i32 s88, s77, s97
	s_add_u32 s98, s46, 0x80
	s_addc_u32 s99, s47, 0
	s_mov_b32 m0, s88
	ds_read_b128 v[192:195], v161 offset:16384
	ds_read_b128 v[196:199], v161 offset:17408
	ds_read_b128 v[200:203], v161 offset:18432
	ds_read_b128 v[204:207], v161 offset:19456
	ds_read_b128 v[208:211], v161 offset:20480
	ds_read_b128 v[212:215], v161 offset:21504
	ds_read_b128 v[216:219], v161 offset:22528
	ds_read_b128 v[220:223], v161 offset:23552
	global_load_lds_dwordx4 v132, s[46:47]
	s_add_i32 m0, s88, 0x2000
	s_add_u32 s88, s46, 0x100000
	s_addc_u32 s89, s47, 0
	s_add_i32 s90, s78, s97
	global_load_lds_dwordx4 v136, s[46:47]
	s_mov_b32 m0, s90
	s_add_u32 s100, s48, 0x80
	s_addc_u32 s101, s49, 0
	global_load_lds_dwordx4 v132, s[88:89]
	s_add_i32 m0, s90, 0x2000
	s_nop 0
	global_load_lds_dwordx4 v136, s[88:89]
	s_mov_b32 m0, s94
	s_nop 0
	global_load_lds_dwordx4 v130, s[48:49]
	s_mov_b32 m0, s52
	s_nop 0
	global_load_lds_dwordx4 v134, s[48:49]
	s_waitcnt vmcnt(8)
	s_waitcnt lgkmcnt(0)
	s_setprio 1
	s_barrier
	v_mfma_f32_16x16x32_bf16 v[60:63], v[148:151], v[192:195], 0
	v_mfma_f32_16x16x32_bf16 v[56:59], v[168:171], v[192:195], 0
	v_mfma_f32_16x16x32_bf16 v[36:39], v[148:151], v[200:203], 0
	v_mfma_f32_16x16x32_bf16 v[32:35], v[168:171], v[200:203], 0
	v_mfma_f32_16x16x32_bf16 v[20:23], v[148:151], v[208:211], 0
	v_mfma_f32_16x16x32_bf16 v[16:19], v[168:171], v[208:211], 0
	v_mfma_f32_16x16x32_bf16 v[4:7], v[148:151], v[216:219], 0
	v_mfma_f32_16x16x32_bf16 v[0:3], v[168:171], v[216:219], 0
	v_mfma_f32_16x16x32_bf16 v[60:63], v[164:167], v[196:199], v[60:63]
	v_mfma_f32_16x16x32_bf16 v[56:59], v[172:175], v[196:199], v[56:59]
	v_mfma_f32_16x16x32_bf16 v[36:39], v[164:167], v[204:207], v[36:39]
	v_mfma_f32_16x16x32_bf16 v[32:35], v[172:175], v[204:207], v[32:35]
	v_mfma_f32_16x16x32_bf16 v[20:23], v[164:167], v[212:215], v[20:23]
	v_mfma_f32_16x16x32_bf16 v[16:19], v[172:175], v[212:215], v[16:19]
	v_mfma_f32_16x16x32_bf16 v[4:7], v[164:167], v[220:223], v[4:7]
	v_mfma_f32_16x16x32_bf16 v[0:3], v[172:175], v[220:223], v[0:3]
	v_mfma_f32_16x16x32_bf16 v[76:79], v[176:179], v[192:195], 0
	v_mfma_f32_16x16x32_bf16 v[72:75], v[184:187], v[192:195], 0
	v_mfma_f32_16x16x32_bf16 v[44:47], v[176:179], v[200:203], 0
	v_mfma_f32_16x16x32_bf16 v[40:43], v[184:187], v[200:203], 0
	v_mfma_f32_16x16x32_bf16 v[28:31], v[176:179], v[208:211], 0
	v_mfma_f32_16x16x32_bf16 v[24:27], v[184:187], v[208:211], 0
	v_mfma_f32_16x16x32_bf16 v[12:15], v[176:179], v[216:219], 0
	v_mfma_f32_16x16x32_bf16 v[8:11], v[184:187], v[216:219], 0
	v_mfma_f32_16x16x32_bf16 v[76:79], v[180:183], v[196:199], v[76:79]
	v_mfma_f32_16x16x32_bf16 v[72:75], v[188:191], v[196:199], v[72:75]
	v_mfma_f32_16x16x32_bf16 v[44:47], v[180:183], v[204:207], v[44:47]
	v_mfma_f32_16x16x32_bf16 v[40:43], v[188:191], v[204:207], v[40:43]
	v_mfma_f32_16x16x32_bf16 v[28:31], v[180:183], v[212:215], v[28:31]
	v_mfma_f32_16x16x32_bf16 v[24:27], v[188:191], v[212:215], v[24:27]
	v_mfma_f32_16x16x32_bf16 v[12:15], v[180:183], v[220:223], v[12:15]
	v_mfma_f32_16x16x32_bf16 v[8:11], v[188:191], v[220:223], v[8:11]
	s_barrier
	s_setprio 0
	s_add_i32 s88, 0, 0x18000
	v_add_u32_e32 v163, s88, v157
	s_add_i32 s89, 0, 0x1c000
	ds_read_b128 v[148:151], v163
	ds_read_b128 v[164:167], v163 offset:1024
	ds_read_b128 v[168:171], v163 offset:2048
	ds_read_b128 v[172:175], v163 offset:3072
	v_add_u32_e32 v163, s89, v157
	ds_read_b128 v[176:179], v163
	ds_read_b128 v[180:183], v163 offset:1024
	ds_read_b128 v[184:187], v163 offset:2048
	ds_read_b128 v[188:191], v163 offset:3072
	s_add_u32 s48, s48, 0x100000
	s_addc_u32 s49, s49, 0
	s_mov_b32 m0, s53
	ds_read_b128 v[192:195], v161 offset:32768
	ds_read_b128 v[196:199], v161 offset:33792
	ds_read_b128 v[200:203], v161 offset:34816
	ds_read_b128 v[204:207], v161 offset:35840
	ds_read_b128 v[208:211], v161 offset:36864
	ds_read_b128 v[212:215], v161 offset:37888
	ds_read_b128 v[216:219], v161 offset:38912
	ds_read_b128 v[220:223], v161 offset:39936
	global_load_lds_dwordx4 v130, s[48:49]
	s_mov_b32 m0, s54
	s_nop 0
	global_load_lds_dwordx4 v134, s[48:49]
	s_waitcnt vmcnt(8)
	s_waitcnt lgkmcnt(0)
	s_setprio 1
	s_barrier
	v_mfma_f32_16x16x32_bf16 v[112:115], v[148:151], v[192:195], v[112:115]
	v_mfma_f32_16x16x32_bf16 v[116:119], v[168:171], v[192:195], v[116:119]
	v_mfma_f32_16x16x32_bf16 v[100:103], v[148:151], v[200:203], v[100:103]
	v_mfma_f32_16x16x32_bf16 v[96:99], v[168:171], v[200:203], v[96:99]
	v_mfma_f32_16x16x32_bf16 v[84:87], v[148:151], v[208:211], v[84:87]
	v_mfma_f32_16x16x32_bf16 v[80:83], v[168:171], v[208:211], v[80:83]
	v_mfma_f32_16x16x32_bf16 v[52:55], v[148:151], v[216:219], v[52:55]
	v_mfma_f32_16x16x32_bf16 v[48:51], v[168:171], v[216:219], v[48:51]
	v_mfma_f32_16x16x32_bf16 v[112:115], v[164:167], v[196:199], v[112:115]
	v_mfma_f32_16x16x32_bf16 v[116:119], v[172:175], v[196:199], v[116:119]
	v_mfma_f32_16x16x32_bf16 v[100:103], v[164:167], v[204:207], v[100:103]
	v_mfma_f32_16x16x32_bf16 v[96:99], v[172:175], v[204:207], v[96:99]
	v_mfma_f32_16x16x32_bf16 v[84:87], v[164:167], v[212:215], v[84:87]
	v_mfma_f32_16x16x32_bf16 v[80:83], v[172:175], v[212:215], v[80:83]
	v_mfma_f32_16x16x32_bf16 v[52:55], v[164:167], v[220:223], v[52:55]
	v_mfma_f32_16x16x32_bf16 v[48:51], v[172:175], v[220:223], v[48:51]
	v_mfma_f32_16x16x32_bf16 v[124:127], v[176:179], v[192:195], v[124:127]
	v_mfma_f32_16x16x32_bf16 v[120:123], v[184:187], v[192:195], v[120:123]
	v_mfma_f32_16x16x32_bf16 v[108:111], v[176:179], v[200:203], v[108:111]
	v_mfma_f32_16x16x32_bf16 v[104:107], v[184:187], v[200:203], v[104:107]
	v_mfma_f32_16x16x32_bf16 v[92:95], v[176:179], v[208:211], v[92:95]
	v_mfma_f32_16x16x32_bf16 v[88:91], v[184:187], v[208:211], v[88:91]
	v_mfma_f32_16x16x32_bf16 v[68:71], v[176:179], v[216:219], v[68:71]
	v_mfma_f32_16x16x32_bf16 v[64:67], v[184:187], v[216:219], v[64:67]
	v_mfma_f32_16x16x32_bf16 v[124:127], v[180:183], v[196:199], v[124:127]
	v_mfma_f32_16x16x32_bf16 v[120:123], v[188:191], v[196:199], v[120:123]
	v_mfma_f32_16x16x32_bf16 v[108:111], v[180:183], v[204:207], v[108:111]
	v_mfma_f32_16x16x32_bf16 v[104:107], v[188:191], v[204:207], v[104:107]
	v_mfma_f32_16x16x32_bf16 v[92:95], v[180:183], v[212:215], v[92:95]
	v_mfma_f32_16x16x32_bf16 v[88:91], v[188:191], v[212:215], v[88:91]
	v_mfma_f32_16x16x32_bf16 v[68:71], v[180:183], v[220:223], v[68:71]
	v_mfma_f32_16x16x32_bf16 v[64:67], v[188:191], v[220:223], v[64:67]
	s_barrier
	s_setprio 0
	s_add_i32 s48, s88, s97
	s_mov_b32 m0, s48
	ds_read_b128 v[192:195], v161 offset:49152
	ds_read_b128 v[196:199], v161 offset:50176
	ds_read_b128 v[200:203], v161 offset:51200
	ds_read_b128 v[204:207], v161 offset:52224
	ds_read_b128 v[208:211], v161 offset:53248
	ds_read_b128 v[212:215], v161 offset:54272
	ds_read_b128 v[216:219], v161 offset:55296
	ds_read_b128 v[220:223], v161 offset:56320
	global_load_lds_dwordx4 v132, s[98:99]
	s_add_i32 m0, s48, 0x2000
	s_add_u32 s46, s46, 0x100080
	s_addc_u32 s47, s47, 0
	s_add_i32 s48, s89, s97
	global_load_lds_dwordx4 v136, s[98:99]
	s_mov_b32 m0, s48
	s_nop 0
	global_load_lds_dwordx4 v132, s[46:47]
	s_add_i32 m0, s48, 0x2000
	s_nop 0
	global_load_lds_dwordx4 v136, s[46:47]
	s_mov_b32 m0, s68
	s_nop 0
	global_load_lds_dwordx4 v130, s[100:101]
	s_mov_b32 m0, s69
	s_nop 0
	global_load_lds_dwordx4 v134, s[100:101]
	s_waitcnt vmcnt(8)
	s_waitcnt lgkmcnt(0)
	s_setprio 1
	s_barrier
	v_mfma_f32_16x16x32_bf16 v[60:63], v[148:151], v[192:195], v[60:63]
	v_mfma_f32_16x16x32_bf16 v[56:59], v[168:171], v[192:195], v[56:59]
	v_mfma_f32_16x16x32_bf16 v[36:39], v[148:151], v[200:203], v[36:39]
	v_mfma_f32_16x16x32_bf16 v[32:35], v[168:171], v[200:203], v[32:35]
	v_mfma_f32_16x16x32_bf16 v[20:23], v[148:151], v[208:211], v[20:23]
	v_mfma_f32_16x16x32_bf16 v[16:19], v[168:171], v[208:211], v[16:19]
	v_mfma_f32_16x16x32_bf16 v[4:7], v[148:151], v[216:219], v[4:7]
	v_mfma_f32_16x16x32_bf16 v[0:3], v[168:171], v[216:219], v[0:3]
	v_mfma_f32_16x16x32_bf16 v[60:63], v[164:167], v[196:199], v[60:63]
	v_mfma_f32_16x16x32_bf16 v[56:59], v[172:175], v[196:199], v[56:59]
	v_mfma_f32_16x16x32_bf16 v[36:39], v[164:167], v[204:207], v[36:39]
	v_mfma_f32_16x16x32_bf16 v[32:35], v[172:175], v[204:207], v[32:35]
	v_mfma_f32_16x16x32_bf16 v[20:23], v[164:167], v[212:215], v[20:23]
	v_mfma_f32_16x16x32_bf16 v[16:19], v[172:175], v[212:215], v[16:19]
	v_mfma_f32_16x16x32_bf16 v[4:7], v[164:167], v[220:223], v[4:7]
	v_mfma_f32_16x16x32_bf16 v[0:3], v[172:175], v[220:223], v[0:3]
	v_mfma_f32_16x16x32_bf16 v[76:79], v[176:179], v[192:195], v[76:79]
	v_mfma_f32_16x16x32_bf16 v[72:75], v[184:187], v[192:195], v[72:75]
	v_mfma_f32_16x16x32_bf16 v[44:47], v[176:179], v[200:203], v[44:47]
	v_mfma_f32_16x16x32_bf16 v[40:43], v[184:187], v[200:203], v[40:43]
	v_mfma_f32_16x16x32_bf16 v[28:31], v[176:179], v[208:211], v[28:31]
	v_mfma_f32_16x16x32_bf16 v[24:27], v[184:187], v[208:211], v[24:27]
	v_mfma_f32_16x16x32_bf16 v[12:15], v[176:179], v[216:219], v[12:15]
	v_mfma_f32_16x16x32_bf16 v[8:11], v[184:187], v[216:219], v[8:11]
	v_mfma_f32_16x16x32_bf16 v[76:79], v[180:183], v[196:199], v[76:79]
	v_mfma_f32_16x16x32_bf16 v[72:75], v[188:191], v[196:199], v[72:75]
	v_mfma_f32_16x16x32_bf16 v[44:47], v[180:183], v[204:207], v[44:47]
	v_mfma_f32_16x16x32_bf16 v[40:43], v[188:191], v[204:207], v[40:43]
	v_mfma_f32_16x16x32_bf16 v[28:31], v[180:183], v[212:215], v[28:31]
	v_mfma_f32_16x16x32_bf16 v[24:27], v[188:191], v[212:215], v[24:27]
	v_mfma_f32_16x16x32_bf16 v[12:15], v[180:183], v[220:223], v[12:15]
	v_mfma_f32_16x16x32_bf16 v[8:11], v[188:191], v[220:223], v[8:11]
	s_barrier
	s_setprio 0
	s_add_u32 s85, s85, 0x100
	s_addc_u32 s86, s86, 0
	s_add_u32 s44, s44, 0x100
	s_addc_u32 s45, s45, 0
	s_cmp_ge_u32 s87, s84
	s_mov_b32 s46, s87
	s_cbranch_scc1 .Lpeel_done_3
.LBB0_2289:
	ds_read_b128 v[148:151], v159
	ds_read_b128 v[164:167], v159 offset:1024
	ds_read_b128 v[168:171], v159 offset:2048
	ds_read_b128 v[172:175], v159 offset:3072
	ds_read_b128 v[176:179], v160
	ds_read_b128 v[180:183], v160 offset:1024
	ds_read_b128 v[184:187], v160 offset:2048
	ds_read_b128 v[188:191], v160 offset:3072
	s_add_i32 s87, s46, 2
	s_add_u32 s47, s44, 0xfff00080
	s_addc_u32 s48, s45, -1
	s_cmp_eq_u32 s43, s46
	s_cselect_b32 s46, s25, s85
	s_cselect_b32 s49, s37, s48
	s_cselect_b32 s48, s36, s47
	s_cselect_b32 s47, s5, s86
	s_add_i32 m0, s94, 0xc000
	ds_read_b128 v[192:195], v161
	ds_read_b128 v[196:199], v161 offset:1024
	ds_read_b128 v[200:203], v161 offset:2048
	ds_read_b128 v[204:207], v161 offset:3072
	ds_read_b128 v[208:211], v161 offset:4096
	ds_read_b128 v[212:215], v161 offset:5120
	ds_read_b128 v[216:219], v161 offset:6144
	ds_read_b128 v[220:223], v161 offset:7168
	global_load_lds_dwordx4 v142, s[44:45]
	s_add_i32 m0, s94, 0xe000
	s_nop 0
	global_load_lds_dwordx4 v144, s[44:45]
	s_waitcnt vmcnt(8)
	s_waitcnt lgkmcnt(0)
	s_setprio 1
	s_barrier
	v_mfma_f32_16x16x32_bf16 v[112:115], v[148:151], v[192:195], v[112:115]
	v_mfma_f32_16x16x32_bf16 v[116:119], v[168:171], v[192:195], v[116:119]
	v_mfma_f32_16x16x32_bf16 v[100:103], v[148:151], v[200:203], v[100:103]
	v_mfma_f32_16x16x32_bf16 v[96:99], v[168:171], v[200:203], v[96:99]
	v_mfma_f32_16x16x32_bf16 v[84:87], v[148:151], v[208:211], v[84:87]
	v_mfma_f32_16x16x32_bf16 v[80:83], v[168:171], v[208:211], v[80:83]
	v_mfma_f32_16x16x32_bf16 v[52:55], v[148:151], v[216:219], v[52:55]
	v_mfma_f32_16x16x32_bf16 v[48:51], v[168:171], v[216:219], v[48:51]
	v_mfma_f32_16x16x32_bf16 v[112:115], v[164:167], v[196:199], v[112:115]
	v_mfma_f32_16x16x32_bf16 v[116:119], v[172:175], v[196:199], v[116:119]
	v_mfma_f32_16x16x32_bf16 v[100:103], v[164:167], v[204:207], v[100:103]
	v_mfma_f32_16x16x32_bf16 v[96:99], v[172:175], v[204:207], v[96:99]
	v_mfma_f32_16x16x32_bf16 v[84:87], v[164:167], v[212:215], v[84:87]
	v_mfma_f32_16x16x32_bf16 v[80:83], v[172:175], v[212:215], v[80:83]
	v_mfma_f32_16x16x32_bf16 v[52:55], v[164:167], v[220:223], v[52:55]
	v_mfma_f32_16x16x32_bf16 v[48:51], v[172:175], v[220:223], v[48:51]
	v_mfma_f32_16x16x32_bf16 v[124:127], v[176:179], v[192:195], v[124:127]
	v_mfma_f32_16x16x32_bf16 v[120:123], v[184:187], v[192:195], v[120:123]
	v_mfma_f32_16x16x32_bf16 v[108:111], v[176:179], v[200:203], v[108:111]
	v_mfma_f32_16x16x32_bf16 v[104:107], v[184:187], v[200:203], v[104:107]
	v_mfma_f32_16x16x32_bf16 v[92:95], v[176:179], v[208:211], v[92:95]
	v_mfma_f32_16x16x32_bf16 v[88:91], v[184:187], v[208:211], v[88:91]
	v_mfma_f32_16x16x32_bf16 v[68:71], v[176:179], v[216:219], v[68:71]
	v_mfma_f32_16x16x32_bf16 v[64:67], v[184:187], v[216:219], v[64:67]
	v_mfma_f32_16x16x32_bf16 v[124:127], v[180:183], v[196:199], v[124:127]
	v_mfma_f32_16x16x32_bf16 v[120:123], v[188:191], v[196:199], v[120:123]
	v_mfma_f32_16x16x32_bf16 v[108:111], v[180:183], v[204:207], v[108:111]
	v_mfma_f32_16x16x32_bf16 v[104:107], v[188:191], v[204:207], v[104:107]
	v_mfma_f32_16x16x32_bf16 v[92:95], v[180:183], v[212:215], v[92:95]
	v_mfma_f32_16x16x32_bf16 v[88:91], v[188:191], v[212:215], v[88:91]
	v_mfma_f32_16x16x32_bf16 v[68:71], v[180:183], v[220:223], v[68:71]
	v_mfma_f32_16x16x32_bf16 v[64:67], v[188:191], v[220:223], v[64:67]
	s_barrier
	s_setprio 0
	s_add_i32 s88, s77, s97
	s_add_u32 s98, s46, 0x80
	s_addc_u32 s99, s47, 0
	s_mov_b32 m0, s88
	ds_read_b128 v[192:195], v161 offset:16384
	ds_read_b128 v[196:199], v161 offset:17408
	ds_read_b128 v[200:203], v161 offset:18432
	ds_read_b128 v[204:207], v161 offset:19456
	ds_read_b128 v[208:211], v161 offset:20480
	ds_read_b128 v[212:215], v161 offset:21504
	ds_read_b128 v[216:219], v161 offset:22528
	ds_read_b128 v[220:223], v161 offset:23552
	global_load_lds_dwordx4 v132, s[46:47]
	s_add_i32 m0, s88, 0x2000
	s_add_u32 s88, s46, 0x100000
	s_addc_u32 s89, s47, 0
	s_add_i32 s90, s78, s97
	global_load_lds_dwordx4 v136, s[46:47]
	s_mov_b32 m0, s90
	s_add_u32 s100, s48, 0x80
	s_addc_u32 s101, s49, 0
	global_load_lds_dwordx4 v132, s[88:89]
	s_add_i32 m0, s90, 0x2000
	s_nop 0
	global_load_lds_dwordx4 v136, s[88:89]
	s_mov_b32 m0, s94
	s_nop 0
	global_load_lds_dwordx4 v130, s[48:49]
	s_mov_b32 m0, s52
	s_nop 0
	global_load_lds_dwordx4 v134, s[48:49]
	s_waitcnt vmcnt(8)
	s_waitcnt lgkmcnt(0)
	s_setprio 1
	s_barrier
	v_mfma_f32_16x16x32_bf16 v[60:63], v[148:151], v[192:195], v[60:63]
	v_mfma_f32_16x16x32_bf16 v[56:59], v[168:171], v[192:195], v[56:59]
	v_mfma_f32_16x16x32_bf16 v[36:39], v[148:151], v[200:203], v[36:39]
	v_mfma_f32_16x16x32_bf16 v[32:35], v[168:171], v[200:203], v[32:35]
	v_mfma_f32_16x16x32_bf16 v[20:23], v[148:151], v[208:211], v[20:23]
	v_mfma_f32_16x16x32_bf16 v[16:19], v[168:171], v[208:211], v[16:19]
	v_mfma_f32_16x16x32_bf16 v[4:7], v[148:151], v[216:219], v[4:7]
	v_mfma_f32_16x16x32_bf16 v[0:3], v[168:171], v[216:219], v[0:3]
	v_mfma_f32_16x16x32_bf16 v[60:63], v[164:167], v[196:199], v[60:63]
	v_mfma_f32_16x16x32_bf16 v[56:59], v[172:175], v[196:199], v[56:59]
	v_mfma_f32_16x16x32_bf16 v[36:39], v[164:167], v[204:207], v[36:39]
	v_mfma_f32_16x16x32_bf16 v[32:35], v[172:175], v[204:207], v[32:35]
	v_mfma_f32_16x16x32_bf16 v[20:23], v[164:167], v[212:215], v[20:23]
	v_mfma_f32_16x16x32_bf16 v[16:19], v[172:175], v[212:215], v[16:19]
	v_mfma_f32_16x16x32_bf16 v[4:7], v[164:167], v[220:223], v[4:7]
	v_mfma_f32_16x16x32_bf16 v[0:3], v[172:175], v[220:223], v[0:3]
	v_mfma_f32_16x16x32_bf16 v[76:79], v[176:179], v[192:195], v[76:79]
	v_mfma_f32_16x16x32_bf16 v[72:75], v[184:187], v[192:195], v[72:75]
	v_mfma_f32_16x16x32_bf16 v[44:47], v[176:179], v[200:203], v[44:47]
	v_mfma_f32_16x16x32_bf16 v[40:43], v[184:187], v[200:203], v[40:43]
	v_mfma_f32_16x16x32_bf16 v[28:31], v[176:179], v[208:211], v[28:31]
	v_mfma_f32_16x16x32_bf16 v[24:27], v[184:187], v[208:211], v[24:27]
	v_mfma_f32_16x16x32_bf16 v[12:15], v[176:179], v[216:219], v[12:15]
	v_mfma_f32_16x16x32_bf16 v[8:11], v[184:187], v[216:219], v[8:11]
	v_mfma_f32_16x16x32_bf16 v[76:79], v[180:183], v[196:199], v[76:79]
	v_mfma_f32_16x16x32_bf16 v[72:75], v[188:191], v[196:199], v[72:75]
	v_mfma_f32_16x16x32_bf16 v[44:47], v[180:183], v[204:207], v[44:47]
	v_mfma_f32_16x16x32_bf16 v[40:43], v[188:191], v[204:207], v[40:43]
	v_mfma_f32_16x16x32_bf16 v[28:31], v[180:183], v[212:215], v[28:31]
	v_mfma_f32_16x16x32_bf16 v[24:27], v[188:191], v[212:215], v[24:27]
	v_mfma_f32_16x16x32_bf16 v[12:15], v[180:183], v[220:223], v[12:15]
	v_mfma_f32_16x16x32_bf16 v[8:11], v[188:191], v[220:223], v[8:11]
	s_barrier
	s_setprio 0
	s_add_i32 s88, 0, 0x18000
	v_add_u32_e32 v163, s88, v157
	s_add_i32 s89, 0, 0x1c000
	ds_read_b128 v[148:151], v163
	ds_read_b128 v[164:167], v163 offset:1024
	ds_read_b128 v[168:171], v163 offset:2048
	ds_read_b128 v[172:175], v163 offset:3072
	v_add_u32_e32 v163, s89, v157
	ds_read_b128 v[176:179], v163
	ds_read_b128 v[180:183], v163 offset:1024
	ds_read_b128 v[184:187], v163 offset:2048
	ds_read_b128 v[188:191], v163 offset:3072
	s_add_u32 s48, s48, 0x100000
	s_addc_u32 s49, s49, 0
	s_mov_b32 m0, s53
	ds_read_b128 v[192:195], v161 offset:32768
	ds_read_b128 v[196:199], v161 offset:33792
	ds_read_b128 v[200:203], v161 offset:34816
	ds_read_b128 v[204:207], v161 offset:35840
	ds_read_b128 v[208:211], v161 offset:36864
	ds_read_b128 v[212:215], v161 offset:37888
	ds_read_b128 v[216:219], v161 offset:38912
	ds_read_b128 v[220:223], v161 offset:39936
	global_load_lds_dwordx4 v130, s[48:49]
	s_mov_b32 m0, s54
	s_nop 0
	global_load_lds_dwordx4 v134, s[48:49]
	s_waitcnt vmcnt(8)
	s_waitcnt lgkmcnt(0)
	s_setprio 1
	s_barrier
	v_mfma_f32_16x16x32_bf16 v[112:115], v[148:151], v[192:195], v[112:115]
	v_mfma_f32_16x16x32_bf16 v[116:119], v[168:171], v[192:195], v[116:119]
	v_mfma_f32_16x16x32_bf16 v[100:103], v[148:151], v[200:203], v[100:103]
	v_mfma_f32_16x16x32_bf16 v[96:99], v[168:171], v[200:203], v[96:99]
	v_mfma_f32_16x16x32_bf16 v[84:87], v[148:151], v[208:211], v[84:87]
	v_mfma_f32_16x16x32_bf16 v[80:83], v[168:171], v[208:211], v[80:83]
	v_mfma_f32_16x16x32_bf16 v[52:55], v[148:151], v[216:219], v[52:55]
	v_mfma_f32_16x16x32_bf16 v[48:51], v[168:171], v[216:219], v[48:51]
	v_mfma_f32_16x16x32_bf16 v[112:115], v[164:167], v[196:199], v[112:115]
	v_mfma_f32_16x16x32_bf16 v[116:119], v[172:175], v[196:199], v[116:119]
	v_mfma_f32_16x16x32_bf16 v[100:103], v[164:167], v[204:207], v[100:103]
	v_mfma_f32_16x16x32_bf16 v[96:99], v[172:175], v[204:207], v[96:99]
	v_mfma_f32_16x16x32_bf16 v[84:87], v[164:167], v[212:215], v[84:87]
	v_mfma_f32_16x16x32_bf16 v[80:83], v[172:175], v[212:215], v[80:83]
	v_mfma_f32_16x16x32_bf16 v[52:55], v[164:167], v[220:223], v[52:55]
	v_mfma_f32_16x16x32_bf16 v[48:51], v[172:175], v[220:223], v[48:51]
	v_mfma_f32_16x16x32_bf16 v[124:127], v[176:179], v[192:195], v[124:127]
	v_mfma_f32_16x16x32_bf16 v[120:123], v[184:187], v[192:195], v[120:123]
	v_mfma_f32_16x16x32_bf16 v[108:111], v[176:179], v[200:203], v[108:111]
	v_mfma_f32_16x16x32_bf16 v[104:107], v[184:187], v[200:203], v[104:107]
	v_mfma_f32_16x16x32_bf16 v[92:95], v[176:179], v[208:211], v[92:95]
	v_mfma_f32_16x16x32_bf16 v[88:91], v[184:187], v[208:211], v[88:91]
	v_mfma_f32_16x16x32_bf16 v[68:71], v[176:179], v[216:219], v[68:71]
	v_mfma_f32_16x16x32_bf16 v[64:67], v[184:187], v[216:219], v[64:67]
	v_mfma_f32_16x16x32_bf16 v[124:127], v[180:183], v[196:199], v[124:127]
	v_mfma_f32_16x16x32_bf16 v[120:123], v[188:191], v[196:199], v[120:123]
	v_mfma_f32_16x16x32_bf16 v[108:111], v[180:183], v[204:207], v[108:111]
	v_mfma_f32_16x16x32_bf16 v[104:107], v[188:191], v[204:207], v[104:107]
	v_mfma_f32_16x16x32_bf16 v[92:95], v[180:183], v[212:215], v[92:95]
	v_mfma_f32_16x16x32_bf16 v[88:91], v[188:191], v[212:215], v[88:91]
	v_mfma_f32_16x16x32_bf16 v[68:71], v[180:183], v[220:223], v[68:71]
	v_mfma_f32_16x16x32_bf16 v[64:67], v[188:191], v[220:223], v[64:67]
	s_barrier
	s_setprio 0
	s_add_i32 s48, s88, s97
	s_mov_b32 m0, s48
	ds_read_b128 v[192:195], v161 offset:49152
	ds_read_b128 v[196:199], v161 offset:50176
	ds_read_b128 v[200:203], v161 offset:51200
	ds_read_b128 v[204:207], v161 offset:52224
	ds_read_b128 v[208:211], v161 offset:53248
	ds_read_b128 v[212:215], v161 offset:54272
	ds_read_b128 v[216:219], v161 offset:55296
	ds_read_b128 v[220:223], v161 offset:56320
	global_load_lds_dwordx4 v132, s[98:99]
	s_add_i32 m0, s48, 0x2000
	s_add_u32 s46, s46, 0x100080
	s_addc_u32 s47, s47, 0
	s_add_i32 s48, s89, s97
	global_load_lds_dwordx4 v136, s[98:99]
	s_mov_b32 m0, s48
	s_nop 0
	global_load_lds_dwordx4 v132, s[46:47]
	s_add_i32 m0, s48, 0x2000
	s_nop 0
	global_load_lds_dwordx4 v136, s[46:47]
	s_mov_b32 m0, s68
	s_nop 0
	global_load_lds_dwordx4 v130, s[100:101]
	s_mov_b32 m0, s69
	s_nop 0
	global_load_lds_dwordx4 v134, s[100:101]
	s_waitcnt vmcnt(8)
	s_waitcnt lgkmcnt(0)
	s_setprio 1
	s_barrier
	v_mfma_f32_16x16x32_bf16 v[60:63], v[148:151], v[192:195], v[60:63]
	v_mfma_f32_16x16x32_bf16 v[56:59], v[168:171], v[192:195], v[56:59]
	v_mfma_f32_16x16x32_bf16 v[36:39], v[148:151], v[200:203], v[36:39]
	v_mfma_f32_16x16x32_bf16 v[32:35], v[168:171], v[200:203], v[32:35]
	v_mfma_f32_16x16x32_bf16 v[20:23], v[148:151], v[208:211], v[20:23]
	v_mfma_f32_16x16x32_bf16 v[16:19], v[168:171], v[208:211], v[16:19]
	v_mfma_f32_16x16x32_bf16 v[4:7], v[148:151], v[216:219], v[4:7]
	v_mfma_f32_16x16x32_bf16 v[0:3], v[168:171], v[216:219], v[0:3]
	v_mfma_f32_16x16x32_bf16 v[60:63], v[164:167], v[196:199], v[60:63]
	v_mfma_f32_16x16x32_bf16 v[56:59], v[172:175], v[196:199], v[56:59]
	v_mfma_f32_16x16x32_bf16 v[36:39], v[164:167], v[204:207], v[36:39]
	v_mfma_f32_16x16x32_bf16 v[32:35], v[172:175], v[204:207], v[32:35]
	v_mfma_f32_16x16x32_bf16 v[20:23], v[164:167], v[212:215], v[20:23]
	v_mfma_f32_16x16x32_bf16 v[16:19], v[172:175], v[212:215], v[16:19]
	v_mfma_f32_16x16x32_bf16 v[4:7], v[164:167], v[220:223], v[4:7]
	v_mfma_f32_16x16x32_bf16 v[0:3], v[172:175], v[220:223], v[0:3]
	v_mfma_f32_16x16x32_bf16 v[76:79], v[176:179], v[192:195], v[76:79]
	v_mfma_f32_16x16x32_bf16 v[72:75], v[184:187], v[192:195], v[72:75]
	v_mfma_f32_16x16x32_bf16 v[44:47], v[176:179], v[200:203], v[44:47]
	v_mfma_f32_16x16x32_bf16 v[40:43], v[184:187], v[200:203], v[40:43]
	v_mfma_f32_16x16x32_bf16 v[28:31], v[176:179], v[208:211], v[28:31]
	v_mfma_f32_16x16x32_bf16 v[24:27], v[184:187], v[208:211], v[24:27]
	v_mfma_f32_16x16x32_bf16 v[12:15], v[176:179], v[216:219], v[12:15]
	v_mfma_f32_16x16x32_bf16 v[8:11], v[184:187], v[216:219], v[8:11]
	v_mfma_f32_16x16x32_bf16 v[76:79], v[180:183], v[196:199], v[76:79]
	v_mfma_f32_16x16x32_bf16 v[72:75], v[188:191], v[196:199], v[72:75]
	v_mfma_f32_16x16x32_bf16 v[44:47], v[180:183], v[204:207], v[44:47]
	v_mfma_f32_16x16x32_bf16 v[40:43], v[188:191], v[204:207], v[40:43]
	v_mfma_f32_16x16x32_bf16 v[28:31], v[180:183], v[212:215], v[28:31]
	v_mfma_f32_16x16x32_bf16 v[24:27], v[188:191], v[212:215], v[24:27]
	v_mfma_f32_16x16x32_bf16 v[12:15], v[180:183], v[220:223], v[12:15]
	v_mfma_f32_16x16x32_bf16 v[8:11], v[188:191], v[220:223], v[8:11]
	s_barrier
	s_setprio 0
	s_add_u32 s85, s85, 0x100
	s_addc_u32 s86, s86, 0
	s_add_u32 s44, s44, 0x100
	s_addc_u32 s45, s45, 0
	s_cmp_ge_u32 s87, s84
	s_mov_b32 s46, s87
	s_cbranch_scc0 .LBB0_2289

.LBB0_2452:
	s_cmp_lt_u32 s35, 0x3fffffff
	s_cselect_b64 s[38:39], -1, 0
	s_ashr_i32 s35, s34, 31
	s_and_b64 s[38:39], s[4:5], s[38:39]
	s_lshl_b64 s[4:5], s[34:35], 23
	s_add_u32 s4, s2, s4
	s_addc_u32 s5, s3, s5
	s_add_u32 s4, s4, s36
	s_addc_u32 s5, s5, s37
	s_and_b64 s[48:49], s[38:39], exec
	s_cselect_b32 s35, s5, s47
	s_cselect_b32 s41, s4, s46
	s_ashr_i32 s31, s30, 31
	s_lshl_b64 s[48:49], s[30:31], 23
	v_readlane_b32 s78, v254, 54
	v_readlane_b32 s79, v254, 55
	s_add_u32 s31, s78, s48
	s_addc_u32 s43, s79, s49
	s_add_u32 s36, s31, s36
	s_addc_u32 s37, s43, s37
	s_and_b64 s[48:49], s[38:39], exec
	s_cselect_b32 s31, s37, s45
	s_cselect_b32 s43, s36, s44
	s_add_i32 s75, s76, -2
	s_add_u32 s77, s44, 0x100
	s_addc_u32 s78, s45, 0
	s_add_u32 s44, s46, 0x400080
	s_addc_u32 s45, s47, 0
	s_mov_b32 s46, 0
	ds_read_b128 v[128:131], v228
	ds_read_b128 v[132:135], v228 offset:1024
	ds_read_b128 v[136:139], v228 offset:2048
	ds_read_b128 v[140:143], v228 offset:3072
	ds_read_b128 v[144:147], v229
	ds_read_b128 v[148:151], v229 offset:1024
	ds_read_b128 v[152:155], v229 offset:2048
	ds_read_b128 v[156:159], v229 offset:3072
	s_add_i32 s79, s46, 2
	s_add_u32 s47, s44, 0xffc00080
	s_addc_u32 s48, s45, -1
	s_cmp_eq_u32 s75, s46
	s_cselect_b32 s46, s43, s77
	s_cselect_b32 s49, s35, s48
	s_cselect_b32 s48, s41, s47
	s_cselect_b32 s47, s31, s78
	s_add_i32 m0, s94, 0xc000
	ds_read_b128 v[160:163], v230
	ds_read_b128 v[164:167], v230 offset:1024
	ds_read_b128 v[168:171], v230 offset:2048
	ds_read_b128 v[172:175], v230 offset:3072
	ds_read_b128 v[176:179], v230 offset:4096
	ds_read_b128 v[180:183], v230 offset:5120
	ds_read_b128 v[184:187], v230 offset:6144
	ds_read_b128 v[188:191], v230 offset:7168
	global_load_lds_dwordx4 v202, s[44:45]
	s_add_i32 m0, s94, 0xe000
	s_nop 0
	global_load_lds_dwordx4 v204, s[44:45]
	s_waitcnt vmcnt(8)
	s_waitcnt lgkmcnt(0)
	s_setprio 1
	s_barrier
	v_mfma_f32_16x16x32_bf16 v[112:115], v[128:131], v[160:163], 0
	v_mfma_f32_16x16x32_bf16 v[116:119], v[136:139], v[160:163], 0
	v_mfma_f32_16x16x32_bf16 v[100:103], v[128:131], v[168:171], 0
	v_mfma_f32_16x16x32_bf16 v[96:99], v[136:139], v[168:171], 0
	v_mfma_f32_16x16x32_bf16 v[84:87], v[128:131], v[176:179], 0
	v_mfma_f32_16x16x32_bf16 v[80:83], v[136:139], v[176:179], 0
	v_mfma_f32_16x16x32_bf16 v[52:55], v[128:131], v[184:187], 0
	v_mfma_f32_16x16x32_bf16 v[48:51], v[136:139], v[184:187], 0
	v_mfma_f32_16x16x32_bf16 v[112:115], v[132:135], v[164:167], v[112:115]
	v_mfma_f32_16x16x32_bf16 v[116:119], v[140:143], v[164:167], v[116:119]
	v_mfma_f32_16x16x32_bf16 v[100:103], v[132:135], v[172:175], v[100:103]
	v_mfma_f32_16x16x32_bf16 v[96:99], v[140:143], v[172:175], v[96:99]
	v_mfma_f32_16x16x32_bf16 v[84:87], v[132:135], v[180:183], v[84:87]
	v_mfma_f32_16x16x32_bf16 v[80:83], v[140:143], v[180:183], v[80:83]
	v_mfma_f32_16x16x32_bf16 v[52:55], v[132:135], v[188:191], v[52:55]
	v_mfma_f32_16x16x32_bf16 v[48:51], v[140:143], v[188:191], v[48:51]
	v_mfma_f32_16x16x32_bf16 v[124:127], v[144:147], v[160:163], 0
	v_mfma_f32_16x16x32_bf16 v[120:123], v[152:155], v[160:163], 0
	v_mfma_f32_16x16x32_bf16 v[108:111], v[144:147], v[168:171], 0
	v_mfma_f32_16x16x32_bf16 v[104:107], v[152:155], v[168:171], 0
	v_mfma_f32_16x16x32_bf16 v[92:95], v[144:147], v[176:179], 0
	v_mfma_f32_16x16x32_bf16 v[88:91], v[152:155], v[176:179], 0
	v_mfma_f32_16x16x32_bf16 v[68:71], v[144:147], v[184:187], 0
	v_mfma_f32_16x16x32_bf16 v[64:67], v[152:155], v[184:187], 0
	v_mfma_f32_16x16x32_bf16 v[124:127], v[148:151], v[164:167], v[124:127]
	v_mfma_f32_16x16x32_bf16 v[120:123], v[156:159], v[164:167], v[120:123]
	v_mfma_f32_16x16x32_bf16 v[108:111], v[148:151], v[172:175], v[108:111]
	v_mfma_f32_16x16x32_bf16 v[104:107], v[156:159], v[172:175], v[104:107]
	v_mfma_f32_16x16x32_bf16 v[92:95], v[148:151], v[180:183], v[92:95]
	v_mfma_f32_16x16x32_bf16 v[88:91], v[156:159], v[180:183], v[88:91]
	v_mfma_f32_16x16x32_bf16 v[68:71], v[148:151], v[188:191], v[68:71]
	v_mfma_f32_16x16x32_bf16 v[64:67], v[156:159], v[188:191], v[64:67]
	s_barrier
	s_setprio 0
	s_add_i32 s80, s68, s97
	s_add_u32 s98, s46, 0x80
	s_addc_u32 s99, s47, 0
	s_mov_b32 m0, s80
	ds_read_b128 v[160:163], v230 offset:16384
	ds_read_b128 v[164:167], v230 offset:17408
	ds_read_b128 v[168:171], v230 offset:18432
	ds_read_b128 v[172:175], v230 offset:19456
	ds_read_b128 v[176:179], v230 offset:20480
	ds_read_b128 v[180:183], v230 offset:21504
	ds_read_b128 v[184:187], v230 offset:22528
	ds_read_b128 v[188:191], v230 offset:23552
	global_load_lds_dwordx4 v194, s[46:47]
	s_add_i32 m0, s80, 0x2000
	s_add_u32 s80, s46, 0x400000
	s_addc_u32 s81, s47, 0
	s_add_i32 s84, s69, s97
	global_load_lds_dwordx4 v198, s[46:47]
	s_mov_b32 m0, s84
	s_add_u32 s100, s48, 0x80
	s_addc_u32 s101, s49, 0
	global_load_lds_dwordx4 v194, s[80:81]
	s_add_i32 m0, s84, 0x2000
	s_nop 0
	global_load_lds_dwordx4 v198, s[80:81]
	s_mov_b32 m0, s94
	s_nop 0
	global_load_lds_dwordx4 v192, s[48:49]
	s_mov_b32 m0, s51
	s_nop 0
	global_load_lds_dwordx4 v196, s[48:49]
	s_waitcnt vmcnt(8)
	s_waitcnt lgkmcnt(0)
	s_setprio 1
	s_barrier
	v_mfma_f32_16x16x32_bf16 v[60:63], v[128:131], v[160:163], 0
	v_mfma_f32_16x16x32_bf16 v[56:59], v[136:139], v[160:163], 0
	v_mfma_f32_16x16x32_bf16 v[36:39], v[128:131], v[168:171], 0
	v_mfma_f32_16x16x32_bf16 v[32:35], v[136:139], v[168:171], 0
	v_mfma_f32_16x16x32_bf16 v[20:23], v[128:131], v[176:179], 0
	v_mfma_f32_16x16x32_bf16 v[16:19], v[136:139], v[176:179], 0
	v_mfma_f32_16x16x32_bf16 v[4:7], v[128:131], v[184:187], 0
	v_mfma_f32_16x16x32_bf16 v[0:3], v[136:139], v[184:187], 0
	v_mfma_f32_16x16x32_bf16 v[60:63], v[132:135], v[164:167], v[60:63]
	v_mfma_f32_16x16x32_bf16 v[56:59], v[140:143], v[164:167], v[56:59]
	v_mfma_f32_16x16x32_bf16 v[36:39], v[132:135], v[172:175], v[36:39]
	v_mfma_f32_16x16x32_bf16 v[32:35], v[140:143], v[172:175], v[32:35]
	v_mfma_f32_16x16x32_bf16 v[20:23], v[132:135], v[180:183], v[20:23]
	v_mfma_f32_16x16x32_bf16 v[16:19], v[140:143], v[180:183], v[16:19]
	v_mfma_f32_16x16x32_bf16 v[4:7], v[132:135], v[188:191], v[4:7]
	v_mfma_f32_16x16x32_bf16 v[0:3], v[140:143], v[188:191], v[0:3]
	v_mfma_f32_16x16x32_bf16 v[76:79], v[144:147], v[160:163], 0
	v_mfma_f32_16x16x32_bf16 v[72:75], v[152:155], v[160:163], 0
	v_mfma_f32_16x16x32_bf16 v[44:47], v[144:147], v[168:171], 0
	v_mfma_f32_16x16x32_bf16 v[40:43], v[152:155], v[168:171], 0
	v_mfma_f32_16x16x32_bf16 v[28:31], v[144:147], v[176:179], 0
	v_mfma_f32_16x16x32_bf16 v[24:27], v[152:155], v[176:179], 0
	v_mfma_f32_16x16x32_bf16 v[12:15], v[144:147], v[184:187], 0
	v_mfma_f32_16x16x32_bf16 v[8:11], v[152:155], v[184:187], 0
	v_mfma_f32_16x16x32_bf16 v[76:79], v[148:151], v[164:167], v[76:79]
	v_mfma_f32_16x16x32_bf16 v[72:75], v[156:159], v[164:167], v[72:75]
	v_mfma_f32_16x16x32_bf16 v[44:47], v[148:151], v[172:175], v[44:47]
	v_mfma_f32_16x16x32_bf16 v[40:43], v[156:159], v[172:175], v[40:43]
	v_mfma_f32_16x16x32_bf16 v[28:31], v[148:151], v[180:183], v[28:31]
	v_mfma_f32_16x16x32_bf16 v[24:27], v[156:159], v[180:183], v[24:27]
	v_mfma_f32_16x16x32_bf16 v[12:15], v[148:151], v[188:191], v[12:15]
	v_mfma_f32_16x16x32_bf16 v[8:11], v[156:159], v[188:191], v[8:11]
	s_barrier
	s_setprio 0
	s_add_i32 s80, 0, 0x18000
	s_add_i32 s81, 0, 0x1c000
	v_add_u32_e32 v140, s80, v226
	v_add_u32_e32 v156, s81, v226
	ds_read_b128 v[128:131], v140
	ds_read_b128 v[132:135], v140 offset:1024
	ds_read_b128 v[136:139], v140 offset:2048
	ds_read_b128 v[140:143], v140 offset:3072
	ds_read_b128 v[144:147], v156
	ds_read_b128 v[148:151], v156 offset:1024
	ds_read_b128 v[152:155], v156 offset:2048
	ds_read_b128 v[156:159], v156 offset:3072
	s_add_u32 s48, s48, 0x400000
	s_addc_u32 s49, s49, 0
	s_mov_b32 m0, s52
	ds_read_b128 v[160:163], v230 offset:32768
	ds_read_b128 v[164:167], v230 offset:33792
	ds_read_b128 v[168:171], v230 offset:34816
	ds_read_b128 v[172:175], v230 offset:35840
	ds_read_b128 v[176:179], v230 offset:36864
	ds_read_b128 v[180:183], v230 offset:37888
	ds_read_b128 v[184:187], v230 offset:38912
	ds_read_b128 v[188:191], v230 offset:39936
	global_load_lds_dwordx4 v192, s[48:49]
	s_mov_b32 m0, s53
	s_nop 0
	global_load_lds_dwordx4 v196, s[48:49]
	s_waitcnt vmcnt(8)
	s_waitcnt lgkmcnt(0)
	s_setprio 1
	s_barrier
	v_mfma_f32_16x16x32_bf16 v[112:115], v[128:131], v[160:163], v[112:115]
	v_mfma_f32_16x16x32_bf16 v[116:119], v[136:139], v[160:163], v[116:119]
	v_mfma_f32_16x16x32_bf16 v[100:103], v[128:131], v[168:171], v[100:103]
	v_mfma_f32_16x16x32_bf16 v[96:99], v[136:139], v[168:171], v[96:99]
	v_mfma_f32_16x16x32_bf16 v[84:87], v[128:131], v[176:179], v[84:87]
	v_mfma_f32_16x16x32_bf16 v[80:83], v[136:139], v[176:179], v[80:83]
	v_mfma_f32_16x16x32_bf16 v[52:55], v[128:131], v[184:187], v[52:55]
	v_mfma_f32_16x16x32_bf16 v[48:51], v[136:139], v[184:187], v[48:51]
	v_mfma_f32_16x16x32_bf16 v[112:115], v[132:135], v[164:167], v[112:115]
	v_mfma_f32_16x16x32_bf16 v[116:119], v[140:143], v[164:167], v[116:119]
	v_mfma_f32_16x16x32_bf16 v[100:103], v[132:135], v[172:175], v[100:103]
	v_mfma_f32_16x16x32_bf16 v[96:99], v[140:143], v[172:175], v[96:99]
	v_mfma_f32_16x16x32_bf16 v[84:87], v[132:135], v[180:183], v[84:87]
	v_mfma_f32_16x16x32_bf16 v[80:83], v[140:143], v[180:183], v[80:83]
	v_mfma_f32_16x16x32_bf16 v[52:55], v[132:135], v[188:191], v[52:55]
	v_mfma_f32_16x16x32_bf16 v[48:51], v[140:143], v[188:191], v[48:51]
	v_mfma_f32_16x16x32_bf16 v[124:127], v[144:147], v[160:163], v[124:127]
	v_mfma_f32_16x16x32_bf16 v[120:123], v[152:155], v[160:163], v[120:123]
	v_mfma_f32_16x16x32_bf16 v[108:111], v[144:147], v[168:171], v[108:111]
	v_mfma_f32_16x16x32_bf16 v[104:107], v[152:155], v[168:171], v[104:107]
	v_mfma_f32_16x16x32_bf16 v[92:95], v[144:147], v[176:179], v[92:95]
	v_mfma_f32_16x16x32_bf16 v[88:91], v[152:155], v[176:179], v[88:91]
	v_mfma_f32_16x16x32_bf16 v[68:71], v[144:147], v[184:187], v[68:71]
	v_mfma_f32_16x16x32_bf16 v[64:67], v[152:155], v[184:187], v[64:67]
	v_mfma_f32_16x16x32_bf16 v[124:127], v[148:151], v[164:167], v[124:127]
	v_mfma_f32_16x16x32_bf16 v[120:123], v[156:159], v[164:167], v[120:123]
	v_mfma_f32_16x16x32_bf16 v[108:111], v[148:151], v[172:175], v[108:111]
	v_mfma_f32_16x16x32_bf16 v[104:107], v[156:159], v[172:175], v[104:107]
	v_mfma_f32_16x16x32_bf16 v[92:95], v[148:151], v[180:183], v[92:95]
	v_mfma_f32_16x16x32_bf16 v[88:91], v[156:159], v[180:183], v[88:91]
	v_mfma_f32_16x16x32_bf16 v[68:71], v[148:151], v[188:191], v[68:71]
	v_mfma_f32_16x16x32_bf16 v[64:67], v[156:159], v[188:191], v[64:67]
	s_barrier
	s_setprio 0
	s_add_i32 s48, s80, s97
	s_mov_b32 m0, s48
	ds_read_b128 v[160:163], v230 offset:49152
	ds_read_b128 v[164:167], v230 offset:50176
	ds_read_b128 v[168:171], v230 offset:51200
	ds_read_b128 v[172:175], v230 offset:52224
	ds_read_b128 v[176:179], v230 offset:53248
	ds_read_b128 v[180:183], v230 offset:54272
	ds_read_b128 v[184:187], v230 offset:55296
	ds_read_b128 v[188:191], v230 offset:56320
	global_load_lds_dwordx4 v194, s[98:99]
	s_add_i32 m0, s48, 0x2000
	s_add_u32 s46, s46, 0x400080
	s_addc_u32 s47, s47, 0
	s_add_i32 s48, s81, s97
	global_load_lds_dwordx4 v198, s[98:99]
	s_mov_b32 m0, s48
	s_nop 0
	global_load_lds_dwordx4 v194, s[46:47]
	s_add_i32 m0, s48, 0x2000
	s_nop 0
	global_load_lds_dwordx4 v198, s[46:47]
	s_mov_b32 m0, s54
	s_nop 0
	global_load_lds_dwordx4 v192, s[100:101]
	s_mov_b32 m0, s55
	s_nop 0
	global_load_lds_dwordx4 v196, s[100:101]
	s_waitcnt vmcnt(8)
	s_waitcnt lgkmcnt(0)
	s_setprio 1
	s_barrier
	v_mfma_f32_16x16x32_bf16 v[60:63], v[128:131], v[160:163], v[60:63]
	v_mfma_f32_16x16x32_bf16 v[56:59], v[136:139], v[160:163], v[56:59]
	v_mfma_f32_16x16x32_bf16 v[36:39], v[128:131], v[168:171], v[36:39]
	v_mfma_f32_16x16x32_bf16 v[32:35], v[136:139], v[168:171], v[32:35]
	v_mfma_f32_16x16x32_bf16 v[20:23], v[128:131], v[176:179], v[20:23]
	v_mfma_f32_16x16x32_bf16 v[16:19], v[136:139], v[176:179], v[16:19]
	v_mfma_f32_16x16x32_bf16 v[4:7], v[128:131], v[184:187], v[4:7]
	v_mfma_f32_16x16x32_bf16 v[0:3], v[136:139], v[184:187], v[0:3]
	v_mfma_f32_16x16x32_bf16 v[60:63], v[132:135], v[164:167], v[60:63]
	v_mfma_f32_16x16x32_bf16 v[56:59], v[140:143], v[164:167], v[56:59]
	v_mfma_f32_16x16x32_bf16 v[36:39], v[132:135], v[172:175], v[36:39]
	v_mfma_f32_16x16x32_bf16 v[32:35], v[140:143], v[172:175], v[32:35]
	v_mfma_f32_16x16x32_bf16 v[20:23], v[132:135], v[180:183], v[20:23]
	v_mfma_f32_16x16x32_bf16 v[16:19], v[140:143], v[180:183], v[16:19]
	v_mfma_f32_16x16x32_bf16 v[4:7], v[132:135], v[188:191], v[4:7]
	v_mfma_f32_16x16x32_bf16 v[0:3], v[140:143], v[188:191], v[0:3]
	v_mfma_f32_16x16x32_bf16 v[76:79], v[144:147], v[160:163], v[76:79]
	v_mfma_f32_16x16x32_bf16 v[72:75], v[152:155], v[160:163], v[72:75]
	v_mfma_f32_16x16x32_bf16 v[44:47], v[144:147], v[168:171], v[44:47]
	v_mfma_f32_16x16x32_bf16 v[40:43], v[152:155], v[168:171], v[40:43]
	v_mfma_f32_16x16x32_bf16 v[28:31], v[144:147], v[176:179], v[28:31]
	v_mfma_f32_16x16x32_bf16 v[24:27], v[152:155], v[176:179], v[24:27]
	v_mfma_f32_16x16x32_bf16 v[12:15], v[144:147], v[184:187], v[12:15]
	v_mfma_f32_16x16x32_bf16 v[8:11], v[152:155], v[184:187], v[8:11]
	v_mfma_f32_16x16x32_bf16 v[76:79], v[148:151], v[164:167], v[76:79]
	v_mfma_f32_16x16x32_bf16 v[72:75], v[156:159], v[164:167], v[72:75]
	v_mfma_f32_16x16x32_bf16 v[44:47], v[148:151], v[172:175], v[44:47]
	v_mfma_f32_16x16x32_bf16 v[40:43], v[156:159], v[172:175], v[40:43]
	v_mfma_f32_16x16x32_bf16 v[28:31], v[148:151], v[180:183], v[28:31]
	v_mfma_f32_16x16x32_bf16 v[24:27], v[156:159], v[180:183], v[24:27]
	v_mfma_f32_16x16x32_bf16 v[12:15], v[148:151], v[188:191], v[12:15]
	v_mfma_f32_16x16x32_bf16 v[8:11], v[156:159], v[188:191], v[8:11]
	s_barrier
	s_setprio 0
	s_add_u32 s77, s77, 0x100
	s_addc_u32 s78, s78, 0
	s_add_u32 s44, s44, 0x100
	s_addc_u32 s45, s45, 0
	s_cmp_ge_u32 s79, s76
	s_mov_b32 s46, s79
	s_cbranch_scc1 .Lpeel_done_4
.LBB0_2453:
	ds_read_b128 v[128:131], v228
	ds_read_b128 v[132:135], v228 offset:1024
	ds_read_b128 v[136:139], v228 offset:2048
	ds_read_b128 v[140:143], v228 offset:3072
	ds_read_b128 v[144:147], v229
	ds_read_b128 v[148:151], v229 offset:1024
	ds_read_b128 v[152:155], v229 offset:2048
	ds_read_b128 v[156:159], v229 offset:3072
	s_add_i32 s79, s46, 2
	s_add_u32 s47, s44, 0xffc00080
	s_addc_u32 s48, s45, -1
	s_cmp_eq_u32 s75, s46
	s_cselect_b32 s46, s43, s77
	s_cselect_b32 s49, s35, s48
	s_cselect_b32 s48, s41, s47
	s_cselect_b32 s47, s31, s78
	s_add_i32 m0, s94, 0xc000
	ds_read_b128 v[160:163], v230
	ds_read_b128 v[164:167], v230 offset:1024
	ds_read_b128 v[168:171], v230 offset:2048
	ds_read_b128 v[172:175], v230 offset:3072
	ds_read_b128 v[176:179], v230 offset:4096
	ds_read_b128 v[180:183], v230 offset:5120
	ds_read_b128 v[184:187], v230 offset:6144
	ds_read_b128 v[188:191], v230 offset:7168
	global_load_lds_dwordx4 v202, s[44:45]
	s_add_i32 m0, s94, 0xe000
	s_nop 0
	global_load_lds_dwordx4 v204, s[44:45]
	s_waitcnt vmcnt(8)
	s_waitcnt lgkmcnt(0)
	s_setprio 1
	s_barrier
	v_mfma_f32_16x16x32_bf16 v[112:115], v[128:131], v[160:163], v[112:115]
	v_mfma_f32_16x16x32_bf16 v[116:119], v[136:139], v[160:163], v[116:119]
	v_mfma_f32_16x16x32_bf16 v[100:103], v[128:131], v[168:171], v[100:103]
	v_mfma_f32_16x16x32_bf16 v[96:99], v[136:139], v[168:171], v[96:99]
	v_mfma_f32_16x16x32_bf16 v[84:87], v[128:131], v[176:179], v[84:87]
	v_mfma_f32_16x16x32_bf16 v[80:83], v[136:139], v[176:179], v[80:83]
	v_mfma_f32_16x16x32_bf16 v[52:55], v[128:131], v[184:187], v[52:55]
	v_mfma_f32_16x16x32_bf16 v[48:51], v[136:139], v[184:187], v[48:51]
	v_mfma_f32_16x16x32_bf16 v[112:115], v[132:135], v[164:167], v[112:115]
	v_mfma_f32_16x16x32_bf16 v[116:119], v[140:143], v[164:167], v[116:119]
	v_mfma_f32_16x16x32_bf16 v[100:103], v[132:135], v[172:175], v[100:103]
	v_mfma_f32_16x16x32_bf16 v[96:99], v[140:143], v[172:175], v[96:99]
	v_mfma_f32_16x16x32_bf16 v[84:87], v[132:135], v[180:183], v[84:87]
	v_mfma_f32_16x16x32_bf16 v[80:83], v[140:143], v[180:183], v[80:83]
	v_mfma_f32_16x16x32_bf16 v[52:55], v[132:135], v[188:191], v[52:55]
	v_mfma_f32_16x16x32_bf16 v[48:51], v[140:143], v[188:191], v[48:51]
	v_mfma_f32_16x16x32_bf16 v[124:127], v[144:147], v[160:163], v[124:127]
	v_mfma_f32_16x16x32_bf16 v[120:123], v[152:155], v[160:163], v[120:123]
	v_mfma_f32_16x16x32_bf16 v[108:111], v[144:147], v[168:171], v[108:111]
	v_mfma_f32_16x16x32_bf16 v[104:107], v[152:155], v[168:171], v[104:107]
	v_mfma_f32_16x16x32_bf16 v[92:95], v[144:147], v[176:179], v[92:95]
	v_mfma_f32_16x16x32_bf16 v[88:91], v[152:155], v[176:179], v[88:91]
	v_mfma_f32_16x16x32_bf16 v[68:71], v[144:147], v[184:187], v[68:71]
	v_mfma_f32_16x16x32_bf16 v[64:67], v[152:155], v[184:187], v[64:67]
	v_mfma_f32_16x16x32_bf16 v[124:127], v[148:151], v[164:167], v[124:127]
	v_mfma_f32_16x16x32_bf16 v[120:123], v[156:159], v[164:167], v[120:123]
	v_mfma_f32_16x16x32_bf16 v[108:111], v[148:151], v[172:175], v[108:111]
	v_mfma_f32_16x16x32_bf16 v[104:107], v[156:159], v[172:175], v[104:107]
	v_mfma_f32_16x16x32_bf16 v[92:95], v[148:151], v[180:183], v[92:95]
	v_mfma_f32_16x16x32_bf16 v[88:91], v[156:159], v[180:183], v[88:91]
	v_mfma_f32_16x16x32_bf16 v[68:71], v[148:151], v[188:191], v[68:71]
	v_mfma_f32_16x16x32_bf16 v[64:67], v[156:159], v[188:191], v[64:67]
	s_barrier
	s_setprio 0
	s_add_i32 s80, s68, s97
	s_add_u32 s98, s46, 0x80
	s_addc_u32 s99, s47, 0
	s_mov_b32 m0, s80
	ds_read_b128 v[160:163], v230 offset:16384
	ds_read_b128 v[164:167], v230 offset:17408
	ds_read_b128 v[168:171], v230 offset:18432
	ds_read_b128 v[172:175], v230 offset:19456
	ds_read_b128 v[176:179], v230 offset:20480
	ds_read_b128 v[180:183], v230 offset:21504
	ds_read_b128 v[184:187], v230 offset:22528
	ds_read_b128 v[188:191], v230 offset:23552
	global_load_lds_dwordx4 v194, s[46:47]
	s_add_i32 m0, s80, 0x2000
	s_add_u32 s80, s46, 0x400000
	s_addc_u32 s81, s47, 0
	s_add_i32 s84, s69, s97
	global_load_lds_dwordx4 v198, s[46:47]
	s_mov_b32 m0, s84
	s_add_u32 s100, s48, 0x80
	s_addc_u32 s101, s49, 0
	global_load_lds_dwordx4 v194, s[80:81]
	s_add_i32 m0, s84, 0x2000
	s_nop 0
	global_load_lds_dwordx4 v198, s[80:81]
	s_mov_b32 m0, s94
	s_nop 0
	global_load_lds_dwordx4 v192, s[48:49]
	s_mov_b32 m0, s51
	s_nop 0
	global_load_lds_dwordx4 v196, s[48:49]
	s_waitcnt vmcnt(8)
	s_waitcnt lgkmcnt(0)
	s_setprio 1
	s_barrier
	v_mfma_f32_16x16x32_bf16 v[60:63], v[128:131], v[160:163], v[60:63]
	v_mfma_f32_16x16x32_bf16 v[56:59], v[136:139], v[160:163], v[56:59]
	v_mfma_f32_16x16x32_bf16 v[36:39], v[128:131], v[168:171], v[36:39]
	v_mfma_f32_16x16x32_bf16 v[32:35], v[136:139], v[168:171], v[32:35]
	v_mfma_f32_16x16x32_bf16 v[20:23], v[128:131], v[176:179], v[20:23]
	v_mfma_f32_16x16x32_bf16 v[16:19], v[136:139], v[176:179], v[16:19]
	v_mfma_f32_16x16x32_bf16 v[4:7], v[128:131], v[184:187], v[4:7]
	v_mfma_f32_16x16x32_bf16 v[0:3], v[136:139], v[184:187], v[0:3]
	v_mfma_f32_16x16x32_bf16 v[60:63], v[132:135], v[164:167], v[60:63]
	v_mfma_f32_16x16x32_bf16 v[56:59], v[140:143], v[164:167], v[56:59]
	v_mfma_f32_16x16x32_bf16 v[36:39], v[132:135], v[172:175], v[36:39]
	v_mfma_f32_16x16x32_bf16 v[32:35], v[140:143], v[172:175], v[32:35]
	v_mfma_f32_16x16x32_bf16 v[20:23], v[132:135], v[180:183], v[20:23]
	v_mfma_f32_16x16x32_bf16 v[16:19], v[140:143], v[180:183], v[16:19]
	v_mfma_f32_16x16x32_bf16 v[4:7], v[132:135], v[188:191], v[4:7]
	v_mfma_f32_16x16x32_bf16 v[0:3], v[140:143], v[188:191], v[0:3]
	v_mfma_f32_16x16x32_bf16 v[76:79], v[144:147], v[160:163], v[76:79]
	v_mfma_f32_16x16x32_bf16 v[72:75], v[152:155], v[160:163], v[72:75]
	v_mfma_f32_16x16x32_bf16 v[44:47], v[144:147], v[168:171], v[44:47]
	v_mfma_f32_16x16x32_bf16 v[40:43], v[152:155], v[168:171], v[40:43]
	v_mfma_f32_16x16x32_bf16 v[28:31], v[144:147], v[176:179], v[28:31]
	v_mfma_f32_16x16x32_bf16 v[24:27], v[152:155], v[176:179], v[24:27]
	v_mfma_f32_16x16x32_bf16 v[12:15], v[144:147], v[184:187], v[12:15]
	v_mfma_f32_16x16x32_bf16 v[8:11], v[152:155], v[184:187], v[8:11]
	v_mfma_f32_16x16x32_bf16 v[76:79], v[148:151], v[164:167], v[76:79]
	v_mfma_f32_16x16x32_bf16 v[72:75], v[156:159], v[164:167], v[72:75]
	v_mfma_f32_16x16x32_bf16 v[44:47], v[148:151], v[172:175], v[44:47]
	v_mfma_f32_16x16x32_bf16 v[40:43], v[156:159], v[172:175], v[40:43]
	v_mfma_f32_16x16x32_bf16 v[28:31], v[148:151], v[180:183], v[28:31]
	v_mfma_f32_16x16x32_bf16 v[24:27], v[156:159], v[180:183], v[24:27]
	v_mfma_f32_16x16x32_bf16 v[12:15], v[148:151], v[188:191], v[12:15]
	v_mfma_f32_16x16x32_bf16 v[8:11], v[156:159], v[188:191], v[8:11]
	s_barrier
	s_setprio 0
	s_add_i32 s80, 0, 0x18000
	s_add_i32 s81, 0, 0x1c000
	v_add_u32_e32 v140, s80, v226
	v_add_u32_e32 v156, s81, v226
	ds_read_b128 v[128:131], v140
	ds_read_b128 v[132:135], v140 offset:1024
	ds_read_b128 v[136:139], v140 offset:2048
	ds_read_b128 v[140:143], v140 offset:3072
	ds_read_b128 v[144:147], v156
	ds_read_b128 v[148:151], v156 offset:1024
	ds_read_b128 v[152:155], v156 offset:2048
	ds_read_b128 v[156:159], v156 offset:3072
	s_add_u32 s48, s48, 0x400000
	s_addc_u32 s49, s49, 0
	s_mov_b32 m0, s52
	ds_read_b128 v[160:163], v230 offset:32768
	ds_read_b128 v[164:167], v230 offset:33792
	ds_read_b128 v[168:171], v230 offset:34816
	ds_read_b128 v[172:175], v230 offset:35840
	ds_read_b128 v[176:179], v230 offset:36864
	ds_read_b128 v[180:183], v230 offset:37888
	ds_read_b128 v[184:187], v230 offset:38912
	ds_read_b128 v[188:191], v230 offset:39936
	global_load_lds_dwordx4 v192, s[48:49]
	s_mov_b32 m0, s53
	s_nop 0
	global_load_lds_dwordx4 v196, s[48:49]
	s_waitcnt vmcnt(8)
	s_waitcnt lgkmcnt(0)
	s_setprio 1
	s_barrier
	v_mfma_f32_16x16x32_bf16 v[112:115], v[128:131], v[160:163], v[112:115]
	v_mfma_f32_16x16x32_bf16 v[116:119], v[136:139], v[160:163], v[116:119]
	v_mfma_f32_16x16x32_bf16 v[100:103], v[128:131], v[168:171], v[100:103]
	v_mfma_f32_16x16x32_bf16 v[96:99], v[136:139], v[168:171], v[96:99]
	v_mfma_f32_16x16x32_bf16 v[84:87], v[128:131], v[176:179], v[84:87]
	v_mfma_f32_16x16x32_bf16 v[80:83], v[136:139], v[176:179], v[80:83]
	v_mfma_f32_16x16x32_bf16 v[52:55], v[128:131], v[184:187], v[52:55]
	v_mfma_f32_16x16x32_bf16 v[48:51], v[136:139], v[184:187], v[48:51]
	v_mfma_f32_16x16x32_bf16 v[112:115], v[132:135], v[164:167], v[112:115]
	v_mfma_f32_16x16x32_bf16 v[116:119], v[140:143], v[164:167], v[116:119]
	v_mfma_f32_16x16x32_bf16 v[100:103], v[132:135], v[172:175], v[100:103]
	v_mfma_f32_16x16x32_bf16 v[96:99], v[140:143], v[172:175], v[96:99]
	v_mfma_f32_16x16x32_bf16 v[84:87], v[132:135], v[180:183], v[84:87]
	v_mfma_f32_16x16x32_bf16 v[80:83], v[140:143], v[180:183], v[80:83]
	v_mfma_f32_16x16x32_bf16 v[52:55], v[132:135], v[188:191], v[52:55]
	v_mfma_f32_16x16x32_bf16 v[48:51], v[140:143], v[188:191], v[48:51]
	v_mfma_f32_16x16x32_bf16 v[124:127], v[144:147], v[160:163], v[124:127]
	v_mfma_f32_16x16x32_bf16 v[120:123], v[152:155], v[160:163], v[120:123]
	v_mfma_f32_16x16x32_bf16 v[108:111], v[144:147], v[168:171], v[108:111]
	v_mfma_f32_16x16x32_bf16 v[104:107], v[152:155], v[168:171], v[104:107]
	v_mfma_f32_16x16x32_bf16 v[92:95], v[144:147], v[176:179], v[92:95]
	v_mfma_f32_16x16x32_bf16 v[88:91], v[152:155], v[176:179], v[88:91]
	v_mfma_f32_16x16x32_bf16 v[68:71], v[144:147], v[184:187], v[68:71]
	v_mfma_f32_16x16x32_bf16 v[64:67], v[152:155], v[184:187], v[64:67]
	v_mfma_f32_16x16x32_bf16 v[124:127], v[148:151], v[164:167], v[124:127]
	v_mfma_f32_16x16x32_bf16 v[120:123], v[156:159], v[164:167], v[120:123]
	v_mfma_f32_16x16x32_bf16 v[108:111], v[148:151], v[172:175], v[108:111]
	v_mfma_f32_16x16x32_bf16 v[104:107], v[156:159], v[172:175], v[104:107]
	v_mfma_f32_16x16x32_bf16 v[92:95], v[148:151], v[180:183], v[92:95]
	v_mfma_f32_16x16x32_bf16 v[88:91], v[156:159], v[180:183], v[88:91]
	v_mfma_f32_16x16x32_bf16 v[68:71], v[148:151], v[188:191], v[68:71]
	v_mfma_f32_16x16x32_bf16 v[64:67], v[156:159], v[188:191], v[64:67]
	s_barrier
	s_setprio 0
	s_add_i32 s48, s80, s97
	s_mov_b32 m0, s48
	ds_read_b128 v[160:163], v230 offset:49152
	ds_read_b128 v[164:167], v230 offset:50176
	ds_read_b128 v[168:171], v230 offset:51200
	ds_read_b128 v[172:175], v230 offset:52224
	ds_read_b128 v[176:179], v230 offset:53248
	ds_read_b128 v[180:183], v230 offset:54272
	ds_read_b128 v[184:187], v230 offset:55296
	ds_read_b128 v[188:191], v230 offset:56320
	global_load_lds_dwordx4 v194, s[98:99]
	s_add_i32 m0, s48, 0x2000
	s_add_u32 s46, s46, 0x400080
	s_addc_u32 s47, s47, 0
	s_add_i32 s48, s81, s97
	global_load_lds_dwordx4 v198, s[98:99]
	s_mov_b32 m0, s48
	s_nop 0
	global_load_lds_dwordx4 v194, s[46:47]
	s_add_i32 m0, s48, 0x2000
	s_nop 0
	global_load_lds_dwordx4 v198, s[46:47]
	s_mov_b32 m0, s54
	s_nop 0
	global_load_lds_dwordx4 v192, s[100:101]
	s_mov_b32 m0, s55
	s_nop 0
	global_load_lds_dwordx4 v196, s[100:101]
	s_waitcnt vmcnt(8)
	s_waitcnt lgkmcnt(0)
	s_setprio 1
	s_barrier
	v_mfma_f32_16x16x32_bf16 v[60:63], v[128:131], v[160:163], v[60:63]
	v_mfma_f32_16x16x32_bf16 v[56:59], v[136:139], v[160:163], v[56:59]
	v_mfma_f32_16x16x32_bf16 v[36:39], v[128:131], v[168:171], v[36:39]
	v_mfma_f32_16x16x32_bf16 v[32:35], v[136:139], v[168:171], v[32:35]
	v_mfma_f32_16x16x32_bf16 v[20:23], v[128:131], v[176:179], v[20:23]
	v_mfma_f32_16x16x32_bf16 v[16:19], v[136:139], v[176:179], v[16:19]
	v_mfma_f32_16x16x32_bf16 v[4:7], v[128:131], v[184:187], v[4:7]
	v_mfma_f32_16x16x32_bf16 v[0:3], v[136:139], v[184:187], v[0:3]
	v_mfma_f32_16x16x32_bf16 v[60:63], v[132:135], v[164:167], v[60:63]
	v_mfma_f32_16x16x32_bf16 v[56:59], v[140:143], v[164:167], v[56:59]
	v_mfma_f32_16x16x32_bf16 v[36:39], v[132:135], v[172:175], v[36:39]
	v_mfma_f32_16x16x32_bf16 v[32:35], v[140:143], v[172:175], v[32:35]
	v_mfma_f32_16x16x32_bf16 v[20:23], v[132:135], v[180:183], v[20:23]
	v_mfma_f32_16x16x32_bf16 v[16:19], v[140:143], v[180:183], v[16:19]
	v_mfma_f32_16x16x32_bf16 v[4:7], v[132:135], v[188:191], v[4:7]
	v_mfma_f32_16x16x32_bf16 v[0:3], v[140:143], v[188:191], v[0:3]
	v_mfma_f32_16x16x32_bf16 v[76:79], v[144:147], v[160:163], v[76:79]
	v_mfma_f32_16x16x32_bf16 v[72:75], v[152:155], v[160:163], v[72:75]
	v_mfma_f32_16x16x32_bf16 v[44:47], v[144:147], v[168:171], v[44:47]
	v_mfma_f32_16x16x32_bf16 v[40:43], v[152:155], v[168:171], v[40:43]
	v_mfma_f32_16x16x32_bf16 v[28:31], v[144:147], v[176:179], v[28:31]
	v_mfma_f32_16x16x32_bf16 v[24:27], v[152:155], v[176:179], v[24:27]
	v_mfma_f32_16x16x32_bf16 v[12:15], v[144:147], v[184:187], v[12:15]
	v_mfma_f32_16x16x32_bf16 v[8:11], v[152:155], v[184:187], v[8:11]
	v_mfma_f32_16x16x32_bf16 v[76:79], v[148:151], v[164:167], v[76:79]
	v_mfma_f32_16x16x32_bf16 v[72:75], v[156:159], v[164:167], v[72:75]
	v_mfma_f32_16x16x32_bf16 v[44:47], v[148:151], v[172:175], v[44:47]
	v_mfma_f32_16x16x32_bf16 v[40:43], v[156:159], v[172:175], v[40:43]
	v_mfma_f32_16x16x32_bf16 v[28:31], v[148:151], v[180:183], v[28:31]
	v_mfma_f32_16x16x32_bf16 v[24:27], v[156:159], v[180:183], v[24:27]
	v_mfma_f32_16x16x32_bf16 v[12:15], v[148:151], v[188:191], v[12:15]
	v_mfma_f32_16x16x32_bf16 v[8:11], v[156:159], v[188:191], v[8:11]
	s_barrier
	s_setprio 0
	s_add_u32 s77, s77, 0x100
	s_addc_u32 s78, s78, 0
	s_add_u32 s44, s44, 0x100
	s_addc_u32 s45, s45, 0
	s_cmp_ge_u32 s79, s76
	s_mov_b32 s46, s79
	s_cbranch_scc0 .LBB0_2453
